# chain-ordered MFMA pairs + mid-block setprio flip pairs removed in GEMM MMA blocks
# baseline (speedup 1.0000x reference)
.LBB0_254:
	ds_read_b128 v[90:93], v86
	ds_read_b128 v[94:97], v86 offset:1024
	ds_read_b128 v[98:101], v86 offset:2048
	ds_read_b128 v[102:105], v86 offset:3072
	ds_read_b128 v[106:109], v87
	ds_read_b128 v[110:113], v87 offset:1024
	ds_read_b128 v[114:117], v87 offset:2048
	ds_read_b128 v[118:121], v87 offset:3072
	s_add_u32 s38, s36, 0xfff80080
	s_addc_u32 s39, s37, -1
	s_cmp_eq_u32 s59, 28
	s_cselect_b32 s41, s17, s39
	s_cselect_b32 s40, s16, s38
	s_cselect_b32 s39, s2, s58
	s_cselect_b32 s38, s3, s29
	s_mov_b32 m0, s57
	v_lshl_add_u64 v[80:81], s[36:37], 0, v[76:77]
	ds_read_b128 v[122:125], v88
	ds_read_b128 v[126:129], v88 offset:1024
	ds_read_b128 v[130:133], v88 offset:2048
	ds_read_b128 v[134:137], v88 offset:3072
	ds_read_b128 v[138:141], v88 offset:4096
	ds_read_b128 v[142:145], v88 offset:5120
	ds_read_b128 v[146:149], v88 offset:6144
	ds_read_b128 v[150:153], v88 offset:7168
	global_load_lds_dwordx4 v[80:81], off
	v_lshl_add_u64 v[80:81], s[36:37], 0, v[78:79]
	s_add_i32 m0, s19, 0xe000
	s_nop 0
	global_load_lds_dwordx4 v[80:81], off
	s_waitcnt vmcnt(8)
	s_waitcnt lgkmcnt(0)
	s_barrier
	s_setprio 1
	s_waitcnt lgkmcnt(0)
	v_mfma_f32_16x16x32_bf16 v[60:63], v[90:93], v[122:125], v[60:63]
	v_mfma_f32_16x16x32_bf16 v[60:63], v[94:97], v[126:129], v[60:63]
	v_mfma_f32_16x16x32_bf16 v[52:55], v[90:93], v[130:133], v[52:55]
	v_mfma_f32_16x16x32_bf16 v[52:55], v[94:97], v[134:137], v[52:55]
	v_mfma_f32_16x16x32_bf16 v[36:39], v[90:93], v[138:141], v[36:39]
	v_mfma_f32_16x16x32_bf16 v[36:39], v[94:97], v[142:145], v[36:39]
	v_mfma_f32_16x16x32_bf16 v[20:23], v[90:93], v[146:149], v[20:23]
	v_mfma_f32_16x16x32_bf16 v[20:23], v[94:97], v[150:153], v[20:23]
	v_mfma_f32_16x16x32_bf16 v[56:59], v[98:101], v[122:125], v[56:59]
	v_mfma_f32_16x16x32_bf16 v[56:59], v[102:105], v[126:129], v[56:59]
	v_mfma_f32_16x16x32_bf16 v[48:51], v[98:101], v[130:133], v[48:51]
	v_mfma_f32_16x16x32_bf16 v[48:51], v[102:105], v[134:137], v[48:51]
	v_mfma_f32_16x16x32_bf16 v[32:35], v[98:101], v[138:141], v[32:35]
	v_mfma_f32_16x16x32_bf16 v[32:35], v[102:105], v[142:145], v[32:35]
	v_mfma_f32_16x16x32_bf16 v[16:19], v[98:101], v[146:149], v[16:19]
	v_mfma_f32_16x16x32_bf16 v[16:19], v[102:105], v[150:153], v[16:19]
	v_mfma_f32_16x16x32_bf16 v[44:47], v[106:109], v[122:125], v[44:47]
	v_mfma_f32_16x16x32_bf16 v[44:47], v[110:113], v[126:129], v[44:47]
	v_mfma_f32_16x16x32_bf16 v[28:31], v[106:109], v[130:133], v[28:31]
	v_mfma_f32_16x16x32_bf16 v[28:31], v[110:113], v[134:137], v[28:31]
	v_mfma_f32_16x16x32_bf16 v[12:15], v[106:109], v[138:141], v[12:15]
	v_mfma_f32_16x16x32_bf16 v[12:15], v[110:113], v[142:145], v[12:15]
	v_mfma_f32_16x16x32_bf16 v[4:7], v[106:109], v[146:149], v[4:7]
	v_mfma_f32_16x16x32_bf16 v[4:7], v[110:113], v[150:153], v[4:7]
	v_mfma_f32_16x16x32_bf16 v[40:43], v[114:117], v[122:125], v[40:43]
	v_mfma_f32_16x16x32_bf16 v[40:43], v[118:121], v[126:129], v[40:43]
	v_mfma_f32_16x16x32_bf16 v[24:27], v[114:117], v[130:133], v[24:27]
	v_mfma_f32_16x16x32_bf16 v[24:27], v[118:121], v[134:137], v[24:27]
	v_mfma_f32_16x16x32_bf16 v[8:11], v[114:117], v[138:141], v[8:11]
	v_mfma_f32_16x16x32_bf16 v[8:11], v[118:121], v[142:145], v[8:11]
	v_mfma_f32_16x16x32_bf16 v[0:3], v[114:117], v[146:149], v[0:3]
	v_mfma_f32_16x16x32_bf16 v[0:3], v[118:121], v[150:153], v[0:3]
	s_setprio 0
	s_barrier
	s_nop 1
	s_add_i32 s60, s55, s48
	v_lshl_add_u64 v[80:81], s[38:39], 0, v[64:65]
	s_mov_b32 m0, s60
	v_lshl_add_u64 v[154:155], s[38:39], 0, v[66:67]
	global_load_lds_dwordx4 v[80:81], off
	s_add_i32 m0, s60, 0x2000
	s_add_u32 s60, s38, 0x80000
	s_addc_u32 s61, s39, 0
	s_add_i32 s62, s56, s48
	global_load_lds_dwordx4 v[154:155], off
	v_lshl_add_u64 v[90:91], s[60:61], 0, v[64:65]
	s_mov_b32 m0, s62
	v_lshl_add_u64 v[156:157], s[40:41], 0, v[64:65]
	global_load_lds_dwordx4 v[90:91], off
	v_lshl_add_u64 v[90:91], s[60:61], 0, v[66:67]
	s_add_i32 m0, s62, 0x2000
	v_lshl_add_u64 v[158:159], s[40:41], 0, v[66:67]
	global_load_lds_dwordx4 v[90:91], off
	s_mov_b32 m0, s19
	s_nop 0
	global_load_lds_dwordx4 v[156:157], off
	s_mov_b32 m0, s49
	s_nop 0
	global_load_lds_dwordx4 v[158:159], off
	s_waitcnt vmcnt(8)
	s_waitcnt lgkmcnt(0)
	s_barrier
	s_setprio 1
	s_setprio 0
	s_setprio 1
	s_setprio 0
	s_barrier
	s_add_i32 s60, 0, 0x18000
	v_add_u32_e32 v89, s60, v84
	s_add_i32 s61, 0, 0x1c000
	ds_read_b128 v[90:93], v89
	ds_read_b128 v[94:97], v89 offset:1024
	ds_read_b128 v[98:101], v89 offset:2048
	ds_read_b128 v[102:105], v89 offset:3072
	v_add_u32_e32 v89, s61, v84
	ds_read_b128 v[106:109], v89
	ds_read_b128 v[110:113], v89 offset:1024
	ds_read_b128 v[114:117], v89 offset:2048
	ds_read_b128 v[118:121], v89 offset:3072
	s_add_u32 s40, s40, 0x80000
	s_addc_u32 s41, s41, 0
	s_mov_b32 m0, s50
	v_lshl_add_u64 v[160:161], s[40:41], 0, v[64:65]
	ds_read_b128 v[122:125], v88 offset:32768
	ds_read_b128 v[126:129], v88 offset:33792
	ds_read_b128 v[130:133], v88 offset:34816
	ds_read_b128 v[134:137], v88 offset:35840
	ds_read_b128 v[138:141], v88 offset:36864
	ds_read_b128 v[142:145], v88 offset:37888
	ds_read_b128 v[146:149], v88 offset:38912
	ds_read_b128 v[150:153], v88 offset:39936
	global_load_lds_dwordx4 v[160:161], off
	v_lshl_add_u64 v[160:161], s[40:41], 0, v[66:67]
	s_mov_b32 m0, s51
	s_nop 0
	global_load_lds_dwordx4 v[160:161], off
	s_waitcnt vmcnt(8)
	s_waitcnt lgkmcnt(0)
	s_barrier
	s_setprio 1
	s_waitcnt lgkmcnt(0)
	v_mfma_f32_16x16x32_bf16 v[60:63], v[90:93], v[122:125], v[60:63]
	v_mfma_f32_16x16x32_bf16 v[60:63], v[94:97], v[126:129], v[60:63]
	v_mfma_f32_16x16x32_bf16 v[52:55], v[90:93], v[130:133], v[52:55]
	v_mfma_f32_16x16x32_bf16 v[52:55], v[94:97], v[134:137], v[52:55]
	v_mfma_f32_16x16x32_bf16 v[36:39], v[90:93], v[138:141], v[36:39]
	v_mfma_f32_16x16x32_bf16 v[36:39], v[94:97], v[142:145], v[36:39]
	v_mfma_f32_16x16x32_bf16 v[20:23], v[90:93], v[146:149], v[20:23]
	v_mfma_f32_16x16x32_bf16 v[20:23], v[94:97], v[150:153], v[20:23]
	v_mfma_f32_16x16x32_bf16 v[56:59], v[98:101], v[122:125], v[56:59]
	v_mfma_f32_16x16x32_bf16 v[56:59], v[102:105], v[126:129], v[56:59]
	v_mfma_f32_16x16x32_bf16 v[48:51], v[98:101], v[130:133], v[48:51]
	v_mfma_f32_16x16x32_bf16 v[48:51], v[102:105], v[134:137], v[48:51]
	v_mfma_f32_16x16x32_bf16 v[32:35], v[98:101], v[138:141], v[32:35]
	v_mfma_f32_16x16x32_bf16 v[32:35], v[102:105], v[142:145], v[32:35]
	v_mfma_f32_16x16x32_bf16 v[16:19], v[98:101], v[146:149], v[16:19]
	v_mfma_f32_16x16x32_bf16 v[16:19], v[102:105], v[150:153], v[16:19]
	v_mfma_f32_16x16x32_bf16 v[44:47], v[106:109], v[122:125], v[44:47]
	v_mfma_f32_16x16x32_bf16 v[44:47], v[110:113], v[126:129], v[44:47]
	v_mfma_f32_16x16x32_bf16 v[28:31], v[106:109], v[130:133], v[28:31]
	v_mfma_f32_16x16x32_bf16 v[28:31], v[110:113], v[134:137], v[28:31]
	v_mfma_f32_16x16x32_bf16 v[12:15], v[106:109], v[138:141], v[12:15]
	v_mfma_f32_16x16x32_bf16 v[12:15], v[110:113], v[142:145], v[12:15]
	v_mfma_f32_16x16x32_bf16 v[4:7], v[106:109], v[146:149], v[4:7]
	v_mfma_f32_16x16x32_bf16 v[4:7], v[110:113], v[150:153], v[4:7]
	v_mfma_f32_16x16x32_bf16 v[40:43], v[114:117], v[122:125], v[40:43]
	v_mfma_f32_16x16x32_bf16 v[40:43], v[118:121], v[126:129], v[40:43]
	v_mfma_f32_16x16x32_bf16 v[24:27], v[114:117], v[130:133], v[24:27]
	v_mfma_f32_16x16x32_bf16 v[24:27], v[118:121], v[134:137], v[24:27]
	v_mfma_f32_16x16x32_bf16 v[8:11], v[114:117], v[138:141], v[8:11]
	v_mfma_f32_16x16x32_bf16 v[8:11], v[118:121], v[142:145], v[8:11]
	v_mfma_f32_16x16x32_bf16 v[0:3], v[114:117], v[146:149], v[0:3]
	v_mfma_f32_16x16x32_bf16 v[0:3], v[118:121], v[150:153], v[0:3]
	s_setprio 0
	s_barrier
	s_nop 1
	s_add_i32 s40, s60, s48
	v_lshl_add_u64 v[80:81], v[80:81], 0, s[22:23]
	s_mov_b32 m0, s40
	s_nop 0
	global_load_lds_dwordx4 v[80:81], off
	s_add_i32 m0, s40, 0x2000
	s_add_u32 s38, s38, 0x80080
	v_lshl_add_u64 v[80:81], v[154:155], 0, s[22:23]
	s_addc_u32 s39, s39, 0
	s_add_i32 s40, s61, s48
	global_load_lds_dwordx4 v[80:81], off
	v_lshl_add_u64 v[80:81], s[38:39], 0, v[64:65]
	s_mov_b32 m0, s40
	s_nop 0
	global_load_lds_dwordx4 v[80:81], off
	v_lshl_add_u64 v[80:81], s[38:39], 0, v[66:67]
	s_add_i32 m0, s40, 0x2000
	s_nop 0
	global_load_lds_dwordx4 v[80:81], off
	v_lshl_add_u64 v[80:81], v[156:157], 0, s[22:23]
	s_mov_b32 m0, s53
	s_nop 0
	global_load_lds_dwordx4 v[80:81], off
	v_lshl_add_u64 v[80:81], v[158:159], 0, s[22:23]
	s_mov_b32 m0, s54
	s_nop 0
	global_load_lds_dwordx4 v[80:81], off
	s_waitcnt vmcnt(8)
	s_waitcnt lgkmcnt(0)
	s_barrier
	s_setprio 1
	s_setprio 0
	s_setprio 1
	s_setprio 0
	s_barrier
	s_add_i32 s59, s59, 2
	s_add_u32 s36, s36, 0x100
	s_addc_u32 s37, s37, 0
	s_add_u32 s29, s29, 0x100
	s_addc_u32 s58, s58, 0
	s_cmp_gt_u32 s59, 29
	s_cbranch_scc0 .LBB0_254
	s_and_b64 vcc, exec, s[24:25]
	s_cbranch_vccz .LBB0_261
	s_barrier
	v_lshl_or_b32 v80, s18, 8, v85
	v_ashrrev_i32_e32 v81, 31, v80
	s_and_saveexec_b64 s[2:3], s[10:11]
	s_cbranch_execnz .LBB0_262

.LBB0_370:
	s_add_u32 s26, s18, 0x100
	s_addc_u32 s27, s19, 0
	s_cmp_eq_u32 s5, 30
	s_cselect_b32 s31, s40, s27
	s_cselect_b32 s30, s41, s26
	s_cselect_b32 s29, s57, s75
	s_cselect_b32 s28, s4, s15
	s_add_i32 s2, 0, 0x10000
	v_add_u32_e32 v152, s2, v154
	s_add_i32 vcc_lo, 0, 0x14000
	ds_read_b128 v[140:143], v152
	ds_read_b128 v[144:147], v152 offset:1024
	ds_read_b128 v[148:151], v152 offset:2048
	ds_read_b128 v[156:159], v152 offset:3072
	v_add_u32_e32 v152, vcc_lo, v154
	ds_read_b128 v[160:163], v152
	ds_read_b128 v[164:167], v152 offset:1024
	ds_read_b128 v[168:171], v152 offset:2048
	ds_read_b128 v[172:175], v152 offset:3072
	v_lshl_add_u64 v[152:153], s[18:19], 0, v[136:137]
	s_add_i32 m0, s63, 0xc000
	ds_read_b128 v[176:179], v155
	ds_read_b128 v[180:183], v155 offset:1024
	ds_read_b128 v[184:187], v155 offset:2048
	ds_read_b128 v[188:191], v155 offset:3072
	ds_read_b128 v[192:195], v155 offset:4096
	ds_read_b128 v[196:199], v155 offset:5120
	ds_read_b128 v[200:203], v155 offset:6144
	ds_read_b128 v[204:207], v155 offset:7168
	global_load_lds_dwordx4 v[152:153], off
	v_lshl_add_u64 v[152:153], s[18:19], 0, v[138:139]
	s_add_i32 m0, s63, 0xe000
	s_nop 0
	global_load_lds_dwordx4 v[152:153], off
	s_waitcnt vmcnt(8)
	s_waitcnt lgkmcnt(0)
	s_barrier
	s_setprio 1
	s_waitcnt lgkmcnt(0)
	v_mfma_f32_16x16x32_bf16 v[96:99], v[140:143], v[176:179], v[96:99]
	v_mfma_f32_16x16x32_bf16 v[96:99], v[144:147], v[180:183], v[96:99]
	v_mfma_f32_16x16x32_bf16 v[124:127], v[140:143], v[184:187], v[124:127]
	v_mfma_f32_16x16x32_bf16 v[124:127], v[144:147], v[188:191], v[124:127]
	v_mfma_f32_16x16x32_bf16 v[120:123], v[140:143], v[192:195], v[120:123]
	v_mfma_f32_16x16x32_bf16 v[120:123], v[144:147], v[196:199], v[120:123]
	v_mfma_f32_16x16x32_bf16 v[84:87], v[140:143], v[200:203], v[84:87]
	v_mfma_f32_16x16x32_bf16 v[84:87], v[144:147], v[204:207], v[84:87]
	v_mfma_f32_16x16x32_bf16 v[56:59], v[148:151], v[176:179], v[56:59]
	v_mfma_f32_16x16x32_bf16 v[56:59], v[156:159], v[180:183], v[56:59]
	v_mfma_f32_16x16x32_bf16 v[116:119], v[148:151], v[184:187], v[116:119]
	v_mfma_f32_16x16x32_bf16 v[116:119], v[156:159], v[188:191], v[116:119]
	v_mfma_f32_16x16x32_bf16 v[112:115], v[148:151], v[192:195], v[112:115]
	v_mfma_f32_16x16x32_bf16 v[112:115], v[156:159], v[196:199], v[112:115]
	v_mfma_f32_16x16x32_bf16 v[48:51], v[148:151], v[200:203], v[48:51]
	v_mfma_f32_16x16x32_bf16 v[48:51], v[156:159], v[204:207], v[48:51]
	v_mfma_f32_16x16x32_bf16 v[100:103], v[160:163], v[176:179], v[100:103]
	v_mfma_f32_16x16x32_bf16 v[100:103], v[164:167], v[180:183], v[100:103]
	v_mfma_f32_16x16x32_bf16 v[88:91], v[160:163], v[184:187], v[88:91]
	v_mfma_f32_16x16x32_bf16 v[88:91], v[164:167], v[188:191], v[88:91]
	v_mfma_f32_16x16x32_bf16 v[72:75], v[160:163], v[192:195], v[72:75]
	v_mfma_f32_16x16x32_bf16 v[72:75], v[164:167], v[196:199], v[72:75]
	v_mfma_f32_16x16x32_bf16 v[64:67], v[160:163], v[200:203], v[64:67]
	v_mfma_f32_16x16x32_bf16 v[64:67], v[164:167], v[204:207], v[64:67]
	v_mfma_f32_16x16x32_bf16 v[60:63], v[168:171], v[176:179], v[60:63]
	v_mfma_f32_16x16x32_bf16 v[60:63], v[172:175], v[180:183], v[60:63]
	v_mfma_f32_16x16x32_bf16 v[44:47], v[168:171], v[184:187], v[44:47]
	v_mfma_f32_16x16x32_bf16 v[44:47], v[172:175], v[188:191], v[44:47]
	v_mfma_f32_16x16x32_bf16 v[32:35], v[168:171], v[192:195], v[32:35]
	v_mfma_f32_16x16x32_bf16 v[32:35], v[172:175], v[196:199], v[32:35]
	v_mfma_f32_16x16x32_bf16 v[24:27], v[168:171], v[200:203], v[24:27]
	v_mfma_f32_16x16x32_bf16 v[24:27], v[172:175], v[204:207], v[24:27]
	s_setprio 0
	s_barrier
	s_nop 1
	s_add_i32 s2, s2, s69
	v_lshl_add_u64 v[152:153], s[28:29], 0, v[130:131]
	s_mov_b32 m0, s2
	ds_read_b128 v[176:179], v155 offset:16384
	ds_read_b128 v[180:183], v155 offset:17408
	ds_read_b128 v[184:187], v155 offset:18432
	ds_read_b128 v[188:191], v155 offset:19456
	ds_read_b128 v[192:195], v155 offset:20480
	ds_read_b128 v[196:199], v155 offset:21504
	ds_read_b128 v[200:203], v155 offset:22528
	ds_read_b128 v[204:207], v155 offset:23552
	global_load_lds_dwordx4 v[152:153], off
	s_add_i32 m0, s2, 0x2000
	s_add_u32 s2, s28, 0x80000
	v_lshl_add_u64 v[208:209], s[28:29], 0, v[134:135]
	s_addc_u32 s3, s29, 0
	s_add_i32 s18, vcc_lo, s69
	global_load_lds_dwordx4 v[208:209], off
	v_lshl_add_u64 v[210:211], s[2:3], 0, v[130:131]
	s_mov_b32 m0, s18
	v_lshl_add_u64 v[214:215], s[30:31], 0, v[132:133]
	global_load_lds_dwordx4 v[210:211], off
	v_lshl_add_u64 v[210:211], s[2:3], 0, v[134:135]
	s_add_i32 m0, s18, 0x2000
	s_nop 0
	global_load_lds_dwordx4 v[210:211], off
	v_lshl_add_u64 v[210:211], s[30:31], 0, v[128:129]
	s_mov_b32 m0, s63
	s_nop 0
	global_load_lds_dwordx4 v[210:211], off
	s_mov_b32 m0, s70
	s_nop 0
	global_load_lds_dwordx4 v[214:215], off
	s_waitcnt vmcnt(8)
	s_waitcnt lgkmcnt(0)
	s_barrier
	s_setprio 1
	s_waitcnt lgkmcnt(0)
	v_mfma_f32_16x16x32_bf16 v[92:95], v[140:143], v[176:179], v[92:95]
	v_mfma_f32_16x16x32_bf16 v[92:95], v[144:147], v[180:183], v[92:95]
	v_mfma_f32_16x16x32_bf16 v[108:111], v[140:143], v[184:187], v[108:111]
	v_mfma_f32_16x16x32_bf16 v[108:111], v[144:147], v[188:191], v[108:111]
	v_mfma_f32_16x16x32_bf16 v[104:107], v[140:143], v[192:195], v[104:107]
	v_mfma_f32_16x16x32_bf16 v[104:107], v[144:147], v[196:199], v[104:107]
	v_mfma_f32_16x16x32_bf16 v[76:79], v[140:143], v[200:203], v[76:79]
	v_mfma_f32_16x16x32_bf16 v[76:79], v[144:147], v[204:207], v[76:79]
	v_mfma_f32_16x16x32_bf16 v[52:55], v[148:151], v[176:179], v[52:55]
	v_mfma_f32_16x16x32_bf16 v[52:55], v[156:159], v[180:183], v[52:55]
	v_mfma_f32_16x16x32_bf16 v[80:83], v[148:151], v[184:187], v[80:83]
	v_mfma_f32_16x16x32_bf16 v[80:83], v[156:159], v[188:191], v[80:83]
	v_mfma_f32_16x16x32_bf16 v[68:71], v[148:151], v[192:195], v[68:71]
	v_mfma_f32_16x16x32_bf16 v[68:71], v[156:159], v[196:199], v[68:71]
	v_mfma_f32_16x16x32_bf16 v[36:39], v[148:151], v[200:203], v[36:39]
	v_mfma_f32_16x16x32_bf16 v[36:39], v[156:159], v[204:207], v[36:39]
	v_mfma_f32_16x16x32_bf16 v[40:43], v[160:163], v[176:179], v[40:43]
	v_mfma_f32_16x16x32_bf16 v[40:43], v[164:167], v[180:183], v[40:43]
	v_mfma_f32_16x16x32_bf16 v[28:31], v[160:163], v[184:187], v[28:31]
	v_mfma_f32_16x16x32_bf16 v[28:31], v[164:167], v[188:191], v[28:31]
	v_mfma_f32_16x16x32_bf16 v[20:23], v[160:163], v[192:195], v[20:23]
	v_mfma_f32_16x16x32_bf16 v[20:23], v[164:167], v[196:199], v[20:23]
	v_mfma_f32_16x16x32_bf16 v[16:19], v[160:163], v[200:203], v[16:19]
	v_mfma_f32_16x16x32_bf16 v[16:19], v[164:167], v[204:207], v[16:19]
	v_mfma_f32_16x16x32_bf16 v[12:15], v[168:171], v[176:179], v[12:15]
	v_mfma_f32_16x16x32_bf16 v[12:15], v[172:175], v[180:183], v[12:15]
	v_mfma_f32_16x16x32_bf16 v[8:11], v[168:171], v[184:187], v[8:11]
	v_mfma_f32_16x16x32_bf16 v[8:11], v[172:175], v[188:191], v[8:11]
	v_mfma_f32_16x16x32_bf16 v[4:7], v[168:171], v[192:195], v[4:7]
	v_mfma_f32_16x16x32_bf16 v[4:7], v[172:175], v[196:199], v[4:7]
	v_mfma_f32_16x16x32_bf16 v[0:3], v[168:171], v[200:203], v[0:3]
	v_mfma_f32_16x16x32_bf16 v[0:3], v[172:175], v[204:207], v[0:3]
	s_setprio 0
	s_barrier
	s_nop 1
	s_add_i32 s18, 0, 0x18000
	s_add_i32 s19, 0, 0x1c000
	v_add_u32_e32 v156, s18, v154
	v_add_u32_e32 v172, s19, v154
	ds_read_b128 v[140:143], v156
	ds_read_b128 v[144:147], v156 offset:1024
	ds_read_b128 v[148:151], v156 offset:2048
	ds_read_b128 v[156:159], v156 offset:3072
	ds_read_b128 v[160:163], v172
	ds_read_b128 v[164:167], v172 offset:1024
	ds_read_b128 v[168:171], v172 offset:2048
	ds_read_b128 v[172:175], v172 offset:3072
	s_add_u32 s2, s30, 0x80000
	s_addc_u32 s3, s31, 0
	s_mov_b32 m0, s71
	v_lshl_add_u64 v[216:217], s[2:3], 0, v[128:129]
	ds_read_b128 v[176:179], v155 offset:32768
	ds_read_b128 v[180:183], v155 offset:33792
	ds_read_b128 v[184:187], v155 offset:34816
	ds_read_b128 v[188:191], v155 offset:35840
	ds_read_b128 v[192:195], v155 offset:36864
	ds_read_b128 v[196:199], v155 offset:37888
	ds_read_b128 v[200:203], v155 offset:38912
	ds_read_b128 v[204:207], v155 offset:39936
	global_load_lds_dwordx4 v[216:217], off
	v_lshl_add_u64 v[216:217], s[2:3], 0, v[132:133]
	s_mov_b32 m0, s76
	s_nop 0
	global_load_lds_dwordx4 v[216:217], off
	s_waitcnt vmcnt(8)
	s_waitcnt lgkmcnt(0)
	s_barrier
	s_setprio 1
	s_waitcnt lgkmcnt(0)
	v_mfma_f32_16x16x32_bf16 v[96:99], v[140:143], v[176:179], v[96:99]
	v_mfma_f32_16x16x32_bf16 v[96:99], v[144:147], v[180:183], v[96:99]
	v_mfma_f32_16x16x32_bf16 v[124:127], v[140:143], v[184:187], v[124:127]
	v_mfma_f32_16x16x32_bf16 v[124:127], v[144:147], v[188:191], v[124:127]
	v_mfma_f32_16x16x32_bf16 v[120:123], v[140:143], v[192:195], v[120:123]
	v_mfma_f32_16x16x32_bf16 v[120:123], v[144:147], v[196:199], v[120:123]
	v_mfma_f32_16x16x32_bf16 v[84:87], v[140:143], v[200:203], v[84:87]
	v_mfma_f32_16x16x32_bf16 v[84:87], v[144:147], v[204:207], v[84:87]
	v_mfma_f32_16x16x32_bf16 v[56:59], v[148:151], v[176:179], v[56:59]
	v_mfma_f32_16x16x32_bf16 v[56:59], v[156:159], v[180:183], v[56:59]
	v_mfma_f32_16x16x32_bf16 v[116:119], v[148:151], v[184:187], v[116:119]
	v_mfma_f32_16x16x32_bf16 v[116:119], v[156:159], v[188:191], v[116:119]
	v_mfma_f32_16x16x32_bf16 v[112:115], v[148:151], v[192:195], v[112:115]
	v_mfma_f32_16x16x32_bf16 v[112:115], v[156:159], v[196:199], v[112:115]
	v_mfma_f32_16x16x32_bf16 v[48:51], v[148:151], v[200:203], v[48:51]
	v_mfma_f32_16x16x32_bf16 v[48:51], v[156:159], v[204:207], v[48:51]
	v_mfma_f32_16x16x32_bf16 v[100:103], v[160:163], v[176:179], v[100:103]
	v_mfma_f32_16x16x32_bf16 v[100:103], v[164:167], v[180:183], v[100:103]
	v_mfma_f32_16x16x32_bf16 v[88:91], v[160:163], v[184:187], v[88:91]
	v_mfma_f32_16x16x32_bf16 v[88:91], v[164:167], v[188:191], v[88:91]
	v_mfma_f32_16x16x32_bf16 v[72:75], v[160:163], v[192:195], v[72:75]
	v_mfma_f32_16x16x32_bf16 v[72:75], v[164:167], v[196:199], v[72:75]
	v_mfma_f32_16x16x32_bf16 v[64:67], v[160:163], v[200:203], v[64:67]
	v_mfma_f32_16x16x32_bf16 v[64:67], v[164:167], v[204:207], v[64:67]
	v_mfma_f32_16x16x32_bf16 v[60:63], v[168:171], v[176:179], v[60:63]
	v_mfma_f32_16x16x32_bf16 v[60:63], v[172:175], v[180:183], v[60:63]
	v_mfma_f32_16x16x32_bf16 v[44:47], v[168:171], v[184:187], v[44:47]
	v_mfma_f32_16x16x32_bf16 v[44:47], v[172:175], v[188:191], v[44:47]
	v_mfma_f32_16x16x32_bf16 v[32:35], v[168:171], v[192:195], v[32:35]
	v_mfma_f32_16x16x32_bf16 v[32:35], v[172:175], v[196:199], v[32:35]
	v_mfma_f32_16x16x32_bf16 v[24:27], v[168:171], v[200:203], v[24:27]
	v_mfma_f32_16x16x32_bf16 v[24:27], v[172:175], v[204:207], v[24:27]
	s_setprio 0
	s_barrier
	s_nop 1
	s_add_i32 s2, s18, s69
	v_lshl_add_u64 v[152:153], v[152:153], 0, s[72:73]
	s_mov_b32 m0, s2
	ds_read_b128 v[176:179], v155 offset:49152
	ds_read_b128 v[180:183], v155 offset:50176
	ds_read_b128 v[184:187], v155 offset:51200
	ds_read_b128 v[188:191], v155 offset:52224
	ds_read_b128 v[192:195], v155 offset:53248
	ds_read_b128 v[196:199], v155 offset:54272
	ds_read_b128 v[200:203], v155 offset:55296
	ds_read_b128 v[204:207], v155 offset:56320
	global_load_lds_dwordx4 v[152:153], off
	s_add_i32 m0, s2, 0x2000
	s_add_u32 s2, s28, 0x80080
	v_lshl_add_u64 v[152:153], v[208:209], 0, s[72:73]
	s_addc_u32 s3, s29, 0
	s_add_i32 s18, s19, s69
	global_load_lds_dwordx4 v[152:153], off
	v_lshl_add_u64 v[152:153], s[2:3], 0, v[130:131]
	s_mov_b32 m0, s18
	s_nop 0
	global_load_lds_dwordx4 v[152:153], off
	v_lshl_add_u64 v[152:153], s[2:3], 0, v[134:135]
	s_add_i32 m0, s18, 0x2000
	s_nop 0
	global_load_lds_dwordx4 v[152:153], off
	v_lshl_add_u64 v[152:153], v[210:211], 0, s[72:73]
	s_mov_b32 m0, s87
	s_nop 0
	global_load_lds_dwordx4 v[152:153], off
	v_lshl_add_u64 v[152:153], v[214:215], 0, s[72:73]
	s_mov_b32 m0, s88
	s_nop 0
	global_load_lds_dwordx4 v[152:153], off
	s_waitcnt vmcnt(8)
	s_waitcnt lgkmcnt(0)
	s_barrier
	s_setprio 1
	s_waitcnt lgkmcnt(0)
	v_mfma_f32_16x16x32_bf16 v[92:95], v[140:143], v[176:179], v[92:95]
	v_mfma_f32_16x16x32_bf16 v[92:95], v[144:147], v[180:183], v[92:95]
	v_mfma_f32_16x16x32_bf16 v[108:111], v[140:143], v[184:187], v[108:111]
	v_mfma_f32_16x16x32_bf16 v[108:111], v[144:147], v[188:191], v[108:111]
	v_mfma_f32_16x16x32_bf16 v[104:107], v[140:143], v[192:195], v[104:107]
	v_mfma_f32_16x16x32_bf16 v[104:107], v[144:147], v[196:199], v[104:107]
	v_mfma_f32_16x16x32_bf16 v[76:79], v[140:143], v[200:203], v[76:79]
	v_mfma_f32_16x16x32_bf16 v[76:79], v[144:147], v[204:207], v[76:79]
	v_mfma_f32_16x16x32_bf16 v[52:55], v[148:151], v[176:179], v[52:55]
	v_mfma_f32_16x16x32_bf16 v[52:55], v[156:159], v[180:183], v[52:55]
	v_mfma_f32_16x16x32_bf16 v[80:83], v[148:151], v[184:187], v[80:83]
	v_mfma_f32_16x16x32_bf16 v[80:83], v[156:159], v[188:191], v[80:83]
	v_mfma_f32_16x16x32_bf16 v[68:71], v[148:151], v[192:195], v[68:71]
	v_mfma_f32_16x16x32_bf16 v[68:71], v[156:159], v[196:199], v[68:71]
	v_mfma_f32_16x16x32_bf16 v[36:39], v[148:151], v[200:203], v[36:39]
	v_mfma_f32_16x16x32_bf16 v[36:39], v[156:159], v[204:207], v[36:39]
	v_mfma_f32_16x16x32_bf16 v[40:43], v[160:163], v[176:179], v[40:43]
	v_mfma_f32_16x16x32_bf16 v[40:43], v[164:167], v[180:183], v[40:43]
	v_mfma_f32_16x16x32_bf16 v[28:31], v[160:163], v[184:187], v[28:31]
	v_mfma_f32_16x16x32_bf16 v[28:31], v[164:167], v[188:191], v[28:31]
	v_mfma_f32_16x16x32_bf16 v[20:23], v[160:163], v[192:195], v[20:23]
	v_mfma_f32_16x16x32_bf16 v[20:23], v[164:167], v[196:199], v[20:23]
	v_mfma_f32_16x16x32_bf16 v[16:19], v[160:163], v[200:203], v[16:19]
	v_mfma_f32_16x16x32_bf16 v[16:19], v[164:167], v[204:207], v[16:19]
	v_mfma_f32_16x16x32_bf16 v[12:15], v[168:171], v[176:179], v[12:15]
	v_mfma_f32_16x16x32_bf16 v[12:15], v[172:175], v[180:183], v[12:15]
	v_mfma_f32_16x16x32_bf16 v[8:11], v[168:171], v[184:187], v[8:11]
	v_mfma_f32_16x16x32_bf16 v[8:11], v[172:175], v[188:191], v[8:11]
	v_mfma_f32_16x16x32_bf16 v[4:7], v[168:171], v[192:195], v[4:7]
	v_mfma_f32_16x16x32_bf16 v[4:7], v[172:175], v[196:199], v[4:7]
	v_mfma_f32_16x16x32_bf16 v[0:3], v[168:171], v[200:203], v[0:3]
	v_mfma_f32_16x16x32_bf16 v[0:3], v[172:175], v[204:207], v[0:3]
	s_setprio 0
	s_barrier
	s_nop 1
	s_add_i32 s2, s5, 2
	s_add_u32 s15, s15, 0x100
	s_addc_u32 s75, s75, 0
	s_cmp_gt_u32 s5, 29
	s_mov_b64 s[18:19], s[26:27]
	s_mov_b32 s5, s2
	s_cbranch_scc1 .LBB0_384

.LBB0_486:
	s_add_u32 s18, s16, 0xfff80080
	s_addc_u32 s19, s17, -1
	s_add_i32 s46, 0, 0x10000
	s_cmp_eq_u32 s37, 28
	s_cselect_b32 s21, s5, s19
	s_cselect_b32 s20, s4, s18
	v_add_u32_e32 v78, s46, v80
	s_cselect_b32 s19, s3, s36
	s_cselect_b32 s18, s7, s35
	s_add_i32 s49, 0, 0x14000
	ds_read_b128 v[84:87], v78
	ds_read_b128 v[88:91], v78 offset:1024
	ds_read_b128 v[92:95], v78 offset:2048
	ds_read_b128 v[96:99], v78 offset:3072
	v_add_u32_e32 v78, s49, v80
	ds_read_b128 v[100:103], v78
	ds_read_b128 v[104:107], v78 offset:1024
	ds_read_b128 v[108:111], v78 offset:2048
	ds_read_b128 v[112:115], v78 offset:3072
	v_lshl_add_u64 v[78:79], s[16:17], 0, v[74:75]
	s_add_i32 m0, s25, 0xc000
	ds_read_b128 v[116:119], v82
	ds_read_b128 v[120:123], v82 offset:1024
	ds_read_b128 v[124:127], v82 offset:2048
	ds_read_b128 v[128:131], v82 offset:3072
	ds_read_b128 v[132:135], v82 offset:4096
	ds_read_b128 v[136:139], v82 offset:5120
	ds_read_b128 v[140:143], v82 offset:6144
	ds_read_b128 v[144:147], v82 offset:7168
	global_load_lds_dwordx4 v[78:79], off
	v_lshl_add_u64 v[78:79], s[16:17], 0, v[76:77]
	s_add_i32 m0, s25, 0xe000
	s_nop 0
	global_load_lds_dwordx4 v[78:79], off
	s_waitcnt vmcnt(8)
	s_waitcnt lgkmcnt(0)
	s_barrier
	s_setprio 1
	s_waitcnt lgkmcnt(0)
	v_mfma_f32_16x16x32_bf16 v[60:63], v[84:87], v[116:119], v[60:63]
	v_mfma_f32_16x16x32_bf16 v[60:63], v[88:91], v[120:123], v[60:63]
	v_mfma_f32_16x16x32_bf16 v[52:55], v[84:87], v[124:127], v[52:55]
	v_mfma_f32_16x16x32_bf16 v[52:55], v[88:91], v[128:131], v[52:55]
	v_mfma_f32_16x16x32_bf16 v[36:39], v[84:87], v[132:135], v[36:39]
	v_mfma_f32_16x16x32_bf16 v[36:39], v[88:91], v[136:139], v[36:39]
	v_mfma_f32_16x16x32_bf16 v[20:23], v[84:87], v[140:143], v[20:23]
	v_mfma_f32_16x16x32_bf16 v[20:23], v[88:91], v[144:147], v[20:23]
	v_mfma_f32_16x16x32_bf16 v[56:59], v[92:95], v[116:119], v[56:59]
	v_mfma_f32_16x16x32_bf16 v[56:59], v[96:99], v[120:123], v[56:59]
	v_mfma_f32_16x16x32_bf16 v[48:51], v[92:95], v[124:127], v[48:51]
	v_mfma_f32_16x16x32_bf16 v[48:51], v[96:99], v[128:131], v[48:51]
	v_mfma_f32_16x16x32_bf16 v[32:35], v[92:95], v[132:135], v[32:35]
	v_mfma_f32_16x16x32_bf16 v[32:35], v[96:99], v[136:139], v[32:35]
	v_mfma_f32_16x16x32_bf16 v[16:19], v[92:95], v[140:143], v[16:19]
	v_mfma_f32_16x16x32_bf16 v[16:19], v[96:99], v[144:147], v[16:19]
	v_mfma_f32_16x16x32_bf16 v[44:47], v[100:103], v[116:119], v[44:47]
	v_mfma_f32_16x16x32_bf16 v[44:47], v[104:107], v[120:123], v[44:47]
	v_mfma_f32_16x16x32_bf16 v[28:31], v[100:103], v[124:127], v[28:31]
	v_mfma_f32_16x16x32_bf16 v[28:31], v[104:107], v[128:131], v[28:31]
	v_mfma_f32_16x16x32_bf16 v[12:15], v[100:103], v[132:135], v[12:15]
	v_mfma_f32_16x16x32_bf16 v[12:15], v[104:107], v[136:139], v[12:15]
	v_mfma_f32_16x16x32_bf16 v[4:7], v[100:103], v[140:143], v[4:7]
	v_mfma_f32_16x16x32_bf16 v[4:7], v[104:107], v[144:147], v[4:7]
	v_mfma_f32_16x16x32_bf16 v[40:43], v[108:111], v[116:119], v[40:43]
	v_mfma_f32_16x16x32_bf16 v[40:43], v[112:115], v[120:123], v[40:43]
	v_mfma_f32_16x16x32_bf16 v[24:27], v[108:111], v[124:127], v[24:27]
	v_mfma_f32_16x16x32_bf16 v[24:27], v[112:115], v[128:131], v[24:27]
	v_mfma_f32_16x16x32_bf16 v[8:11], v[108:111], v[132:135], v[8:11]
	v_mfma_f32_16x16x32_bf16 v[8:11], v[112:115], v[136:139], v[8:11]
	v_mfma_f32_16x16x32_bf16 v[0:3], v[108:111], v[140:143], v[0:3]
	v_mfma_f32_16x16x32_bf16 v[0:3], v[112:115], v[144:147], v[0:3]
	s_setprio 0
	s_barrier
	s_nop 1
	s_add_i32 s46, s46, s24
	v_lshl_add_u64 v[78:79], s[18:19], 0, v[212:213]
	s_mov_b32 m0, s46
	v_lshl_add_u64 v[148:149], s[18:19], 0, v[64:65]
	global_load_lds_dwordx4 v[78:79], off
	s_add_i32 m0, s46, 0x2000
	s_add_u32 s46, s18, 0x80000
	s_addc_u32 s47, s19, 0
	s_add_i32 s49, s49, s24
	global_load_lds_dwordx4 v[148:149], off
	v_lshl_add_u64 v[84:85], s[46:47], 0, v[212:213]
	s_mov_b32 m0, s49
	v_lshl_add_u64 v[150:151], s[20:21], 0, v[212:213]
	global_load_lds_dwordx4 v[84:85], off
	v_lshl_add_u64 v[84:85], s[46:47], 0, v[64:65]
	s_add_i32 m0, s49, 0x2000
	v_lshl_add_u64 v[152:153], s[20:21], 0, v[64:65]
	global_load_lds_dwordx4 v[84:85], off
	s_mov_b32 m0, s25
	s_nop 0
	global_load_lds_dwordx4 v[150:151], off
	s_mov_b32 m0, s28
	s_nop 0
	global_load_lds_dwordx4 v[152:153], off
	s_waitcnt vmcnt(8)
	s_waitcnt lgkmcnt(0)
	s_barrier
	s_setprio 1
	s_setprio 0
	s_setprio 1
	s_setprio 0
	s_barrier
	s_add_i32 s46, 0, 0x18000
	v_add_u32_e32 v83, s46, v80
	s_add_i32 s47, 0, 0x1c000
	ds_read_b128 v[84:87], v83
	ds_read_b128 v[88:91], v83 offset:1024
	ds_read_b128 v[92:95], v83 offset:2048
	ds_read_b128 v[96:99], v83 offset:3072
	v_add_u32_e32 v83, s47, v80
	ds_read_b128 v[100:103], v83
	ds_read_b128 v[104:107], v83 offset:1024
	ds_read_b128 v[108:111], v83 offset:2048
	ds_read_b128 v[112:115], v83 offset:3072
	s_add_u32 s20, s20, 0x80000
	s_addc_u32 s21, s21, 0
	s_mov_b32 m0, s29
	v_lshl_add_u64 v[154:155], s[20:21], 0, v[212:213]
	ds_read_b128 v[116:119], v82 offset:32768
	ds_read_b128 v[120:123], v82 offset:33792
	ds_read_b128 v[124:127], v82 offset:34816
	ds_read_b128 v[128:131], v82 offset:35840
	ds_read_b128 v[132:135], v82 offset:36864
	ds_read_b128 v[136:139], v82 offset:37888
	ds_read_b128 v[140:143], v82 offset:38912
	ds_read_b128 v[144:147], v82 offset:39936
	global_load_lds_dwordx4 v[154:155], off
	v_lshl_add_u64 v[154:155], s[20:21], 0, v[64:65]
	s_mov_b32 m0, s30
	s_nop 0
	global_load_lds_dwordx4 v[154:155], off
	s_waitcnt vmcnt(8)
	s_waitcnt lgkmcnt(0)
	s_barrier
	s_setprio 1
	s_waitcnt lgkmcnt(0)
	v_mfma_f32_16x16x32_bf16 v[60:63], v[84:87], v[116:119], v[60:63]
	v_mfma_f32_16x16x32_bf16 v[60:63], v[88:91], v[120:123], v[60:63]
	v_mfma_f32_16x16x32_bf16 v[52:55], v[84:87], v[124:127], v[52:55]
	v_mfma_f32_16x16x32_bf16 v[52:55], v[88:91], v[128:131], v[52:55]
	v_mfma_f32_16x16x32_bf16 v[36:39], v[84:87], v[132:135], v[36:39]
	v_mfma_f32_16x16x32_bf16 v[36:39], v[88:91], v[136:139], v[36:39]
	v_mfma_f32_16x16x32_bf16 v[20:23], v[84:87], v[140:143], v[20:23]
	v_mfma_f32_16x16x32_bf16 v[20:23], v[88:91], v[144:147], v[20:23]
	v_mfma_f32_16x16x32_bf16 v[56:59], v[92:95], v[116:119], v[56:59]
	v_mfma_f32_16x16x32_bf16 v[56:59], v[96:99], v[120:123], v[56:59]
	v_mfma_f32_16x16x32_bf16 v[48:51], v[92:95], v[124:127], v[48:51]
	v_mfma_f32_16x16x32_bf16 v[48:51], v[96:99], v[128:131], v[48:51]
	v_mfma_f32_16x16x32_bf16 v[32:35], v[92:95], v[132:135], v[32:35]
	v_mfma_f32_16x16x32_bf16 v[32:35], v[96:99], v[136:139], v[32:35]
	v_mfma_f32_16x16x32_bf16 v[16:19], v[92:95], v[140:143], v[16:19]
	v_mfma_f32_16x16x32_bf16 v[16:19], v[96:99], v[144:147], v[16:19]
	v_mfma_f32_16x16x32_bf16 v[44:47], v[100:103], v[116:119], v[44:47]
	v_mfma_f32_16x16x32_bf16 v[44:47], v[104:107], v[120:123], v[44:47]
	v_mfma_f32_16x16x32_bf16 v[28:31], v[100:103], v[124:127], v[28:31]
	v_mfma_f32_16x16x32_bf16 v[28:31], v[104:107], v[128:131], v[28:31]
	v_mfma_f32_16x16x32_bf16 v[12:15], v[100:103], v[132:135], v[12:15]
	v_mfma_f32_16x16x32_bf16 v[12:15], v[104:107], v[136:139], v[12:15]
	v_mfma_f32_16x16x32_bf16 v[4:7], v[100:103], v[140:143], v[4:7]
	v_mfma_f32_16x16x32_bf16 v[4:7], v[104:107], v[144:147], v[4:7]
	v_mfma_f32_16x16x32_bf16 v[40:43], v[108:111], v[116:119], v[40:43]
	v_mfma_f32_16x16x32_bf16 v[40:43], v[112:115], v[120:123], v[40:43]
	v_mfma_f32_16x16x32_bf16 v[24:27], v[108:111], v[124:127], v[24:27]
	v_mfma_f32_16x16x32_bf16 v[24:27], v[112:115], v[128:131], v[24:27]
	v_mfma_f32_16x16x32_bf16 v[8:11], v[108:111], v[132:135], v[8:11]
	v_mfma_f32_16x16x32_bf16 v[8:11], v[112:115], v[136:139], v[8:11]
	v_mfma_f32_16x16x32_bf16 v[0:3], v[108:111], v[140:143], v[0:3]
	v_mfma_f32_16x16x32_bf16 v[0:3], v[112:115], v[144:147], v[0:3]
	s_setprio 0
	s_barrier
	s_nop 1
	s_add_i32 s20, s46, s24
	v_lshl_add_u64 v[78:79], v[78:79], 0, s[72:73]
	s_mov_b32 m0, s20
	s_nop 0
	global_load_lds_dwordx4 v[78:79], off
	s_add_i32 m0, s20, 0x2000
	s_add_u32 s18, s18, 0x80080
	v_lshl_add_u64 v[78:79], v[148:149], 0, s[72:73]
	s_addc_u32 s19, s19, 0
	s_add_i32 s20, s47, s24
	global_load_lds_dwordx4 v[78:79], off
	v_lshl_add_u64 v[78:79], s[18:19], 0, v[212:213]
	s_mov_b32 m0, s20
	s_nop 0
	global_load_lds_dwordx4 v[78:79], off
	v_lshl_add_u64 v[78:79], s[18:19], 0, v[64:65]
	s_add_i32 m0, s20, 0x2000
	s_nop 0
	global_load_lds_dwordx4 v[78:79], off
	v_lshl_add_u64 v[78:79], v[150:151], 0, s[72:73]
	s_mov_b32 m0, s31
	s_nop 0
	global_load_lds_dwordx4 v[78:79], off
	v_lshl_add_u64 v[78:79], v[152:153], 0, s[72:73]
	s_mov_b32 m0, s33
	s_nop 0
	global_load_lds_dwordx4 v[78:79], off
	s_waitcnt vmcnt(8)
	s_waitcnt lgkmcnt(0)
	s_barrier
	s_setprio 1
	s_setprio 0
	s_setprio 1
	s_setprio 0
	s_barrier
	s_add_i32 s37, s37, 2
	s_add_u32 s16, s16, 0x100
	s_addc_u32 s17, s17, 0
	s_add_u32 s35, s35, 0x100
	s_addc_u32 s36, s36, 0
	s_cmp_gt_u32 s37, 29
	s_cbranch_scc0 .LBB0_486
	s_and_b64 vcc, exec, s[12:13]
	s_cbranch_vccz .LBB0_493
	s_barrier
	v_lshl_or_b32 v78, s2, 8, v81
	v_ashrrev_i32_e32 v79, 31, v78
	s_and_saveexec_b64 s[2:3], s[38:39]
	s_cbranch_execnz .LBB0_494

.LBB0_659:
	s_add_i32 s2, s41, 2
	s_add_u32 s3, s10, s34
	s_addc_u32 s50, s11, s35
	s_add_u32 s3, s3, 0x100
	s_addc_u32 s50, s50, 0
	s_add_u32 s51, s9, s34
	s_addc_u32 s75, s19, s35
	s_cmp_eq_u32 s45, s41
	s_cselect_b32 s89, s17, s50
	s_cselect_b32 s88, s16, s3
	s_cselect_b32 vcc_hi, s13, s75
	s_cselect_b32 vcc_lo, s12, s51
	s_add_i32 s3, 0, 0x10000
	s_add_i32 s41, 0, 0x14000
	v_add_u32_e32 v136, s3, v220
	v_add_u32_e32 v160, s41, v220
	ds_read_b128 v[108:111], v136
	ds_read_b128 v[120:123], v136 offset:1024
	ds_read_b128 v[132:135], v136 offset:2048
	ds_read_b128 v[136:139], v136 offset:3072
	ds_read_b128 v[140:143], v160
	ds_read_b128 v[144:147], v160 offset:1024
	ds_read_b128 v[148:151], v160 offset:2048
	ds_read_b128 v[160:163], v160 offset:3072
	v_lshl_add_u64 v[196:197], v[96:97], 0, s[34:35]
	s_add_i32 m0, s15, 0xc000
	ds_read_b128 v[164:167], v223
	ds_read_b128 v[168:171], v223 offset:1024
	ds_read_b128 v[172:175], v223 offset:2048
	ds_read_b128 v[176:179], v223 offset:3072
	ds_read_b128 v[180:183], v223 offset:4096
	ds_read_b128 v[184:187], v223 offset:5120
	ds_read_b128 v[188:191], v223 offset:6144
	ds_read_b128 v[192:195], v223 offset:7168
	global_load_lds_dwordx4 v[196:197], off
	v_lshl_add_u64 v[196:197], v[98:99], 0, s[34:35]
	s_add_i32 m0, s15, 0xe000
	s_nop 0
	global_load_lds_dwordx4 v[196:197], off
	s_waitcnt vmcnt(8)
	s_waitcnt lgkmcnt(0)
	s_barrier
	s_setprio 1
	s_waitcnt lgkmcnt(0)
	v_mfma_f32_16x16x32_bf16 v[156:159], v[108:111], v[164:167], v[156:159]
	v_mfma_f32_16x16x32_bf16 v[156:159], v[120:123], v[168:171], v[156:159]
	v_mfma_f32_16x16x32_bf16 v[128:131], v[108:111], v[172:175], v[128:131]
	v_mfma_f32_16x16x32_bf16 v[128:131], v[120:123], v[176:179], v[128:131]
	v_mfma_f32_16x16x32_bf16 v[116:119], v[108:111], v[180:183], v[116:119]
	v_mfma_f32_16x16x32_bf16 v[116:119], v[120:123], v[184:187], v[116:119]
	v_mfma_f32_16x16x32_bf16 v[104:107], v[108:111], v[188:191], v[104:107]
	v_mfma_f32_16x16x32_bf16 v[104:107], v[120:123], v[192:195], v[104:107]
	v_mfma_f32_16x16x32_bf16 v[152:155], v[132:135], v[164:167], v[152:155]
	v_mfma_f32_16x16x32_bf16 v[152:155], v[136:139], v[168:171], v[152:155]
	v_mfma_f32_16x16x32_bf16 v[124:127], v[132:135], v[172:175], v[124:127]
	v_mfma_f32_16x16x32_bf16 v[124:127], v[136:139], v[176:179], v[124:127]
	v_mfma_f32_16x16x32_bf16 v[112:115], v[132:135], v[180:183], v[112:115]
	v_mfma_f32_16x16x32_bf16 v[112:115], v[136:139], v[184:187], v[112:115]
	v_mfma_f32_16x16x32_bf16 v[100:103], v[132:135], v[188:191], v[100:103]
	v_mfma_f32_16x16x32_bf16 v[100:103], v[136:139], v[192:195], v[100:103]
	v_mfma_f32_16x16x32_bf16 v[92:95], v[140:143], v[164:167], v[92:95]
	v_mfma_f32_16x16x32_bf16 v[92:95], v[144:147], v[168:171], v[92:95]
	v_mfma_f32_16x16x32_bf16 v[84:87], v[140:143], v[172:175], v[84:87]
	v_mfma_f32_16x16x32_bf16 v[84:87], v[144:147], v[176:179], v[84:87]
	v_mfma_f32_16x16x32_bf16 v[76:79], v[140:143], v[180:183], v[76:79]
	v_mfma_f32_16x16x32_bf16 v[76:79], v[144:147], v[184:187], v[76:79]
	v_mfma_f32_16x16x32_bf16 v[68:71], v[140:143], v[188:191], v[68:71]
	v_mfma_f32_16x16x32_bf16 v[68:71], v[144:147], v[192:195], v[68:71]
	v_mfma_f32_16x16x32_bf16 v[88:91], v[148:151], v[164:167], v[88:91]
	v_mfma_f32_16x16x32_bf16 v[88:91], v[160:163], v[168:171], v[88:91]
	v_mfma_f32_16x16x32_bf16 v[80:83], v[148:151], v[172:175], v[80:83]
	v_mfma_f32_16x16x32_bf16 v[80:83], v[160:163], v[176:179], v[80:83]
	v_mfma_f32_16x16x32_bf16 v[72:75], v[148:151], v[180:183], v[72:75]
	v_mfma_f32_16x16x32_bf16 v[72:75], v[160:163], v[184:187], v[72:75]
	v_mfma_f32_16x16x32_bf16 v[64:67], v[148:151], v[188:191], v[64:67]
	v_mfma_f32_16x16x32_bf16 v[64:67], v[160:163], v[192:195], v[64:67]
	s_setprio 0
	s_barrier
	s_nop 1
	s_add_i32 s3, s3, s64
	v_lshl_add_u64 v[196:197], vcc, 0, v[212:213]
	s_mov_b32 m0, s3
	ds_read_b128 v[164:167], v223 offset:16384
	ds_read_b128 v[168:171], v223 offset:17408
	ds_read_b128 v[172:175], v223 offset:18432
	ds_read_b128 v[176:179], v223 offset:19456
	ds_read_b128 v[180:183], v223 offset:20480
	ds_read_b128 v[184:187], v223 offset:21504
	ds_read_b128 v[188:191], v223 offset:22528
	ds_read_b128 v[192:195], v223 offset:23552
	global_load_lds_dwordx4 v[196:197], off
	s_add_i32 m0, s3, 0x2000
	s_add_u32 s50, vcc_lo, 0x80000
	v_lshl_add_u64 v[198:199], vcc, 0, v[208:209]
	s_addc_u32 s51, vcc_hi, 0
	s_add_i32 s3, s41, s64
	global_load_lds_dwordx4 v[198:199], off
	v_lshl_add_u64 v[200:201], s[50:51], 0, v[212:213]
	s_mov_b32 m0, s3
	v_lshl_add_u64 v[202:203], s[88:89], 0, v[206:207]
	global_load_lds_dwordx4 v[200:201], off
	v_lshl_add_u64 v[200:201], s[50:51], 0, v[208:209]
	s_add_i32 m0, s3, 0x2000
	s_nop 0
	global_load_lds_dwordx4 v[200:201], off
	v_lshl_add_u64 v[200:201], s[88:89], 0, v[204:205]
	s_mov_b32 m0, s15
	s_nop 0
	global_load_lds_dwordx4 v[200:201], off
	s_mov_b32 m0, s43
	s_nop 0
	global_load_lds_dwordx4 v[202:203], off
	s_waitcnt vmcnt(8)
	s_waitcnt lgkmcnt(0)
	s_barrier
	s_setprio 1
	s_waitcnt lgkmcnt(0)
	v_mfma_f32_16x16x32_bf16 v[60:63], v[108:111], v[164:167], v[60:63]
	v_mfma_f32_16x16x32_bf16 v[60:63], v[120:123], v[168:171], v[60:63]
	v_mfma_f32_16x16x32_bf16 v[52:55], v[108:111], v[172:175], v[52:55]
	v_mfma_f32_16x16x32_bf16 v[52:55], v[120:123], v[176:179], v[52:55]
	v_mfma_f32_16x16x32_bf16 v[44:47], v[108:111], v[180:183], v[44:47]
	v_mfma_f32_16x16x32_bf16 v[44:47], v[120:123], v[184:187], v[44:47]
	v_mfma_f32_16x16x32_bf16 v[36:39], v[108:111], v[188:191], v[36:39]
	v_mfma_f32_16x16x32_bf16 v[36:39], v[120:123], v[192:195], v[36:39]
	v_mfma_f32_16x16x32_bf16 v[56:59], v[132:135], v[164:167], v[56:59]
	v_mfma_f32_16x16x32_bf16 v[56:59], v[136:139], v[168:171], v[56:59]
	v_mfma_f32_16x16x32_bf16 v[48:51], v[132:135], v[172:175], v[48:51]
	v_mfma_f32_16x16x32_bf16 v[48:51], v[136:139], v[176:179], v[48:51]
	v_mfma_f32_16x16x32_bf16 v[40:43], v[132:135], v[180:183], v[40:43]
	v_mfma_f32_16x16x32_bf16 v[40:43], v[136:139], v[184:187], v[40:43]
	v_mfma_f32_16x16x32_bf16 v[32:35], v[132:135], v[188:191], v[32:35]
	v_mfma_f32_16x16x32_bf16 v[32:35], v[136:139], v[192:195], v[32:35]
	v_mfma_f32_16x16x32_bf16 v[28:31], v[140:143], v[164:167], v[28:31]
	v_mfma_f32_16x16x32_bf16 v[28:31], v[144:147], v[168:171], v[28:31]
	v_mfma_f32_16x16x32_bf16 v[20:23], v[140:143], v[172:175], v[20:23]
	v_mfma_f32_16x16x32_bf16 v[20:23], v[144:147], v[176:179], v[20:23]
	v_mfma_f32_16x16x32_bf16 v[12:15], v[140:143], v[180:183], v[12:15]
	v_mfma_f32_16x16x32_bf16 v[12:15], v[144:147], v[184:187], v[12:15]
	v_mfma_f32_16x16x32_bf16 v[4:7], v[140:143], v[188:191], v[4:7]
	v_mfma_f32_16x16x32_bf16 v[4:7], v[144:147], v[192:195], v[4:7]
	v_mfma_f32_16x16x32_bf16 v[24:27], v[148:151], v[164:167], v[24:27]
	v_mfma_f32_16x16x32_bf16 v[24:27], v[160:163], v[168:171], v[24:27]
	v_mfma_f32_16x16x32_bf16 v[16:19], v[148:151], v[172:175], v[16:19]
	v_mfma_f32_16x16x32_bf16 v[16:19], v[160:163], v[176:179], v[16:19]
	v_mfma_f32_16x16x32_bf16 v[8:11], v[148:151], v[180:183], v[8:11]
	v_mfma_f32_16x16x32_bf16 v[8:11], v[160:163], v[184:187], v[8:11]
	v_mfma_f32_16x16x32_bf16 v[0:3], v[148:151], v[188:191], v[0:3]
	v_mfma_f32_16x16x32_bf16 v[0:3], v[160:163], v[192:195], v[0:3]
	s_setprio 0
	s_barrier
	s_nop 1
	s_add_i32 s3, 0, 0x18000
	s_add_i32 s41, 0, 0x1c000
	v_add_u32_e32 v136, s3, v220
	v_add_u32_e32 v160, s41, v220
	ds_read_b128 v[108:111], v136
	ds_read_b128 v[120:123], v136 offset:1024
	ds_read_b128 v[132:135], v136 offset:2048
	ds_read_b128 v[136:139], v136 offset:3072
	ds_read_b128 v[140:143], v160
	ds_read_b128 v[144:147], v160 offset:1024
	ds_read_b128 v[148:151], v160 offset:2048
	ds_read_b128 v[160:163], v160 offset:3072
	s_add_u32 s50, s88, 0x80000
	s_addc_u32 s51, s89, 0
	s_mov_b32 m0, s69
	v_lshl_add_u64 v[214:215], s[50:51], 0, v[204:205]
	ds_read_b128 v[164:167], v223 offset:32768
	ds_read_b128 v[168:171], v223 offset:33792
	ds_read_b128 v[172:175], v223 offset:34816
	ds_read_b128 v[176:179], v223 offset:35840
	ds_read_b128 v[180:183], v223 offset:36864
	ds_read_b128 v[184:187], v223 offset:37888
	ds_read_b128 v[188:191], v223 offset:38912
	ds_read_b128 v[192:195], v223 offset:39936
	global_load_lds_dwordx4 v[214:215], off
	v_lshl_add_u64 v[214:215], s[50:51], 0, v[206:207]
	s_mov_b32 m0, s70
	s_nop 0
	global_load_lds_dwordx4 v[214:215], off
	s_waitcnt vmcnt(8)
	s_waitcnt lgkmcnt(0)
	s_barrier
	s_setprio 1
	s_waitcnt lgkmcnt(0)
	v_mfma_f32_16x16x32_bf16 v[156:159], v[108:111], v[164:167], v[156:159]
	v_mfma_f32_16x16x32_bf16 v[156:159], v[120:123], v[168:171], v[156:159]
	v_mfma_f32_16x16x32_bf16 v[128:131], v[108:111], v[172:175], v[128:131]
	v_mfma_f32_16x16x32_bf16 v[128:131], v[120:123], v[176:179], v[128:131]
	v_mfma_f32_16x16x32_bf16 v[116:119], v[108:111], v[180:183], v[116:119]
	v_mfma_f32_16x16x32_bf16 v[116:119], v[120:123], v[184:187], v[116:119]
	v_mfma_f32_16x16x32_bf16 v[104:107], v[108:111], v[188:191], v[104:107]
	v_mfma_f32_16x16x32_bf16 v[104:107], v[120:123], v[192:195], v[104:107]
	v_mfma_f32_16x16x32_bf16 v[152:155], v[132:135], v[164:167], v[152:155]
	v_mfma_f32_16x16x32_bf16 v[152:155], v[136:139], v[168:171], v[152:155]
	v_mfma_f32_16x16x32_bf16 v[124:127], v[132:135], v[172:175], v[124:127]
	v_mfma_f32_16x16x32_bf16 v[124:127], v[136:139], v[176:179], v[124:127]
	v_mfma_f32_16x16x32_bf16 v[112:115], v[132:135], v[180:183], v[112:115]
	v_mfma_f32_16x16x32_bf16 v[112:115], v[136:139], v[184:187], v[112:115]
	v_mfma_f32_16x16x32_bf16 v[100:103], v[132:135], v[188:191], v[100:103]
	v_mfma_f32_16x16x32_bf16 v[100:103], v[136:139], v[192:195], v[100:103]
	v_mfma_f32_16x16x32_bf16 v[92:95], v[140:143], v[164:167], v[92:95]
	v_mfma_f32_16x16x32_bf16 v[92:95], v[144:147], v[168:171], v[92:95]
	v_mfma_f32_16x16x32_bf16 v[84:87], v[140:143], v[172:175], v[84:87]
	v_mfma_f32_16x16x32_bf16 v[84:87], v[144:147], v[176:179], v[84:87]
	v_mfma_f32_16x16x32_bf16 v[76:79], v[140:143], v[180:183], v[76:79]
	v_mfma_f32_16x16x32_bf16 v[76:79], v[144:147], v[184:187], v[76:79]
	v_mfma_f32_16x16x32_bf16 v[68:71], v[140:143], v[188:191], v[68:71]
	v_mfma_f32_16x16x32_bf16 v[68:71], v[144:147], v[192:195], v[68:71]
	v_mfma_f32_16x16x32_bf16 v[88:91], v[148:151], v[164:167], v[88:91]
	v_mfma_f32_16x16x32_bf16 v[88:91], v[160:163], v[168:171], v[88:91]
	v_mfma_f32_16x16x32_bf16 v[80:83], v[148:151], v[172:175], v[80:83]
	v_mfma_f32_16x16x32_bf16 v[80:83], v[160:163], v[176:179], v[80:83]
	v_mfma_f32_16x16x32_bf16 v[72:75], v[148:151], v[180:183], v[72:75]
	v_mfma_f32_16x16x32_bf16 v[72:75], v[160:163], v[184:187], v[72:75]
	v_mfma_f32_16x16x32_bf16 v[64:67], v[148:151], v[188:191], v[64:67]
	v_mfma_f32_16x16x32_bf16 v[64:67], v[160:163], v[192:195], v[64:67]
	s_setprio 0
	s_barrier
	s_nop 1
	s_add_i32 s3, s3, s64
	v_lshl_add_u64 v[196:197], v[196:197], 0, s[72:73]
	s_mov_b32 m0, s3
	ds_read_b128 v[164:167], v223 offset:49152
	ds_read_b128 v[168:171], v223 offset:50176
	ds_read_b128 v[172:175], v223 offset:51200
	ds_read_b128 v[176:179], v223 offset:52224
	ds_read_b128 v[180:183], v223 offset:53248
	ds_read_b128 v[184:187], v223 offset:54272
	ds_read_b128 v[188:191], v223 offset:55296
	ds_read_b128 v[192:195], v223 offset:56320
	global_load_lds_dwordx4 v[196:197], off
	s_add_i32 m0, s3, 0x2000
	s_add_u32 s50, vcc_lo, 0x80080
	v_lshl_add_u64 v[196:197], v[198:199], 0, s[72:73]
	s_addc_u32 s51, vcc_hi, 0
	s_add_i32 s3, s41, s64
	global_load_lds_dwordx4 v[196:197], off
	v_lshl_add_u64 v[196:197], s[50:51], 0, v[212:213]
	s_mov_b32 m0, s3
	s_nop 0
	global_load_lds_dwordx4 v[196:197], off
	v_lshl_add_u64 v[196:197], s[50:51], 0, v[208:209]
	s_add_i32 m0, s3, 0x2000
	s_nop 0
	global_load_lds_dwordx4 v[196:197], off
	v_lshl_add_u64 v[196:197], v[200:201], 0, s[72:73]
	s_mov_b32 m0, s83
	s_nop 0
	global_load_lds_dwordx4 v[196:197], off
	v_lshl_add_u64 v[196:197], v[202:203], 0, s[72:73]
	s_mov_b32 m0, s84
	s_nop 0
	global_load_lds_dwordx4 v[196:197], off
	s_waitcnt vmcnt(8)
	s_waitcnt lgkmcnt(0)
	s_barrier
	s_setprio 1
	s_waitcnt lgkmcnt(0)
	v_mfma_f32_16x16x32_bf16 v[60:63], v[108:111], v[164:167], v[60:63]
	v_mfma_f32_16x16x32_bf16 v[60:63], v[120:123], v[168:171], v[60:63]
	v_mfma_f32_16x16x32_bf16 v[52:55], v[108:111], v[172:175], v[52:55]
	v_mfma_f32_16x16x32_bf16 v[52:55], v[120:123], v[176:179], v[52:55]
	v_mfma_f32_16x16x32_bf16 v[44:47], v[108:111], v[180:183], v[44:47]
	v_mfma_f32_16x16x32_bf16 v[44:47], v[120:123], v[184:187], v[44:47]
	v_mfma_f32_16x16x32_bf16 v[36:39], v[108:111], v[188:191], v[36:39]
	v_mfma_f32_16x16x32_bf16 v[36:39], v[120:123], v[192:195], v[36:39]
	v_mfma_f32_16x16x32_bf16 v[56:59], v[132:135], v[164:167], v[56:59]
	v_mfma_f32_16x16x32_bf16 v[56:59], v[136:139], v[168:171], v[56:59]
	v_mfma_f32_16x16x32_bf16 v[48:51], v[132:135], v[172:175], v[48:51]
	v_mfma_f32_16x16x32_bf16 v[48:51], v[136:139], v[176:179], v[48:51]
	v_mfma_f32_16x16x32_bf16 v[40:43], v[132:135], v[180:183], v[40:43]
	v_mfma_f32_16x16x32_bf16 v[40:43], v[136:139], v[184:187], v[40:43]
	v_mfma_f32_16x16x32_bf16 v[32:35], v[132:135], v[188:191], v[32:35]
	v_mfma_f32_16x16x32_bf16 v[32:35], v[136:139], v[192:195], v[32:35]
	v_mfma_f32_16x16x32_bf16 v[28:31], v[140:143], v[164:167], v[28:31]
	v_mfma_f32_16x16x32_bf16 v[28:31], v[144:147], v[168:171], v[28:31]
	v_mfma_f32_16x16x32_bf16 v[20:23], v[140:143], v[172:175], v[20:23]
	v_mfma_f32_16x16x32_bf16 v[20:23], v[144:147], v[176:179], v[20:23]
	v_mfma_f32_16x16x32_bf16 v[12:15], v[140:143], v[180:183], v[12:15]
	v_mfma_f32_16x16x32_bf16 v[12:15], v[144:147], v[184:187], v[12:15]
	v_mfma_f32_16x16x32_bf16 v[4:7], v[140:143], v[188:191], v[4:7]
	v_mfma_f32_16x16x32_bf16 v[4:7], v[144:147], v[192:195], v[4:7]
	v_mfma_f32_16x16x32_bf16 v[24:27], v[148:151], v[164:167], v[24:27]
	v_mfma_f32_16x16x32_bf16 v[24:27], v[160:163], v[168:171], v[24:27]
	v_mfma_f32_16x16x32_bf16 v[16:19], v[148:151], v[172:175], v[16:19]
	v_mfma_f32_16x16x32_bf16 v[16:19], v[160:163], v[176:179], v[16:19]
	v_mfma_f32_16x16x32_bf16 v[8:11], v[148:151], v[180:183], v[8:11]
	v_mfma_f32_16x16x32_bf16 v[8:11], v[160:163], v[184:187], v[8:11]
	v_mfma_f32_16x16x32_bf16 v[0:3], v[148:151], v[188:191], v[0:3]
	v_mfma_f32_16x16x32_bf16 v[0:3], v[160:163], v[192:195], v[0:3]
	s_setprio 0
	s_barrier
	s_nop 1
	s_add_u32 s34, s34, 0x100
	s_addc_u32 s35, s35, 0
	s_cmp_ge_i32 s2, s21
	s_mov_b32 s41, s2
	s_cbranch_scc1 .LBB0_666

.LBB0_831:
	s_add_u32 s2, s24, 0xfff80080
	s_addc_u32 s3, s25, -1
	s_cmp_eq_u32 s17, 30
	s_cselect_b32 s29, s13, s3
	s_cselect_b32 s28, s63, s2
	s_cselect_b32 s27, s11, s65
	s_cselect_b32 s26, s64, s19
	s_add_i32 s2, 0, 0x10000
	v_add_u32_e32 v138, s2, v140
	s_add_i32 s66, 0, 0x14000
	ds_read_b128 v[142:145], v138
	ds_read_b128 v[146:149], v138 offset:1024
	ds_read_b128 v[150:153], v138 offset:2048
	ds_read_b128 v[154:157], v138 offset:3072
	v_add_u32_e32 v138, s66, v140
	ds_read_b128 v[158:161], v138
	ds_read_b128 v[162:165], v138 offset:1024
	ds_read_b128 v[166:169], v138 offset:2048
	ds_read_b128 v[170:173], v138 offset:3072
	v_lshl_add_u64 v[138:139], s[24:25], 0, v[134:135]
	s_add_i32 m0, s43, 0xc000
	ds_read_b128 v[174:177], v141
	ds_read_b128 v[178:181], v141 offset:1024
	ds_read_b128 v[182:185], v141 offset:2048
	ds_read_b128 v[186:189], v141 offset:3072
	ds_read_b128 v[190:193], v141 offset:4096
	ds_read_b128 v[194:197], v141 offset:5120
	ds_read_b128 v[198:201], v141 offset:6144
	ds_read_b128 v[202:205], v141 offset:7168
	global_load_lds_dwordx4 v[138:139], off
	v_lshl_add_u64 v[138:139], s[24:25], 0, v[136:137]
	s_add_i32 m0, s43, 0xe000
	s_nop 0
	global_load_lds_dwordx4 v[138:139], off
	s_waitcnt vmcnt(8)
	s_waitcnt lgkmcnt(0)
	s_barrier
	s_setprio 1
	s_waitcnt lgkmcnt(0)
	v_mfma_f32_16x16x32_bf16 v[124:127], v[142:145], v[174:177], v[124:127]
	v_mfma_f32_16x16x32_bf16 v[124:127], v[146:149], v[178:181], v[124:127]
	v_mfma_f32_16x16x32_bf16 v[120:123], v[142:145], v[182:185], v[120:123]
	v_mfma_f32_16x16x32_bf16 v[120:123], v[146:149], v[186:189], v[120:123]
	v_mfma_f32_16x16x32_bf16 v[116:119], v[142:145], v[190:193], v[116:119]
	v_mfma_f32_16x16x32_bf16 v[116:119], v[146:149], v[194:197], v[116:119]
	v_mfma_f32_16x16x32_bf16 v[112:115], v[142:145], v[198:201], v[112:115]
	v_mfma_f32_16x16x32_bf16 v[112:115], v[146:149], v[202:205], v[112:115]
	v_mfma_f32_16x16x32_bf16 v[108:111], v[150:153], v[174:177], v[108:111]
	v_mfma_f32_16x16x32_bf16 v[108:111], v[154:157], v[178:181], v[108:111]
	v_mfma_f32_16x16x32_bf16 v[104:107], v[150:153], v[182:185], v[104:107]
	v_mfma_f32_16x16x32_bf16 v[104:107], v[154:157], v[186:189], v[104:107]
	v_mfma_f32_16x16x32_bf16 v[100:103], v[150:153], v[190:193], v[100:103]
	v_mfma_f32_16x16x32_bf16 v[100:103], v[154:157], v[194:197], v[100:103]
	v_mfma_f32_16x16x32_bf16 v[96:99], v[150:153], v[198:201], v[96:99]
	v_mfma_f32_16x16x32_bf16 v[96:99], v[154:157], v[202:205], v[96:99]
	v_mfma_f32_16x16x32_bf16 v[84:87], v[158:161], v[174:177], v[84:87]
	v_mfma_f32_16x16x32_bf16 v[84:87], v[162:165], v[178:181], v[84:87]
	v_mfma_f32_16x16x32_bf16 v[76:79], v[158:161], v[182:185], v[76:79]
	v_mfma_f32_16x16x32_bf16 v[76:79], v[162:165], v[186:189], v[76:79]
	v_mfma_f32_16x16x32_bf16 v[64:67], v[158:161], v[190:193], v[64:67]
	v_mfma_f32_16x16x32_bf16 v[64:67], v[162:165], v[194:197], v[64:67]
	v_mfma_f32_16x16x32_bf16 v[56:59], v[158:161], v[198:201], v[56:59]
	v_mfma_f32_16x16x32_bf16 v[56:59], v[162:165], v[202:205], v[56:59]
	v_mfma_f32_16x16x32_bf16 v[52:55], v[166:169], v[174:177], v[52:55]
	v_mfma_f32_16x16x32_bf16 v[52:55], v[170:173], v[178:181], v[52:55]
	v_mfma_f32_16x16x32_bf16 v[44:47], v[166:169], v[182:185], v[44:47]
	v_mfma_f32_16x16x32_bf16 v[44:47], v[170:173], v[186:189], v[44:47]
	v_mfma_f32_16x16x32_bf16 v[36:39], v[166:169], v[190:193], v[36:39]
	v_mfma_f32_16x16x32_bf16 v[36:39], v[170:173], v[194:197], v[36:39]
	v_mfma_f32_16x16x32_bf16 v[32:35], v[166:169], v[198:201], v[32:35]
	v_mfma_f32_16x16x32_bf16 v[32:35], v[170:173], v[202:205], v[32:35]
	s_setprio 0
	s_barrier
	s_nop 1
	s_add_i32 s2, s2, s41
	v_lshl_add_u64 v[138:139], s[26:27], 0, v[212:213]
	s_mov_b32 m0, s2
	ds_read_b128 v[174:177], v141 offset:16384
	ds_read_b128 v[178:181], v141 offset:17408
	ds_read_b128 v[182:185], v141 offset:18432
	ds_read_b128 v[186:189], v141 offset:19456
	ds_read_b128 v[190:193], v141 offset:20480
	ds_read_b128 v[194:197], v141 offset:21504
	ds_read_b128 v[198:201], v141 offset:22528
	ds_read_b128 v[202:205], v141 offset:23552
	global_load_lds_dwordx4 v[138:139], off
	s_add_i32 m0, s2, 0x2000
	s_add_u32 s2, s26, 0x80000
	v_lshl_add_u64 v[206:207], s[26:27], 0, v[128:129]
	s_addc_u32 s3, s27, 0
	s_add_i32 s66, s66, s41
	global_load_lds_dwordx4 v[206:207], off
	v_lshl_add_u64 v[208:209], s[2:3], 0, v[212:213]
	s_mov_b32 m0, s66
	v_lshl_add_u64 v[210:211], s[28:29], 0, v[130:131]
	global_load_lds_dwordx4 v[208:209], off
	v_lshl_add_u64 v[208:209], s[2:3], 0, v[128:129]
	s_add_i32 m0, s66, 0x2000
	s_nop 0
	global_load_lds_dwordx4 v[208:209], off
	v_lshl_add_u64 v[208:209], s[28:29], 0, v[132:133]
	s_mov_b32 m0, s43
	s_nop 0
	global_load_lds_dwordx4 v[208:209], off
	s_mov_b32 m0, s44
	s_nop 0
	global_load_lds_dwordx4 v[210:211], off
	s_waitcnt vmcnt(8)
	s_waitcnt lgkmcnt(0)
	s_barrier
	s_setprio 1
	s_waitcnt lgkmcnt(0)
	v_mfma_f32_16x16x32_bf16 v[92:95], v[142:145], v[174:177], v[92:95]
	v_mfma_f32_16x16x32_bf16 v[92:95], v[146:149], v[178:181], v[92:95]
	v_mfma_f32_16x16x32_bf16 v[88:91], v[142:145], v[182:185], v[88:91]
	v_mfma_f32_16x16x32_bf16 v[88:91], v[146:149], v[186:189], v[88:91]
	v_mfma_f32_16x16x32_bf16 v[80:83], v[142:145], v[190:193], v[80:83]
	v_mfma_f32_16x16x32_bf16 v[80:83], v[146:149], v[194:197], v[80:83]
	v_mfma_f32_16x16x32_bf16 v[72:75], v[142:145], v[198:201], v[72:75]
	v_mfma_f32_16x16x32_bf16 v[72:75], v[146:149], v[202:205], v[72:75]
	v_mfma_f32_16x16x32_bf16 v[68:71], v[150:153], v[174:177], v[68:71]
	v_mfma_f32_16x16x32_bf16 v[68:71], v[154:157], v[178:181], v[68:71]
	v_mfma_f32_16x16x32_bf16 v[60:63], v[150:153], v[182:185], v[60:63]
	v_mfma_f32_16x16x32_bf16 v[60:63], v[154:157], v[186:189], v[60:63]
	v_mfma_f32_16x16x32_bf16 v[48:51], v[150:153], v[190:193], v[48:51]
	v_mfma_f32_16x16x32_bf16 v[48:51], v[154:157], v[194:197], v[48:51]
	v_mfma_f32_16x16x32_bf16 v[40:43], v[150:153], v[198:201], v[40:43]
	v_mfma_f32_16x16x32_bf16 v[40:43], v[154:157], v[202:205], v[40:43]
	v_mfma_f32_16x16x32_bf16 v[28:31], v[158:161], v[174:177], v[28:31]
	v_mfma_f32_16x16x32_bf16 v[28:31], v[162:165], v[178:181], v[28:31]
	v_mfma_f32_16x16x32_bf16 v[24:27], v[158:161], v[182:185], v[24:27]
	v_mfma_f32_16x16x32_bf16 v[24:27], v[162:165], v[186:189], v[24:27]
	v_mfma_f32_16x16x32_bf16 v[20:23], v[158:161], v[190:193], v[20:23]
	v_mfma_f32_16x16x32_bf16 v[20:23], v[162:165], v[194:197], v[20:23]
	v_mfma_f32_16x16x32_bf16 v[16:19], v[158:161], v[198:201], v[16:19]
	v_mfma_f32_16x16x32_bf16 v[16:19], v[162:165], v[202:205], v[16:19]
	v_mfma_f32_16x16x32_bf16 v[12:15], v[166:169], v[174:177], v[12:15]
	v_mfma_f32_16x16x32_bf16 v[12:15], v[170:173], v[178:181], v[12:15]
	v_mfma_f32_16x16x32_bf16 v[8:11], v[166:169], v[182:185], v[8:11]
	v_mfma_f32_16x16x32_bf16 v[8:11], v[170:173], v[186:189], v[8:11]
	v_mfma_f32_16x16x32_bf16 v[4:7], v[166:169], v[190:193], v[4:7]
	v_mfma_f32_16x16x32_bf16 v[4:7], v[170:173], v[194:197], v[4:7]
	v_mfma_f32_16x16x32_bf16 v[0:3], v[166:169], v[198:201], v[0:3]
	v_mfma_f32_16x16x32_bf16 v[0:3], v[170:173], v[202:205], v[0:3]
	s_setprio 0
	s_barrier
	s_nop 1
	s_add_i32 s66, 0, 0x18000
	s_add_i32 s67, 0, 0x1c000
	v_add_u32_e32 v154, s66, v140
	v_add_u32_e32 v170, s67, v140
	ds_read_b128 v[142:145], v154
	ds_read_b128 v[146:149], v154 offset:1024
	ds_read_b128 v[150:153], v154 offset:2048
	ds_read_b128 v[154:157], v154 offset:3072
	ds_read_b128 v[158:161], v170
	ds_read_b128 v[162:165], v170 offset:1024
	ds_read_b128 v[166:169], v170 offset:2048
	ds_read_b128 v[170:173], v170 offset:3072
	s_add_u32 s2, s28, 0x80000
	s_addc_u32 s3, s29, 0
	s_mov_b32 m0, s45
	v_lshl_add_u64 v[214:215], s[2:3], 0, v[132:133]
	ds_read_b128 v[174:177], v141 offset:32768
	ds_read_b128 v[178:181], v141 offset:33792
	ds_read_b128 v[182:185], v141 offset:34816
	ds_read_b128 v[186:189], v141 offset:35840
	ds_read_b128 v[190:193], v141 offset:36864
	ds_read_b128 v[194:197], v141 offset:37888
	ds_read_b128 v[198:201], v141 offset:38912
	ds_read_b128 v[202:205], v141 offset:39936
	global_load_lds_dwordx4 v[214:215], off
	v_lshl_add_u64 v[214:215], s[2:3], 0, v[130:131]
	s_mov_b32 m0, s46
	s_nop 0
	global_load_lds_dwordx4 v[214:215], off
	s_waitcnt vmcnt(8)
	s_waitcnt lgkmcnt(0)
	s_barrier
	s_setprio 1
	s_waitcnt lgkmcnt(0)
	v_mfma_f32_16x16x32_bf16 v[124:127], v[142:145], v[174:177], v[124:127]
	v_mfma_f32_16x16x32_bf16 v[124:127], v[146:149], v[178:181], v[124:127]
	v_mfma_f32_16x16x32_bf16 v[120:123], v[142:145], v[182:185], v[120:123]
	v_mfma_f32_16x16x32_bf16 v[120:123], v[146:149], v[186:189], v[120:123]
	v_mfma_f32_16x16x32_bf16 v[116:119], v[142:145], v[190:193], v[116:119]
	v_mfma_f32_16x16x32_bf16 v[116:119], v[146:149], v[194:197], v[116:119]
	v_mfma_f32_16x16x32_bf16 v[112:115], v[142:145], v[198:201], v[112:115]
	v_mfma_f32_16x16x32_bf16 v[112:115], v[146:149], v[202:205], v[112:115]
	v_mfma_f32_16x16x32_bf16 v[108:111], v[150:153], v[174:177], v[108:111]
	v_mfma_f32_16x16x32_bf16 v[108:111], v[154:157], v[178:181], v[108:111]
	v_mfma_f32_16x16x32_bf16 v[104:107], v[150:153], v[182:185], v[104:107]
	v_mfma_f32_16x16x32_bf16 v[104:107], v[154:157], v[186:189], v[104:107]
	v_mfma_f32_16x16x32_bf16 v[100:103], v[150:153], v[190:193], v[100:103]
	v_mfma_f32_16x16x32_bf16 v[100:103], v[154:157], v[194:197], v[100:103]
	v_mfma_f32_16x16x32_bf16 v[96:99], v[150:153], v[198:201], v[96:99]
	v_mfma_f32_16x16x32_bf16 v[96:99], v[154:157], v[202:205], v[96:99]
	v_mfma_f32_16x16x32_bf16 v[84:87], v[158:161], v[174:177], v[84:87]
	v_mfma_f32_16x16x32_bf16 v[84:87], v[162:165], v[178:181], v[84:87]
	v_mfma_f32_16x16x32_bf16 v[76:79], v[158:161], v[182:185], v[76:79]
	v_mfma_f32_16x16x32_bf16 v[76:79], v[162:165], v[186:189], v[76:79]
	v_mfma_f32_16x16x32_bf16 v[64:67], v[158:161], v[190:193], v[64:67]
	v_mfma_f32_16x16x32_bf16 v[64:67], v[162:165], v[194:197], v[64:67]
	v_mfma_f32_16x16x32_bf16 v[56:59], v[158:161], v[198:201], v[56:59]
	v_mfma_f32_16x16x32_bf16 v[56:59], v[162:165], v[202:205], v[56:59]
	v_mfma_f32_16x16x32_bf16 v[52:55], v[166:169], v[174:177], v[52:55]
	v_mfma_f32_16x16x32_bf16 v[52:55], v[170:173], v[178:181], v[52:55]
	v_mfma_f32_16x16x32_bf16 v[44:47], v[166:169], v[182:185], v[44:47]
	v_mfma_f32_16x16x32_bf16 v[44:47], v[170:173], v[186:189], v[44:47]
	v_mfma_f32_16x16x32_bf16 v[36:39], v[166:169], v[190:193], v[36:39]
	v_mfma_f32_16x16x32_bf16 v[36:39], v[170:173], v[194:197], v[36:39]
	v_mfma_f32_16x16x32_bf16 v[32:35], v[166:169], v[198:201], v[32:35]
	v_mfma_f32_16x16x32_bf16 v[32:35], v[170:173], v[202:205], v[32:35]
	s_setprio 0
	s_barrier
	s_nop 1
	s_add_i32 s2, s66, s41
	v_lshl_add_u64 v[138:139], v[138:139], 0, s[72:73]
	s_mov_b32 m0, s2
	ds_read_b128 v[174:177], v141 offset:49152
	ds_read_b128 v[178:181], v141 offset:50176
	ds_read_b128 v[182:185], v141 offset:51200
	ds_read_b128 v[186:189], v141 offset:52224
	ds_read_b128 v[190:193], v141 offset:53248
	ds_read_b128 v[194:197], v141 offset:54272
	ds_read_b128 v[198:201], v141 offset:55296
	ds_read_b128 v[202:205], v141 offset:56320
	global_load_lds_dwordx4 v[138:139], off
	s_add_i32 m0, s2, 0x2000
	s_add_u32 s2, s26, 0x80080
	v_lshl_add_u64 v[138:139], v[206:207], 0, s[72:73]
	s_addc_u32 s3, s27, 0
	s_add_i32 s26, s67, s41
	global_load_lds_dwordx4 v[138:139], off
	v_lshl_add_u64 v[138:139], s[2:3], 0, v[212:213]
	s_mov_b32 m0, s26
	s_nop 0
	global_load_lds_dwordx4 v[138:139], off
	v_lshl_add_u64 v[138:139], s[2:3], 0, v[128:129]
	s_add_i32 m0, s26, 0x2000
	s_nop 0
	global_load_lds_dwordx4 v[138:139], off
	v_lshl_add_u64 v[138:139], v[208:209], 0, s[72:73]
	s_mov_b32 m0, s54
	s_nop 0
	global_load_lds_dwordx4 v[138:139], off
	v_lshl_add_u64 v[138:139], v[210:211], 0, s[72:73]
	s_mov_b32 m0, s55
	s_nop 0
	global_load_lds_dwordx4 v[138:139], off
	s_waitcnt vmcnt(8)
	s_waitcnt lgkmcnt(0)
	s_barrier
	s_setprio 1
	s_waitcnt lgkmcnt(0)
	v_mfma_f32_16x16x32_bf16 v[92:95], v[142:145], v[174:177], v[92:95]
	v_mfma_f32_16x16x32_bf16 v[92:95], v[146:149], v[178:181], v[92:95]
	v_mfma_f32_16x16x32_bf16 v[88:91], v[142:145], v[182:185], v[88:91]
	v_mfma_f32_16x16x32_bf16 v[88:91], v[146:149], v[186:189], v[88:91]
	v_mfma_f32_16x16x32_bf16 v[80:83], v[142:145], v[190:193], v[80:83]
	v_mfma_f32_16x16x32_bf16 v[80:83], v[146:149], v[194:197], v[80:83]
	v_mfma_f32_16x16x32_bf16 v[72:75], v[142:145], v[198:201], v[72:75]
	v_mfma_f32_16x16x32_bf16 v[72:75], v[146:149], v[202:205], v[72:75]
	v_mfma_f32_16x16x32_bf16 v[68:71], v[150:153], v[174:177], v[68:71]
	v_mfma_f32_16x16x32_bf16 v[68:71], v[154:157], v[178:181], v[68:71]
	v_mfma_f32_16x16x32_bf16 v[60:63], v[150:153], v[182:185], v[60:63]
	v_mfma_f32_16x16x32_bf16 v[60:63], v[154:157], v[186:189], v[60:63]
	v_mfma_f32_16x16x32_bf16 v[48:51], v[150:153], v[190:193], v[48:51]
	v_mfma_f32_16x16x32_bf16 v[48:51], v[154:157], v[194:197], v[48:51]
	v_mfma_f32_16x16x32_bf16 v[40:43], v[150:153], v[198:201], v[40:43]
	v_mfma_f32_16x16x32_bf16 v[40:43], v[154:157], v[202:205], v[40:43]
	v_mfma_f32_16x16x32_bf16 v[28:31], v[158:161], v[174:177], v[28:31]
	v_mfma_f32_16x16x32_bf16 v[28:31], v[162:165], v[178:181], v[28:31]
	v_mfma_f32_16x16x32_bf16 v[24:27], v[158:161], v[182:185], v[24:27]
	v_mfma_f32_16x16x32_bf16 v[24:27], v[162:165], v[186:189], v[24:27]
	v_mfma_f32_16x16x32_bf16 v[20:23], v[158:161], v[190:193], v[20:23]
	v_mfma_f32_16x16x32_bf16 v[20:23], v[162:165], v[194:197], v[20:23]
	v_mfma_f32_16x16x32_bf16 v[16:19], v[158:161], v[198:201], v[16:19]
	v_mfma_f32_16x16x32_bf16 v[16:19], v[162:165], v[202:205], v[16:19]
	v_mfma_f32_16x16x32_bf16 v[12:15], v[166:169], v[174:177], v[12:15]
	v_mfma_f32_16x16x32_bf16 v[12:15], v[170:173], v[178:181], v[12:15]
	v_mfma_f32_16x16x32_bf16 v[8:11], v[166:169], v[182:185], v[8:11]
	v_mfma_f32_16x16x32_bf16 v[8:11], v[170:173], v[186:189], v[8:11]
	v_mfma_f32_16x16x32_bf16 v[4:7], v[166:169], v[190:193], v[4:7]
	v_mfma_f32_16x16x32_bf16 v[4:7], v[170:173], v[194:197], v[4:7]
	v_mfma_f32_16x16x32_bf16 v[0:3], v[166:169], v[198:201], v[0:3]
	v_mfma_f32_16x16x32_bf16 v[0:3], v[170:173], v[202:205], v[0:3]
	s_setprio 0
	s_barrier
	s_nop 1
	s_add_i32 s2, s17, 2
	s_add_u32 s24, s24, 0x100
	s_addc_u32 s25, s25, 0
	s_add_u32 s19, s19, 0x100
	s_addc_u32 s65, s65, 0
	s_cmp_gt_u32 s17, 29
	s_mov_b32 s17, s2
	s_cbranch_scc1 .LBB0_842

.LBB0_997:
	s_add_u32 s20, s18, 0xfffe0080
	s_addc_u32 s21, s19, -1
	s_add_i32 s63, 0, 0x10000
	s_cmp_eq_u32 s62, 4
	s_cselect_b32 s23, s2, s21
	s_cselect_b32 s22, s3, s20
	s_cselect_b32 s21, s39, s61
	s_cselect_b32 s20, s43, s60
	s_add_i32 s66, 0, 0x14000
	v_add_u32_e32 v152, s63, v142
	v_add_u32_e32 v168, s66, v142
	ds_read_b128 v[138:141], v152
	ds_read_b128 v[144:147], v152 offset:1024
	ds_read_b128 v[148:151], v152 offset:2048
	ds_read_b128 v[152:155], v152 offset:3072
	ds_read_b128 v[156:159], v168
	ds_read_b128 v[160:163], v168 offset:1024
	ds_read_b128 v[164:167], v168 offset:2048
	ds_read_b128 v[168:171], v168 offset:3072
	v_lshl_add_u64 v[204:205], s[18:19], 0, v[134:135]
	s_add_i32 m0, s41, 0xc000
	ds_read_b128 v[172:175], v143
	ds_read_b128 v[176:179], v143 offset:1024
	ds_read_b128 v[180:183], v143 offset:2048
	ds_read_b128 v[184:187], v143 offset:3072
	ds_read_b128 v[188:191], v143 offset:4096
	ds_read_b128 v[192:195], v143 offset:5120
	ds_read_b128 v[196:199], v143 offset:6144
	ds_read_b128 v[200:203], v143 offset:7168
	global_load_lds_dwordx4 v[204:205], off
	v_lshl_add_u64 v[204:205], s[18:19], 0, v[136:137]
	s_add_i32 m0, s41, 0xe000
	s_nop 0
	global_load_lds_dwordx4 v[204:205], off
	s_waitcnt vmcnt(8)
	s_waitcnt lgkmcnt(0)
	s_barrier
	s_setprio 1
	s_waitcnt lgkmcnt(0)
	v_mfma_f32_16x16x32_bf16 v[124:127], v[138:141], v[172:175], v[124:127]
	v_mfma_f32_16x16x32_bf16 v[124:127], v[144:147], v[176:179], v[124:127]
	v_mfma_f32_16x16x32_bf16 v[116:119], v[138:141], v[180:183], v[116:119]
	v_mfma_f32_16x16x32_bf16 v[116:119], v[144:147], v[184:187], v[116:119]
	v_mfma_f32_16x16x32_bf16 v[100:103], v[138:141], v[188:191], v[100:103]
	v_mfma_f32_16x16x32_bf16 v[100:103], v[144:147], v[192:195], v[100:103]
	v_mfma_f32_16x16x32_bf16 v[84:87], v[138:141], v[196:199], v[84:87]
	v_mfma_f32_16x16x32_bf16 v[84:87], v[144:147], v[200:203], v[84:87]
	v_mfma_f32_16x16x32_bf16 v[120:123], v[148:151], v[172:175], v[120:123]
	v_mfma_f32_16x16x32_bf16 v[120:123], v[152:155], v[176:179], v[120:123]
	v_mfma_f32_16x16x32_bf16 v[108:111], v[148:151], v[180:183], v[108:111]
	v_mfma_f32_16x16x32_bf16 v[108:111], v[152:155], v[184:187], v[108:111]
	v_mfma_f32_16x16x32_bf16 v[92:95], v[148:151], v[188:191], v[92:95]
	v_mfma_f32_16x16x32_bf16 v[92:95], v[152:155], v[192:195], v[92:95]
	v_mfma_f32_16x16x32_bf16 v[76:79], v[148:151], v[196:199], v[76:79]
	v_mfma_f32_16x16x32_bf16 v[76:79], v[152:155], v[200:203], v[76:79]
	v_mfma_f32_16x16x32_bf16 v[112:115], v[156:159], v[172:175], v[112:115]
	v_mfma_f32_16x16x32_bf16 v[112:115], v[160:163], v[176:179], v[112:115]
	v_mfma_f32_16x16x32_bf16 v[96:99], v[156:159], v[180:183], v[96:99]
	v_mfma_f32_16x16x32_bf16 v[96:99], v[160:163], v[184:187], v[96:99]
	v_mfma_f32_16x16x32_bf16 v[80:83], v[156:159], v[188:191], v[80:83]
	v_mfma_f32_16x16x32_bf16 v[80:83], v[160:163], v[192:195], v[80:83]
	v_mfma_f32_16x16x32_bf16 v[68:71], v[156:159], v[196:199], v[68:71]
	v_mfma_f32_16x16x32_bf16 v[68:71], v[160:163], v[200:203], v[68:71]
	v_mfma_f32_16x16x32_bf16 v[104:107], v[164:167], v[172:175], v[104:107]
	v_mfma_f32_16x16x32_bf16 v[104:107], v[168:171], v[176:179], v[104:107]
	v_mfma_f32_16x16x32_bf16 v[88:91], v[164:167], v[180:183], v[88:91]
	v_mfma_f32_16x16x32_bf16 v[88:91], v[168:171], v[184:187], v[88:91]
	v_mfma_f32_16x16x32_bf16 v[72:75], v[164:167], v[188:191], v[72:75]
	v_mfma_f32_16x16x32_bf16 v[72:75], v[168:171], v[192:195], v[72:75]
	v_mfma_f32_16x16x32_bf16 v[64:67], v[164:167], v[196:199], v[64:67]
	v_mfma_f32_16x16x32_bf16 v[64:67], v[168:171], v[200:203], v[64:67]
	s_setprio 0
	s_barrier
	s_nop 1
	s_add_i32 s63, s63, s33
	v_lshl_add_u64 v[204:205], s[20:21], 0, v[212:213]
	s_mov_b32 m0, s63
	ds_read_b128 v[172:175], v143 offset:16384
	ds_read_b128 v[176:179], v143 offset:17408
	ds_read_b128 v[180:183], v143 offset:18432
	ds_read_b128 v[184:187], v143 offset:19456
	ds_read_b128 v[188:191], v143 offset:20480
	ds_read_b128 v[192:195], v143 offset:21504
	ds_read_b128 v[196:199], v143 offset:22528
	ds_read_b128 v[200:203], v143 offset:23552
	global_load_lds_dwordx4 v[204:205], off
	s_add_i32 m0, s63, 0x2000
	s_add_u32 s64, s20, 0x20000
	v_lshl_add_u64 v[206:207], s[20:21], 0, v[128:129]
	s_addc_u32 s65, s21, 0
	s_add_i32 s63, s66, s33
	global_load_lds_dwordx4 v[206:207], off
	v_lshl_add_u64 v[208:209], s[64:65], 0, v[212:213]
	s_mov_b32 m0, s63
	v_lshl_add_u64 v[210:211], s[22:23], 0, v[130:131]
	global_load_lds_dwordx4 v[208:209], off
	v_lshl_add_u64 v[208:209], s[64:65], 0, v[128:129]
	s_add_i32 m0, s63, 0x2000
	s_nop 0
	global_load_lds_dwordx4 v[208:209], off
	v_lshl_add_u64 v[208:209], s[22:23], 0, v[132:133]
	s_mov_b32 m0, s41
	s_nop 0
	global_load_lds_dwordx4 v[208:209], off
	s_mov_b32 m0, s47
	s_nop 0
	global_load_lds_dwordx4 v[210:211], off
	s_waitcnt vmcnt(8)
	s_waitcnt lgkmcnt(0)
	s_barrier
	s_setprio 1
	s_waitcnt lgkmcnt(0)
	v_mfma_f32_16x16x32_bf16 v[60:63], v[138:141], v[172:175], v[60:63]
	v_mfma_f32_16x16x32_bf16 v[60:63], v[144:147], v[176:179], v[60:63]
	v_mfma_f32_16x16x32_bf16 v[52:55], v[138:141], v[180:183], v[52:55]
	v_mfma_f32_16x16x32_bf16 v[52:55], v[144:147], v[184:187], v[52:55]
	v_mfma_f32_16x16x32_bf16 v[36:39], v[138:141], v[188:191], v[36:39]
	v_mfma_f32_16x16x32_bf16 v[36:39], v[144:147], v[192:195], v[36:39]
	v_mfma_f32_16x16x32_bf16 v[20:23], v[138:141], v[196:199], v[20:23]
	v_mfma_f32_16x16x32_bf16 v[20:23], v[144:147], v[200:203], v[20:23]
	v_mfma_f32_16x16x32_bf16 v[56:59], v[148:151], v[172:175], v[56:59]
	v_mfma_f32_16x16x32_bf16 v[56:59], v[152:155], v[176:179], v[56:59]
	v_mfma_f32_16x16x32_bf16 v[44:47], v[148:151], v[180:183], v[44:47]
	v_mfma_f32_16x16x32_bf16 v[44:47], v[152:155], v[184:187], v[44:47]
	v_mfma_f32_16x16x32_bf16 v[28:31], v[148:151], v[188:191], v[28:31]
	v_mfma_f32_16x16x32_bf16 v[28:31], v[152:155], v[192:195], v[28:31]
	v_mfma_f32_16x16x32_bf16 v[12:15], v[148:151], v[196:199], v[12:15]
	v_mfma_f32_16x16x32_bf16 v[12:15], v[152:155], v[200:203], v[12:15]
	v_mfma_f32_16x16x32_bf16 v[48:51], v[156:159], v[172:175], v[48:51]
	v_mfma_f32_16x16x32_bf16 v[48:51], v[160:163], v[176:179], v[48:51]
	v_mfma_f32_16x16x32_bf16 v[32:35], v[156:159], v[180:183], v[32:35]
	v_mfma_f32_16x16x32_bf16 v[32:35], v[160:163], v[184:187], v[32:35]
	v_mfma_f32_16x16x32_bf16 v[16:19], v[156:159], v[188:191], v[16:19]
	v_mfma_f32_16x16x32_bf16 v[16:19], v[160:163], v[192:195], v[16:19]
	v_mfma_f32_16x16x32_bf16 v[4:7], v[156:159], v[196:199], v[4:7]
	v_mfma_f32_16x16x32_bf16 v[4:7], v[160:163], v[200:203], v[4:7]
	v_mfma_f32_16x16x32_bf16 v[40:43], v[164:167], v[172:175], v[40:43]
	v_mfma_f32_16x16x32_bf16 v[40:43], v[168:171], v[176:179], v[40:43]
	v_mfma_f32_16x16x32_bf16 v[24:27], v[164:167], v[180:183], v[24:27]
	v_mfma_f32_16x16x32_bf16 v[24:27], v[168:171], v[184:187], v[24:27]
	v_mfma_f32_16x16x32_bf16 v[8:11], v[164:167], v[188:191], v[8:11]
	v_mfma_f32_16x16x32_bf16 v[8:11], v[168:171], v[192:195], v[8:11]
	v_mfma_f32_16x16x32_bf16 v[0:3], v[164:167], v[196:199], v[0:3]
	v_mfma_f32_16x16x32_bf16 v[0:3], v[168:171], v[200:203], v[0:3]
	s_setprio 0
	s_barrier
	s_nop 1
	s_add_i32 s63, 0, 0x18000
	s_add_i32 s64, 0, 0x1c000
	v_add_u32_e32 v152, s63, v142
	v_add_u32_e32 v168, s64, v142
	ds_read_b128 v[138:141], v152
	ds_read_b128 v[144:147], v152 offset:1024
	ds_read_b128 v[148:151], v152 offset:2048
	ds_read_b128 v[152:155], v152 offset:3072
	ds_read_b128 v[156:159], v168
	ds_read_b128 v[160:163], v168 offset:1024
	ds_read_b128 v[164:167], v168 offset:2048
	ds_read_b128 v[168:171], v168 offset:3072
	s_add_u32 s22, s22, 0x20000
	s_addc_u32 s23, s23, 0
	s_mov_b32 m0, s49
	v_lshl_add_u64 v[214:215], s[22:23], 0, v[132:133]
	ds_read_b128 v[172:175], v143 offset:32768
	ds_read_b128 v[176:179], v143 offset:33792
	ds_read_b128 v[180:183], v143 offset:34816
	ds_read_b128 v[184:187], v143 offset:35840
	ds_read_b128 v[188:191], v143 offset:36864
	ds_read_b128 v[192:195], v143 offset:37888
	ds_read_b128 v[196:199], v143 offset:38912
	ds_read_b128 v[200:203], v143 offset:39936
	global_load_lds_dwordx4 v[214:215], off
	v_lshl_add_u64 v[214:215], s[22:23], 0, v[130:131]
	s_mov_b32 m0, s52
	s_nop 0
	global_load_lds_dwordx4 v[214:215], off
	s_waitcnt vmcnt(8)
	s_waitcnt lgkmcnt(0)
	s_barrier
	s_setprio 1
	s_waitcnt lgkmcnt(0)
	v_mfma_f32_16x16x32_bf16 v[124:127], v[138:141], v[172:175], v[124:127]
	v_mfma_f32_16x16x32_bf16 v[124:127], v[144:147], v[176:179], v[124:127]
	v_mfma_f32_16x16x32_bf16 v[116:119], v[138:141], v[180:183], v[116:119]
	v_mfma_f32_16x16x32_bf16 v[116:119], v[144:147], v[184:187], v[116:119]
	v_mfma_f32_16x16x32_bf16 v[100:103], v[138:141], v[188:191], v[100:103]
	v_mfma_f32_16x16x32_bf16 v[100:103], v[144:147], v[192:195], v[100:103]
	v_mfma_f32_16x16x32_bf16 v[84:87], v[138:141], v[196:199], v[84:87]
	v_mfma_f32_16x16x32_bf16 v[84:87], v[144:147], v[200:203], v[84:87]
	v_mfma_f32_16x16x32_bf16 v[120:123], v[148:151], v[172:175], v[120:123]
	v_mfma_f32_16x16x32_bf16 v[120:123], v[152:155], v[176:179], v[120:123]
	v_mfma_f32_16x16x32_bf16 v[108:111], v[148:151], v[180:183], v[108:111]
	v_mfma_f32_16x16x32_bf16 v[108:111], v[152:155], v[184:187], v[108:111]
	v_mfma_f32_16x16x32_bf16 v[92:95], v[148:151], v[188:191], v[92:95]
	v_mfma_f32_16x16x32_bf16 v[92:95], v[152:155], v[192:195], v[92:95]
	v_mfma_f32_16x16x32_bf16 v[76:79], v[148:151], v[196:199], v[76:79]
	v_mfma_f32_16x16x32_bf16 v[76:79], v[152:155], v[200:203], v[76:79]
	v_mfma_f32_16x16x32_bf16 v[112:115], v[156:159], v[172:175], v[112:115]
	v_mfma_f32_16x16x32_bf16 v[112:115], v[160:163], v[176:179], v[112:115]
	v_mfma_f32_16x16x32_bf16 v[96:99], v[156:159], v[180:183], v[96:99]
	v_mfma_f32_16x16x32_bf16 v[96:99], v[160:163], v[184:187], v[96:99]
	v_mfma_f32_16x16x32_bf16 v[80:83], v[156:159], v[188:191], v[80:83]
	v_mfma_f32_16x16x32_bf16 v[80:83], v[160:163], v[192:195], v[80:83]
	v_mfma_f32_16x16x32_bf16 v[68:71], v[156:159], v[196:199], v[68:71]
	v_mfma_f32_16x16x32_bf16 v[68:71], v[160:163], v[200:203], v[68:71]
	v_mfma_f32_16x16x32_bf16 v[104:107], v[164:167], v[172:175], v[104:107]
	v_mfma_f32_16x16x32_bf16 v[104:107], v[168:171], v[176:179], v[104:107]
	v_mfma_f32_16x16x32_bf16 v[88:91], v[164:167], v[180:183], v[88:91]
	v_mfma_f32_16x16x32_bf16 v[88:91], v[168:171], v[184:187], v[88:91]
	v_mfma_f32_16x16x32_bf16 v[72:75], v[164:167], v[188:191], v[72:75]
	v_mfma_f32_16x16x32_bf16 v[72:75], v[168:171], v[192:195], v[72:75]
	v_mfma_f32_16x16x32_bf16 v[64:67], v[164:167], v[196:199], v[64:67]
	v_mfma_f32_16x16x32_bf16 v[64:67], v[168:171], v[200:203], v[64:67]
	s_setprio 0
	s_barrier
	s_nop 1
	s_add_i32 s22, s63, s33
	v_lshl_add_u64 v[204:205], v[204:205], 0, s[72:73]
	s_mov_b32 m0, s22
	ds_read_b128 v[172:175], v143 offset:49152
	ds_read_b128 v[176:179], v143 offset:50176
	ds_read_b128 v[180:183], v143 offset:51200
	ds_read_b128 v[184:187], v143 offset:52224
	ds_read_b128 v[188:191], v143 offset:53248
	ds_read_b128 v[192:195], v143 offset:54272
	ds_read_b128 v[196:199], v143 offset:55296
	ds_read_b128 v[200:203], v143 offset:56320
	global_load_lds_dwordx4 v[204:205], off
	s_add_i32 m0, s22, 0x2000
	s_add_u32 s20, s20, 0x20080
	v_lshl_add_u64 v[204:205], v[206:207], 0, s[72:73]
	s_addc_u32 s21, s21, 0
	s_add_i32 s22, s64, s33
	global_load_lds_dwordx4 v[204:205], off
	v_lshl_add_u64 v[204:205], s[20:21], 0, v[212:213]
	s_mov_b32 m0, s22
	s_nop 0
	global_load_lds_dwordx4 v[204:205], off
	v_lshl_add_u64 v[204:205], s[20:21], 0, v[128:129]
	s_add_i32 m0, s22, 0x2000
	s_nop 0
	global_load_lds_dwordx4 v[204:205], off
	v_lshl_add_u64 v[204:205], v[208:209], 0, s[72:73]
	s_mov_b32 m0, s55
	s_nop 0
	global_load_lds_dwordx4 v[204:205], off
	v_lshl_add_u64 v[204:205], v[210:211], 0, s[72:73]
	s_mov_b32 m0, s56
	s_nop 0
	global_load_lds_dwordx4 v[204:205], off
	s_waitcnt vmcnt(8)
	s_waitcnt lgkmcnt(0)
	s_barrier
	s_setprio 1
	s_waitcnt lgkmcnt(0)
	v_mfma_f32_16x16x32_bf16 v[60:63], v[138:141], v[172:175], v[60:63]
	v_mfma_f32_16x16x32_bf16 v[60:63], v[144:147], v[176:179], v[60:63]
	v_mfma_f32_16x16x32_bf16 v[52:55], v[138:141], v[180:183], v[52:55]
	v_mfma_f32_16x16x32_bf16 v[52:55], v[144:147], v[184:187], v[52:55]
	v_mfma_f32_16x16x32_bf16 v[36:39], v[138:141], v[188:191], v[36:39]
	v_mfma_f32_16x16x32_bf16 v[36:39], v[144:147], v[192:195], v[36:39]
	v_mfma_f32_16x16x32_bf16 v[20:23], v[138:141], v[196:199], v[20:23]
	v_mfma_f32_16x16x32_bf16 v[20:23], v[144:147], v[200:203], v[20:23]
	v_mfma_f32_16x16x32_bf16 v[56:59], v[148:151], v[172:175], v[56:59]
	v_mfma_f32_16x16x32_bf16 v[56:59], v[152:155], v[176:179], v[56:59]
	v_mfma_f32_16x16x32_bf16 v[44:47], v[148:151], v[180:183], v[44:47]
	v_mfma_f32_16x16x32_bf16 v[44:47], v[152:155], v[184:187], v[44:47]
	v_mfma_f32_16x16x32_bf16 v[28:31], v[148:151], v[188:191], v[28:31]
	v_mfma_f32_16x16x32_bf16 v[28:31], v[152:155], v[192:195], v[28:31]
	v_mfma_f32_16x16x32_bf16 v[12:15], v[148:151], v[196:199], v[12:15]
	v_mfma_f32_16x16x32_bf16 v[12:15], v[152:155], v[200:203], v[12:15]
	v_mfma_f32_16x16x32_bf16 v[48:51], v[156:159], v[172:175], v[48:51]
	v_mfma_f32_16x16x32_bf16 v[48:51], v[160:163], v[176:179], v[48:51]
	v_mfma_f32_16x16x32_bf16 v[32:35], v[156:159], v[180:183], v[32:35]
	v_mfma_f32_16x16x32_bf16 v[32:35], v[160:163], v[184:187], v[32:35]
	v_mfma_f32_16x16x32_bf16 v[16:19], v[156:159], v[188:191], v[16:19]
	v_mfma_f32_16x16x32_bf16 v[16:19], v[160:163], v[192:195], v[16:19]
	v_mfma_f32_16x16x32_bf16 v[4:7], v[156:159], v[196:199], v[4:7]
	v_mfma_f32_16x16x32_bf16 v[4:7], v[160:163], v[200:203], v[4:7]
	v_mfma_f32_16x16x32_bf16 v[40:43], v[164:167], v[172:175], v[40:43]
	v_mfma_f32_16x16x32_bf16 v[40:43], v[168:171], v[176:179], v[40:43]
	v_mfma_f32_16x16x32_bf16 v[24:27], v[164:167], v[180:183], v[24:27]
	v_mfma_f32_16x16x32_bf16 v[24:27], v[168:171], v[184:187], v[24:27]
	v_mfma_f32_16x16x32_bf16 v[8:11], v[164:167], v[188:191], v[8:11]
	v_mfma_f32_16x16x32_bf16 v[8:11], v[168:171], v[192:195], v[8:11]
	v_mfma_f32_16x16x32_bf16 v[0:3], v[164:167], v[196:199], v[0:3]
	v_mfma_f32_16x16x32_bf16 v[0:3], v[168:171], v[200:203], v[0:3]
	s_setprio 0
	s_barrier
	s_nop 1
	s_add_i32 s62, s62, 2
	s_add_u32 s18, s18, 0x100
	s_addc_u32 s19, s19, 0
	s_add_u32 s60, s60, 0x100
	s_addc_u32 s61, s61, 0
	s_cmp_gt_u32 s62, 5
	s_cbranch_scc0 .LBB0_997
	s_and_b64 vcc, exec, s[16:17]
	s_cbranch_vccz .LBB0_1000
	s_barrier

.LBB0_1012:
	s_ashr_i32 s15, s14, 31
	s_lshl_b64 s[16:17], s[14:15], 17
	s_add_u32 s16, s31, s16
	s_addc_u32 s17, s33, s17
	s_and_b64 s[18:19], s[36:37], exec
	s_cselect_b32 s29, s17, s23
	s_cselect_b32 s28, s16, s22
	s_ashr_i32 s13, s12, 31
	s_lshl_b64 s[18:19], s[12:13], 17
	s_add_u32 s18, s34, s18
	s_addc_u32 s19, s35, s19
	s_and_b64 s[26:27], s[36:37], exec
	s_cselect_b32 s27, s19, s25
	s_cselect_b32 s26, s18, s24
	s_add_i32 s49, 0, 0x10000
	s_add_i32 s15, 0, 0x14000
	v_add_u32_e32 v210, s49, v136
	v_add_u32_e32 v211, s15, v136
	ds_read_b128 v[0:3], v210
	ds_read_b128 v[4:7], v210 offset:1024
	ds_read_b128 v[8:11], v210 offset:2048
	ds_read_b128 v[12:15], v210 offset:3072
	ds_read_b128 v[16:19], v211
	ds_read_b128 v[20:23], v211 offset:1024
	ds_read_b128 v[24:27], v211 offset:2048
	ds_read_b128 v[28:31], v211 offset:3072
	s_add_u32 s52, s22, 0x10080
	s_addc_u32 s53, s23, 0
	s_add_i32 s51, s21, 0xc000
	v_lshl_add_u64 v[64:65], s[52:53], 0, v[132:133]
	s_mov_b32 m0, s51
	s_add_i32 s3, s21, 0xe000
	ds_read_b128 v[32:35], v137
	ds_read_b128 v[36:39], v137 offset:1024
	ds_read_b128 v[40:43], v137 offset:2048
	ds_read_b128 v[44:47], v137 offset:3072
	ds_read_b128 v[48:51], v137 offset:4096
	ds_read_b128 v[52:55], v137 offset:5120
	ds_read_b128 v[56:59], v137 offset:6144
	ds_read_b128 v[60:63], v137 offset:7168
	global_load_lds_dwordx4 v[64:65], off
	v_lshl_add_u64 v[64:65], s[52:53], 0, v[130:131]
	s_mov_b32 m0, s3
	s_nop 0
	global_load_lds_dwordx4 v[64:65], off
	s_waitcnt vmcnt(8)
	s_waitcnt lgkmcnt(0)
	s_barrier
	s_setprio 1
	s_waitcnt lgkmcnt(0)
	v_mfma_f32_16x16x32_bf16 v[64:67], v[0:3], v[32:35], 0
	v_mfma_f32_16x16x32_bf16 v[68:71], v[8:11], v[32:35], 0
	v_mfma_f32_16x16x32_bf16 v[72:75], v[0:3], v[40:43], 0
	v_mfma_f32_16x16x32_bf16 v[76:79], v[8:11], v[40:43], 0
	v_mfma_f32_16x16x32_bf16 v[80:83], v[0:3], v[48:51], 0
	v_mfma_f32_16x16x32_bf16 v[84:87], v[8:11], v[48:51], 0
	v_mfma_f32_16x16x32_bf16 v[88:91], v[0:3], v[56:59], 0
	v_mfma_f32_16x16x32_bf16 v[92:95], v[8:11], v[56:59], 0
	v_mfma_f32_16x16x32_bf16 v[64:67], v[4:7], v[36:39], v[64:67]
	v_mfma_f32_16x16x32_bf16 v[72:75], v[4:7], v[44:47], v[72:75]
	v_mfma_f32_16x16x32_bf16 v[80:83], v[4:7], v[52:55], v[80:83]
	v_mfma_f32_16x16x32_bf16 v[88:91], v[4:7], v[60:63], v[88:91]
	v_mfma_f32_16x16x32_bf16 v[68:71], v[12:15], v[36:39], v[68:71]
	v_mfma_f32_16x16x32_bf16 v[76:79], v[12:15], v[44:47], v[76:79]
	v_mfma_f32_16x16x32_bf16 v[84:87], v[12:15], v[52:55], v[84:87]
	v_mfma_f32_16x16x32_bf16 v[92:95], v[12:15], v[60:63], v[92:95]
	v_mfma_f32_16x16x32_bf16 v[96:99], v[16:19], v[32:35], 0
	v_mfma_f32_16x16x32_bf16 v[32:35], v[24:27], v[32:35], 0
	v_mfma_f32_16x16x32_bf16 v[96:99], v[20:23], v[36:39], v[96:99]
	v_mfma_f32_16x16x32_bf16 v[32:35], v[28:31], v[36:39], v[32:35]
	v_mfma_f32_16x16x32_bf16 v[36:39], v[16:19], v[40:43], 0
	v_mfma_f32_16x16x32_bf16 v[40:43], v[24:27], v[40:43], 0
	v_mfma_f32_16x16x32_bf16 v[36:39], v[20:23], v[44:47], v[36:39]
	v_mfma_f32_16x16x32_bf16 v[40:43], v[28:31], v[44:47], v[40:43]
	v_mfma_f32_16x16x32_bf16 v[44:47], v[16:19], v[48:51], 0
	v_mfma_f32_16x16x32_bf16 v[48:51], v[24:27], v[48:51], 0
	v_mfma_f32_16x16x32_bf16 v[44:47], v[20:23], v[52:55], v[44:47]
	v_mfma_f32_16x16x32_bf16 v[48:51], v[28:31], v[52:55], v[48:51]
	v_mfma_f32_16x16x32_bf16 v[52:55], v[16:19], v[56:59], 0
	v_mfma_f32_16x16x32_bf16 v[56:59], v[24:27], v[56:59], 0
	v_mfma_f32_16x16x32_bf16 v[52:55], v[20:23], v[60:63], v[52:55]
	v_mfma_f32_16x16x32_bf16 v[56:59], v[28:31], v[60:63], v[56:59]
	s_setprio 0
	s_barrier
	s_nop 1
	s_add_i32 s49, s49, s38
	v_lshl_add_u64 v[134:135], s[24:25], 0, v[212:213]
	s_mov_b64 s[54:55], 0x100
	s_add_i32 s13, s49, 0x2000
	v_lshl_add_u64 v[138:139], v[134:135], 0, s[54:55]
	s_mov_b32 m0, s49
	v_lshl_add_u64 v[202:203], s[24:25], 0, v[128:129]
	s_add_u32 s52, s24, 0x10100
	ds_read_b128 v[60:63], v137 offset:16384
	ds_read_b128 v[100:103], v137 offset:17408
	ds_read_b128 v[104:107], v137 offset:18432
	ds_read_b128 v[108:111], v137 offset:19456
	ds_read_b128 v[112:115], v137 offset:20480
	ds_read_b128 v[116:119], v137 offset:21504
	ds_read_b128 v[120:123], v137 offset:22528
	ds_read_b128 v[124:127], v137 offset:23552
	global_load_lds_dwordx4 v[138:139], off
	v_lshl_add_u64 v[138:139], v[202:203], 0, s[54:55]
	s_mov_b32 m0, s13
	s_addc_u32 s53, s25, 0
	s_add_i32 s15, s15, s38
	global_load_lds_dwordx4 v[138:139], off
	v_lshl_add_u64 v[138:139], s[52:53], 0, v[212:213]
	s_mov_b32 m0, s15
	s_add_i32 s47, s15, 0x2000
	global_load_lds_dwordx4 v[138:139], off
	v_lshl_add_u64 v[138:139], s[52:53], 0, v[128:129]
	s_mov_b32 m0, s47
	v_lshl_add_u64 v[204:205], s[22:23], 0, v[132:133]
	global_load_lds_dwordx4 v[138:139], off
	v_lshl_add_u64 v[138:139], v[204:205], 0, s[54:55]
	s_mov_b32 m0, s21
	v_lshl_add_u64 v[206:207], s[22:23], 0, v[130:131]
	global_load_lds_dwordx4 v[138:139], off
	v_lshl_add_u64 v[138:139], v[206:207], 0, s[54:55]
	s_mov_b32 m0, s39
	s_nop 0
	global_load_lds_dwordx4 v[138:139], off
	s_waitcnt vmcnt(8)
	s_waitcnt lgkmcnt(0)
	s_barrier
	s_setprio 1
	s_waitcnt lgkmcnt(0)
	v_mfma_f32_16x16x32_bf16 v[138:141], v[0:3], v[60:63], 0
	v_mfma_f32_16x16x32_bf16 v[146:149], v[0:3], v[104:107], 0
	v_mfma_f32_16x16x32_bf16 v[154:157], v[0:3], v[112:115], 0
	v_mfma_f32_16x16x32_bf16 v[0:3], v[0:3], v[120:123], 0
	v_mfma_f32_16x16x32_bf16 v[138:141], v[4:7], v[100:103], v[138:141]
	v_mfma_f32_16x16x32_bf16 v[146:149], v[4:7], v[108:111], v[146:149]
	v_mfma_f32_16x16x32_bf16 v[154:157], v[4:7], v[116:119], v[154:157]
	v_mfma_f32_16x16x32_bf16 v[0:3], v[4:7], v[124:127], v[0:3]
	v_mfma_f32_16x16x32_bf16 v[4:7], v[8:11], v[120:123], 0
	v_mfma_f32_16x16x32_bf16 v[142:145], v[8:11], v[60:63], 0
	v_mfma_f32_16x16x32_bf16 v[150:153], v[8:11], v[104:107], 0
	v_mfma_f32_16x16x32_bf16 v[158:161], v[8:11], v[112:115], 0
	v_mfma_f32_16x16x32_bf16 v[4:7], v[12:15], v[124:127], v[4:7]
	v_mfma_f32_16x16x32_bf16 v[142:145], v[12:15], v[100:103], v[142:145]
	v_mfma_f32_16x16x32_bf16 v[150:153], v[12:15], v[108:111], v[150:153]
	v_mfma_f32_16x16x32_bf16 v[158:161], v[12:15], v[116:119], v[158:161]
	v_mfma_f32_16x16x32_bf16 v[8:11], v[16:19], v[60:63], 0
	v_mfma_f32_16x16x32_bf16 v[12:15], v[24:27], v[60:63], 0
	v_mfma_f32_16x16x32_bf16 v[8:11], v[20:23], v[100:103], v[8:11]
	v_mfma_f32_16x16x32_bf16 v[12:15], v[28:31], v[100:103], v[12:15]
	v_mfma_f32_16x16x32_bf16 v[60:63], v[16:19], v[104:107], 0
	v_mfma_f32_16x16x32_bf16 v[100:103], v[24:27], v[104:107], 0
	v_mfma_f32_16x16x32_bf16 v[104:107], v[16:19], v[112:115], 0
	v_mfma_f32_16x16x32_bf16 v[16:19], v[16:19], v[120:123], 0
	v_mfma_f32_16x16x32_bf16 v[60:63], v[20:23], v[108:111], v[60:63]
	v_mfma_f32_16x16x32_bf16 v[100:103], v[28:31], v[108:111], v[100:103]
	v_mfma_f32_16x16x32_bf16 v[104:107], v[20:23], v[116:119], v[104:107]
	v_mfma_f32_16x16x32_bf16 v[108:111], v[24:27], v[112:115], 0
	v_mfma_f32_16x16x32_bf16 v[16:19], v[20:23], v[124:127], v[16:19]
	v_mfma_f32_16x16x32_bf16 v[20:23], v[24:27], v[120:123], 0
	v_mfma_f32_16x16x32_bf16 v[108:111], v[28:31], v[116:119], v[108:111]
	v_mfma_f32_16x16x32_bf16 v[20:23], v[28:31], v[124:127], v[20:23]
	s_setprio 0
	s_barrier
	s_nop 1
	s_add_i32 s50, 0, 0x18000
	s_add_i32 s56, 0, 0x1c000
	v_add_u32_e32 v214, s50, v136
	v_add_u32_e32 v215, s56, v136
	ds_read_b128 v[24:27], v214
	ds_read_b128 v[28:31], v214 offset:1024
	ds_read_b128 v[112:115], v214 offset:2048
	ds_read_b128 v[116:119], v214 offset:3072
	ds_read_b128 v[120:123], v215
	ds_read_b128 v[124:127], v215 offset:1024
	ds_read_b128 v[162:165], v215 offset:2048
	ds_read_b128 v[166:169], v215 offset:3072
	s_add_u32 s52, s22, 0x10100
	s_addc_u32 s53, s23, 0
	s_mov_b32 m0, s40
	v_lshl_add_u64 v[208:209], s[52:53], 0, v[132:133]
	ds_read_b128 v[170:173], v137 offset:32768
	ds_read_b128 v[174:177], v137 offset:33792
	ds_read_b128 v[178:181], v137 offset:34816
	ds_read_b128 v[182:185], v137 offset:35840
	ds_read_b128 v[186:189], v137 offset:36864
	ds_read_b128 v[190:193], v137 offset:37888
	ds_read_b128 v[194:197], v137 offset:38912
	ds_read_b128 v[198:201], v137 offset:39936
	global_load_lds_dwordx4 v[208:209], off
	v_lshl_add_u64 v[208:209], s[52:53], 0, v[130:131]
	s_mov_b32 m0, s41
	s_nop 0
	global_load_lds_dwordx4 v[208:209], off
	s_waitcnt vmcnt(8)
	s_waitcnt lgkmcnt(0)
	s_barrier
	s_setprio 1
	s_waitcnt lgkmcnt(0)
	v_mfma_f32_16x16x32_bf16 v[64:67], v[24:27], v[170:173], v[64:67]
	v_mfma_f32_16x16x32_bf16 v[64:67], v[28:31], v[174:177], v[64:67]
	v_mfma_f32_16x16x32_bf16 v[72:75], v[24:27], v[178:181], v[72:75]
	v_mfma_f32_16x16x32_bf16 v[72:75], v[28:31], v[182:185], v[72:75]
	v_mfma_f32_16x16x32_bf16 v[80:83], v[24:27], v[186:189], v[80:83]
	v_mfma_f32_16x16x32_bf16 v[80:83], v[28:31], v[190:193], v[80:83]
	v_mfma_f32_16x16x32_bf16 v[88:91], v[24:27], v[194:197], v[88:91]
	v_mfma_f32_16x16x32_bf16 v[88:91], v[28:31], v[198:201], v[88:91]
	v_mfma_f32_16x16x32_bf16 v[68:71], v[112:115], v[170:173], v[68:71]
	v_mfma_f32_16x16x32_bf16 v[68:71], v[116:119], v[174:177], v[68:71]
	v_mfma_f32_16x16x32_bf16 v[76:79], v[112:115], v[178:181], v[76:79]
	v_mfma_f32_16x16x32_bf16 v[76:79], v[116:119], v[182:185], v[76:79]
	v_mfma_f32_16x16x32_bf16 v[84:87], v[112:115], v[186:189], v[84:87]
	v_mfma_f32_16x16x32_bf16 v[84:87], v[116:119], v[190:193], v[84:87]
	v_mfma_f32_16x16x32_bf16 v[92:95], v[112:115], v[194:197], v[92:95]
	v_mfma_f32_16x16x32_bf16 v[92:95], v[116:119], v[198:201], v[92:95]
	v_mfma_f32_16x16x32_bf16 v[96:99], v[120:123], v[170:173], v[96:99]
	v_mfma_f32_16x16x32_bf16 v[96:99], v[124:127], v[174:177], v[96:99]
	v_mfma_f32_16x16x32_bf16 v[36:39], v[120:123], v[178:181], v[36:39]
	v_mfma_f32_16x16x32_bf16 v[36:39], v[124:127], v[182:185], v[36:39]
	v_mfma_f32_16x16x32_bf16 v[44:47], v[120:123], v[186:189], v[44:47]
	v_mfma_f32_16x16x32_bf16 v[44:47], v[124:127], v[190:193], v[44:47]
	v_mfma_f32_16x16x32_bf16 v[52:55], v[120:123], v[194:197], v[52:55]
	v_mfma_f32_16x16x32_bf16 v[52:55], v[124:127], v[198:201], v[52:55]
	v_mfma_f32_16x16x32_bf16 v[32:35], v[162:165], v[170:173], v[32:35]
	v_mfma_f32_16x16x32_bf16 v[32:35], v[166:169], v[174:177], v[32:35]
	v_mfma_f32_16x16x32_bf16 v[40:43], v[162:165], v[178:181], v[40:43]
	v_mfma_f32_16x16x32_bf16 v[40:43], v[166:169], v[182:185], v[40:43]
	v_mfma_f32_16x16x32_bf16 v[48:51], v[162:165], v[186:189], v[48:51]
	v_mfma_f32_16x16x32_bf16 v[48:51], v[166:169], v[190:193], v[48:51]
	v_mfma_f32_16x16x32_bf16 v[56:59], v[162:165], v[194:197], v[56:59]
	v_mfma_f32_16x16x32_bf16 v[56:59], v[166:169], v[198:201], v[56:59]
	s_setprio 0
	s_barrier
	s_nop 1
	s_add_i32 s52, s50, s38
	s_mov_b64 s[60:61], 0x180
	s_add_i32 s50, s52, 0x2000
	v_lshl_add_u64 v[134:135], v[134:135], 0, s[60:61]
	s_mov_b32 m0, s52
	s_add_u32 s54, s24, 0x10180
	ds_read_b128 v[170:173], v137 offset:49152
	ds_read_b128 v[174:177], v137 offset:50176
	ds_read_b128 v[178:181], v137 offset:51200
	ds_read_b128 v[182:185], v137 offset:52224
	ds_read_b128 v[186:189], v137 offset:53248
	ds_read_b128 v[190:193], v137 offset:54272
	ds_read_b128 v[194:197], v137 offset:55296
	ds_read_b128 v[198:201], v137 offset:56320
	global_load_lds_dwordx4 v[134:135], off
	v_lshl_add_u64 v[134:135], v[202:203], 0, s[60:61]
	s_mov_b32 m0, s50
	s_addc_u32 s55, s25, 0
	s_add_i32 s24, s56, s38
	global_load_lds_dwordx4 v[134:135], off
	v_lshl_add_u64 v[134:135], s[54:55], 0, v[212:213]
	s_mov_b32 m0, s24
	s_add_i32 s25, s24, 0x2000
	global_load_lds_dwordx4 v[134:135], off
	v_lshl_add_u64 v[134:135], s[54:55], 0, v[128:129]
	s_mov_b32 m0, s25
	s_nop 0
	global_load_lds_dwordx4 v[134:135], off
	v_lshl_add_u64 v[134:135], v[204:205], 0, s[60:61]
	s_mov_b32 m0, s44
	s_nop 0
	global_load_lds_dwordx4 v[134:135], off
	v_lshl_add_u64 v[134:135], v[206:207], 0, s[60:61]
	s_mov_b32 m0, s45
	s_nop 0
	global_load_lds_dwordx4 v[134:135], off
	s_waitcnt vmcnt(8)
	s_waitcnt lgkmcnt(0)
	s_barrier
	s_setprio 1
	s_waitcnt lgkmcnt(0)
	v_mfma_f32_16x16x32_bf16 v[0:3], v[24:27], v[194:197], v[0:3]
	v_mfma_f32_16x16x32_bf16 v[0:3], v[28:31], v[198:201], v[0:3]
	v_mfma_f32_16x16x32_bf16 v[138:141], v[24:27], v[170:173], v[138:141]
	v_mfma_f32_16x16x32_bf16 v[138:141], v[28:31], v[174:177], v[138:141]
	v_mfma_f32_16x16x32_bf16 v[146:149], v[24:27], v[178:181], v[146:149]
	v_mfma_f32_16x16x32_bf16 v[146:149], v[28:31], v[182:185], v[146:149]
	v_mfma_f32_16x16x32_bf16 v[154:157], v[24:27], v[186:189], v[154:157]
	v_mfma_f32_16x16x32_bf16 v[154:157], v[28:31], v[190:193], v[154:157]
	v_mfma_f32_16x16x32_bf16 v[4:7], v[112:115], v[194:197], v[4:7]
	v_mfma_f32_16x16x32_bf16 v[4:7], v[116:119], v[198:201], v[4:7]
	v_mfma_f32_16x16x32_bf16 v[142:145], v[112:115], v[170:173], v[142:145]
	v_mfma_f32_16x16x32_bf16 v[142:145], v[116:119], v[174:177], v[142:145]
	v_mfma_f32_16x16x32_bf16 v[150:153], v[112:115], v[178:181], v[150:153]
	v_mfma_f32_16x16x32_bf16 v[150:153], v[116:119], v[182:185], v[150:153]
	v_mfma_f32_16x16x32_bf16 v[158:161], v[112:115], v[186:189], v[158:161]
	v_mfma_f32_16x16x32_bf16 v[158:161], v[116:119], v[190:193], v[158:161]
	v_mfma_f32_16x16x32_bf16 v[8:11], v[120:123], v[170:173], v[8:11]
	v_mfma_f32_16x16x32_bf16 v[8:11], v[124:127], v[174:177], v[8:11]
	v_mfma_f32_16x16x32_bf16 v[24:27], v[120:123], v[178:181], v[60:63]
	v_mfma_f32_16x16x32_bf16 v[24:27], v[124:127], v[182:185], v[24:27]
	v_mfma_f32_16x16x32_bf16 v[16:19], v[120:123], v[194:197], v[16:19]
	v_mfma_f32_16x16x32_bf16 v[16:19], v[124:127], v[198:201], v[16:19]
	v_mfma_f32_16x16x32_bf16 v[12:15], v[162:165], v[170:173], v[12:15]
	v_mfma_f32_16x16x32_bf16 v[12:15], v[166:169], v[174:177], v[12:15]
	v_mfma_f32_16x16x32_bf16 v[28:31], v[162:165], v[178:181], v[100:103]
	v_mfma_f32_16x16x32_bf16 v[28:31], v[166:169], v[182:185], v[28:31]
	v_mfma_f32_16x16x32_bf16 v[60:63], v[120:123], v[186:189], v[104:107]
	v_mfma_f32_16x16x32_bf16 v[60:63], v[124:127], v[190:193], v[60:63]
	v_mfma_f32_16x16x32_bf16 v[100:103], v[162:165], v[186:189], v[108:111]
	v_mfma_f32_16x16x32_bf16 v[100:103], v[166:169], v[190:193], v[100:103]
	v_mfma_f32_16x16x32_bf16 v[20:23], v[162:165], v[194:197], v[20:23]
	v_mfma_f32_16x16x32_bf16 v[20:23], v[166:169], v[198:201], v[20:23]
	s_setprio 0
	s_barrier
	s_nop 1
	ds_read_b128 v[104:107], v210
	ds_read_b128 v[108:111], v210 offset:1024
	ds_read_b128 v[112:115], v210 offset:2048
	ds_read_b128 v[116:119], v210 offset:3072
	ds_read_b128 v[120:123], v211
	ds_read_b128 v[124:127], v211 offset:1024
	ds_read_b128 v[162:165], v211 offset:2048
	ds_read_b128 v[166:169], v211 offset:3072
	s_add_u32 s22, s22, 0x10180
	s_addc_u32 s23, s23, 0
	s_mov_b32 m0, s51
	v_lshl_add_u64 v[134:135], s[22:23], 0, v[132:133]
	ds_read_b128 v[170:173], v137
	ds_read_b128 v[174:177], v137 offset:1024
	ds_read_b128 v[178:181], v137 offset:2048
	ds_read_b128 v[182:185], v137 offset:3072
	ds_read_b128 v[186:189], v137 offset:4096
	ds_read_b128 v[190:193], v137 offset:5120
	ds_read_b128 v[194:197], v137 offset:6144
	ds_read_b128 v[198:201], v137 offset:7168
	global_load_lds_dwordx4 v[134:135], off
	v_lshl_add_u64 v[134:135], s[22:23], 0, v[130:131]
	s_mov_b32 m0, s3
	s_nop 0
	global_load_lds_dwordx4 v[134:135], off
	s_waitcnt vmcnt(8)
	s_waitcnt lgkmcnt(0)
	s_barrier
	s_setprio 1
	s_waitcnt lgkmcnt(0)
	v_mfma_f32_16x16x32_bf16 v[64:67], v[104:107], v[170:173], v[64:67]
	v_mfma_f32_16x16x32_bf16 v[64:67], v[108:111], v[174:177], v[64:67]
	v_mfma_f32_16x16x32_bf16 v[72:75], v[104:107], v[178:181], v[72:75]
	v_mfma_f32_16x16x32_bf16 v[72:75], v[108:111], v[182:185], v[72:75]
	v_mfma_f32_16x16x32_bf16 v[80:83], v[104:107], v[186:189], v[80:83]
	v_mfma_f32_16x16x32_bf16 v[80:83], v[108:111], v[190:193], v[80:83]
	v_mfma_f32_16x16x32_bf16 v[88:91], v[104:107], v[194:197], v[88:91]
	v_mfma_f32_16x16x32_bf16 v[202:205], v[108:111], v[198:201], v[88:91]
	v_mfma_f32_16x16x32_bf16 v[68:71], v[112:115], v[170:173], v[68:71]
	v_mfma_f32_16x16x32_bf16 v[68:71], v[116:119], v[174:177], v[68:71]
	v_mfma_f32_16x16x32_bf16 v[76:79], v[112:115], v[178:181], v[76:79]
	v_mfma_f32_16x16x32_bf16 v[76:79], v[116:119], v[182:185], v[76:79]
	v_mfma_f32_16x16x32_bf16 v[84:87], v[112:115], v[186:189], v[84:87]
	v_mfma_f32_16x16x32_bf16 v[84:87], v[116:119], v[190:193], v[84:87]
	v_mfma_f32_16x16x32_bf16 v[88:91], v[112:115], v[194:197], v[92:95]
	v_mfma_f32_16x16x32_bf16 v[92:95], v[116:119], v[198:201], v[88:91]
	v_mfma_f32_16x16x32_bf16 v[48:51], v[162:165], v[186:189], v[48:51]
	v_mfma_f32_16x16x32_bf16 v[88:91], v[120:123], v[170:173], v[96:99]
	v_mfma_f32_16x16x32_bf16 v[206:209], v[124:127], v[174:177], v[88:91]
	v_mfma_f32_16x16x32_bf16 v[36:39], v[120:123], v[178:181], v[36:39]
	v_mfma_f32_16x16x32_bf16 v[36:39], v[124:127], v[182:185], v[36:39]
	v_mfma_f32_16x16x32_bf16 v[32:35], v[162:165], v[170:173], v[32:35]
	v_mfma_f32_16x16x32_bf16 v[32:35], v[166:169], v[174:177], v[32:35]
	v_mfma_f32_16x16x32_bf16 v[40:43], v[162:165], v[178:181], v[40:43]
	v_mfma_f32_16x16x32_bf16 v[40:43], v[166:169], v[182:185], v[40:43]
	v_mfma_f32_16x16x32_bf16 v[44:47], v[120:123], v[186:189], v[44:47]
	v_mfma_f32_16x16x32_bf16 v[44:47], v[124:127], v[190:193], v[44:47]
	v_mfma_f32_16x16x32_bf16 v[170:173], v[166:169], v[190:193], v[48:51]
	v_mfma_f32_16x16x32_bf16 v[48:51], v[120:123], v[194:197], v[52:55]
	v_mfma_f32_16x16x32_bf16 v[52:55], v[124:127], v[198:201], v[48:51]
	v_mfma_f32_16x16x32_bf16 v[48:51], v[162:165], v[194:197], v[56:59]
	v_mfma_f32_16x16x32_bf16 v[174:177], v[166:169], v[198:201], v[48:51]
	s_setprio 0
	s_barrier
	s_nop 1
	s_mov_b32 m0, s49
	v_lshl_add_u64 v[134:135], s[26:27], 0, v[212:213]
	s_add_u32 s22, s26, 0x10000
	s_nop 0
	ds_read_b128 v[48:51], v137 offset:16384
	ds_read_b128 v[56:59], v137 offset:17408
	ds_read_b128 v[88:91], v137 offset:18432
	ds_read_b128 v[96:99], v137 offset:19456
	ds_read_b128 v[178:181], v137 offset:20480
	ds_read_b128 v[182:185], v137 offset:21504
	ds_read_b128 v[186:189], v137 offset:22528
	ds_read_b128 v[190:193], v137 offset:23552
	global_load_lds_dwordx4 v[134:135], off
	v_lshl_add_u64 v[210:211], s[26:27], 0, v[128:129]
	s_mov_b32 m0, s13
	s_addc_u32 s23, s27, 0
	global_load_lds_dwordx4 v[210:211], off
	v_lshl_add_u64 v[194:195], s[22:23], 0, v[212:213]
	s_mov_b32 m0, s15
	v_lshl_add_u64 v[226:227], s[28:29], 0, v[132:133]
	global_load_lds_dwordx4 v[194:195], off
	v_lshl_add_u64 v[194:195], s[22:23], 0, v[128:129]
	s_mov_b32 m0, s47
	v_lshl_add_u64 v[234:235], s[28:29], 0, v[130:131]
	global_load_lds_dwordx4 v[194:195], off
	s_mov_b32 m0, s21
	s_nop 0
	global_load_lds_dwordx4 v[226:227], off
	s_mov_b32 m0, s39
	s_nop 0
	global_load_lds_dwordx4 v[234:235], off
	s_waitcnt vmcnt(8)
	s_waitcnt lgkmcnt(0)
	s_barrier
	s_setprio 1
	s_waitcnt lgkmcnt(0)
	v_mfma_f32_16x16x32_bf16 v[0:3], v[104:107], v[186:189], v[0:3]
	v_mfma_f32_16x16x32_bf16 v[0:3], v[108:111], v[190:193], v[0:3]
	v_mfma_f32_16x16x32_bf16 v[138:141], v[104:107], v[48:51], v[138:141]
	v_mfma_f32_16x16x32_bf16 v[138:141], v[108:111], v[56:59], v[138:141]
	v_mfma_f32_16x16x32_bf16 v[146:149], v[104:107], v[88:91], v[146:149]
	v_mfma_f32_16x16x32_bf16 v[146:149], v[108:111], v[96:99], v[146:149]
	v_mfma_f32_16x16x32_bf16 v[154:157], v[104:107], v[178:181], v[154:157]
	v_mfma_f32_16x16x32_bf16 v[154:157], v[108:111], v[182:185], v[154:157]
	v_mfma_f32_16x16x32_bf16 v[4:7], v[112:115], v[186:189], v[4:7]
	v_mfma_f32_16x16x32_bf16 v[4:7], v[116:119], v[190:193], v[4:7]
	v_mfma_f32_16x16x32_bf16 v[142:145], v[112:115], v[48:51], v[142:145]
	v_mfma_f32_16x16x32_bf16 v[142:145], v[116:119], v[56:59], v[142:145]
	v_mfma_f32_16x16x32_bf16 v[150:153], v[112:115], v[88:91], v[150:153]
	v_mfma_f32_16x16x32_bf16 v[150:153], v[116:119], v[96:99], v[150:153]
	v_mfma_f32_16x16x32_bf16 v[158:161], v[112:115], v[178:181], v[158:161]
	v_mfma_f32_16x16x32_bf16 v[158:161], v[116:119], v[182:185], v[158:161]
	v_mfma_f32_16x16x32_bf16 v[12:15], v[162:165], v[48:51], v[12:15]
	v_mfma_f32_16x16x32_bf16 v[194:197], v[166:169], v[56:59], v[12:15]
	v_mfma_f32_16x16x32_bf16 v[12:15], v[120:123], v[88:91], v[24:27]
	v_mfma_f32_16x16x32_bf16 v[24:27], v[124:127], v[96:99], v[12:15]
	v_mfma_f32_16x16x32_bf16 v[12:15], v[162:165], v[88:91], v[28:31]
	v_mfma_f32_16x16x32_bf16 v[198:201], v[166:169], v[96:99], v[12:15]
	v_mfma_f32_16x16x32_bf16 v[12:15], v[120:123], v[178:181], v[60:63]
	v_mfma_f32_16x16x32_bf16 v[218:221], v[124:127], v[182:185], v[12:15]
	v_mfma_f32_16x16x32_bf16 v[12:15], v[162:165], v[178:181], v[100:103]
	v_mfma_f32_16x16x32_bf16 v[178:181], v[166:169], v[182:185], v[12:15]
	v_mfma_f32_16x16x32_bf16 v[8:11], v[120:123], v[48:51], v[8:11]
	v_mfma_f32_16x16x32_bf16 v[8:11], v[124:127], v[56:59], v[8:11]
	v_mfma_f32_16x16x32_bf16 v[12:15], v[120:123], v[186:189], v[16:19]
	v_mfma_f32_16x16x32_bf16 v[182:185], v[124:127], v[190:193], v[12:15]
	v_mfma_f32_16x16x32_bf16 v[12:15], v[162:165], v[186:189], v[20:23]
	v_mfma_f32_16x16x32_bf16 v[162:165], v[166:169], v[190:193], v[12:15]
	s_setprio 0
	s_barrier
	s_nop 1
	s_nop 4
	ds_read_b128 v[12:15], v214
	ds_read_b128 v[16:19], v214 offset:1024
	ds_read_b128 v[166:169], v214 offset:2048
	ds_read_b128 v[186:189], v214 offset:3072
	ds_read_b128 v[190:193], v215
	ds_read_b128 v[222:225], v215 offset:1024
	ds_read_b128 v[238:241], v215 offset:2048
	ds_read_b128 v[242:245], v215 offset:3072
	s_add_u32 s22, s28, 0x10000
	s_addc_u32 s23, s29, 0
	s_mov_b32 m0, s40
	v_lshl_add_u64 v[48:49], s[22:23], 0, v[132:133]
	ds_read_b128 v[20:23], v137 offset:32768
	ds_read_b128 v[28:31], v137 offset:33792
	ds_read_b128 v[60:63], v137 offset:34816
	ds_read_b128 v[100:103], v137 offset:35840
	ds_read_b128 v[246:249], v137 offset:36864
	ds_read_b128 v[250:253], v137 offset:37888
	ds_read_b128 v[230:233], v137 offset:38912
	ds_read_b128 v[214:217], v137 offset:39936
	global_load_lds_dwordx4 v[48:49], off
	v_lshl_add_u64 v[48:49], s[22:23], 0, v[130:131]
	s_mov_b32 m0, s41
	s_nop 0
	global_load_lds_dwordx4 v[48:49], off
	s_waitcnt vmcnt(8)
	s_waitcnt lgkmcnt(0)
	s_barrier
	s_setprio 1
	s_waitcnt lgkmcnt(0)
	v_mfma_f32_16x16x32_bf16 v[48:51], v[12:15], v[20:23], v[64:67]
	v_mfma_f32_16x16x32_bf16 v[120:123], v[16:19], v[28:31], v[48:51]
	v_mfma_f32_16x16x32_bf16 v[48:51], v[166:169], v[20:23], v[68:71]
	v_mfma_f32_16x16x32_bf16 v[112:115], v[186:189], v[28:31], v[48:51]
	v_mfma_f32_16x16x32_bf16 v[48:51], v[12:15], v[60:63], v[72:75]
	v_mfma_f32_16x16x32_bf16 v[104:107], v[16:19], v[100:103], v[48:51]
	v_mfma_f32_16x16x32_bf16 v[48:51], v[166:169], v[60:63], v[76:79]
	v_mfma_f32_16x16x32_bf16 v[96:99], v[186:189], v[100:103], v[48:51]
	v_mfma_f32_16x16x32_bf16 v[48:51], v[12:15], v[246:249], v[80:83]
	v_mfma_f32_16x16x32_bf16 v[88:91], v[16:19], v[250:253], v[48:51]
	v_mfma_f32_16x16x32_bf16 v[48:51], v[166:169], v[246:249], v[84:87]
	v_mfma_f32_16x16x32_bf16 v[80:83], v[186:189], v[250:253], v[48:51]
	v_mfma_f32_16x16x32_bf16 v[48:51], v[12:15], v[230:233], v[202:205]
	v_mfma_f32_16x16x32_bf16 v[56:59], v[16:19], v[214:217], v[48:51]
	v_mfma_f32_16x16x32_bf16 v[48:51], v[166:169], v[230:233], v[92:95]
	v_mfma_f32_16x16x32_bf16 v[48:51], v[186:189], v[214:217], v[48:51]
	v_mfma_f32_16x16x32_bf16 v[64:67], v[190:193], v[20:23], v[206:209]
	v_mfma_f32_16x16x32_bf16 v[124:127], v[222:225], v[28:31], v[64:67]
	v_mfma_f32_16x16x32_bf16 v[20:23], v[238:241], v[20:23], v[32:35]
	v_mfma_f32_16x16x32_bf16 v[116:119], v[242:245], v[28:31], v[20:23]
	v_mfma_f32_16x16x32_bf16 v[20:23], v[190:193], v[60:63], v[36:39]
	v_mfma_f32_16x16x32_bf16 v[108:111], v[222:225], v[100:103], v[20:23]
	v_mfma_f32_16x16x32_bf16 v[20:23], v[238:241], v[60:63], v[40:43]
	v_mfma_f32_16x16x32_bf16 v[100:103], v[242:245], v[100:103], v[20:23]
	v_mfma_f32_16x16x32_bf16 v[20:23], v[190:193], v[246:249], v[44:47]
	v_mfma_f32_16x16x32_bf16 v[92:95], v[222:225], v[250:253], v[20:23]
	v_mfma_f32_16x16x32_bf16 v[20:23], v[238:241], v[246:249], v[170:173]
	v_mfma_f32_16x16x32_bf16 v[84:87], v[242:245], v[250:253], v[20:23]
	v_mfma_f32_16x16x32_bf16 v[20:23], v[190:193], v[230:233], v[52:55]
	v_mfma_f32_16x16x32_bf16 v[60:63], v[222:225], v[214:217], v[20:23]
	v_mfma_f32_16x16x32_bf16 v[20:23], v[238:241], v[230:233], v[174:177]
	v_mfma_f32_16x16x32_bf16 v[52:55], v[242:245], v[214:217], v[20:23]
	s_setprio 0
	s_barrier
	s_nop 1
	s_mov_b32 m0, s52
	s_nop 2
	v_lshl_add_u64 v[20:21], v[134:135], 0, s[72:73]
	s_add_u32 s22, s26, 0x10080
	ds_read_b128 v[32:35], v137 offset:49152
	ds_read_b128 v[40:43], v137 offset:50176
	ds_read_b128 v[170:173], v137 offset:51200
	ds_read_b128 v[174:177], v137 offset:52224
	ds_read_b128 v[202:205], v137 offset:53248
	ds_read_b128 v[206:209], v137 offset:54272
	ds_read_b128 v[214:217], v137 offset:55296
	ds_read_b128 v[230:233], v137 offset:56320
	global_load_lds_dwordx4 v[20:21], off
	v_lshl_add_u64 v[20:21], v[210:211], 0, s[72:73]
	s_mov_b32 m0, s50
	s_addc_u32 s23, s27, 0
	global_load_lds_dwordx4 v[20:21], off
	v_lshl_add_u64 v[20:21], s[22:23], 0, v[212:213]
	s_mov_b32 m0, s24
	s_nop 0
	global_load_lds_dwordx4 v[20:21], off
	v_lshl_add_u64 v[20:21], s[22:23], 0, v[128:129]
	s_mov_b32 m0, s25
	s_nop 0
	global_load_lds_dwordx4 v[20:21], off
	v_lshl_add_u64 v[20:21], v[226:227], 0, s[72:73]
	s_mov_b32 m0, s44
	s_nop 0
	global_load_lds_dwordx4 v[20:21], off
	v_lshl_add_u64 v[20:21], v[234:235], 0, s[72:73]
	s_mov_b32 m0, s45
	s_nop 0
	global_load_lds_dwordx4 v[20:21], off
	s_waitcnt vmcnt(8)
	s_waitcnt lgkmcnt(0)
	s_barrier
	s_setprio 1
	s_waitcnt lgkmcnt(0)
	v_mfma_f32_16x16x32_bf16 v[20:23], v[12:15], v[32:35], v[138:141]
	v_mfma_f32_16x16x32_bf16 v[76:79], v[16:19], v[40:43], v[20:23]
	v_mfma_f32_16x16x32_bf16 v[20:23], v[166:169], v[32:35], v[142:145]
	v_mfma_f32_16x16x32_bf16 v[68:71], v[186:189], v[40:43], v[20:23]
	v_mfma_f32_16x16x32_bf16 v[20:23], v[12:15], v[170:173], v[146:149]
	v_mfma_f32_16x16x32_bf16 v[44:47], v[16:19], v[174:177], v[20:23]
	v_mfma_f32_16x16x32_bf16 v[20:23], v[166:169], v[170:173], v[150:153]
	v_mfma_f32_16x16x32_bf16 v[36:39], v[186:189], v[174:177], v[20:23]
	v_mfma_f32_16x16x32_bf16 v[20:23], v[12:15], v[202:205], v[154:157]
	v_mfma_f32_16x16x32_bf16 v[28:31], v[16:19], v[206:209], v[20:23]
	v_mfma_f32_16x16x32_bf16 v[0:3], v[12:15], v[214:217], v[0:3]
	v_mfma_f32_16x16x32_bf16 v[12:15], v[16:19], v[230:233], v[0:3]
	v_mfma_f32_16x16x32_bf16 v[20:23], v[166:169], v[202:205], v[158:161]
	v_mfma_f32_16x16x32_bf16 v[20:23], v[186:189], v[206:209], v[20:23]
	v_mfma_f32_16x16x32_bf16 v[0:3], v[166:169], v[214:217], v[4:7]
	v_mfma_f32_16x16x32_bf16 v[4:7], v[186:189], v[230:233], v[0:3]
	v_mfma_f32_16x16x32_bf16 v[0:3], v[190:193], v[32:35], v[8:11]
	v_mfma_f32_16x16x32_bf16 v[72:75], v[222:225], v[40:43], v[0:3]
	v_mfma_f32_16x16x32_bf16 v[0:3], v[238:241], v[32:35], v[194:197]
	v_mfma_f32_16x16x32_bf16 v[64:67], v[242:245], v[40:43], v[0:3]
	v_mfma_f32_16x16x32_bf16 v[0:3], v[190:193], v[170:173], v[24:27]
	v_mfma_f32_16x16x32_bf16 v[40:43], v[222:225], v[174:177], v[0:3]
	v_mfma_f32_16x16x32_bf16 v[0:3], v[238:241], v[170:173], v[198:201]
	v_mfma_f32_16x16x32_bf16 v[32:35], v[242:245], v[174:177], v[0:3]
	v_mfma_f32_16x16x32_bf16 v[0:3], v[190:193], v[202:205], v[218:221]
	v_mfma_f32_16x16x32_bf16 v[24:27], v[222:225], v[206:209], v[0:3]
	v_mfma_f32_16x16x32_bf16 v[0:3], v[238:241], v[202:205], v[178:181]
	v_mfma_f32_16x16x32_bf16 v[16:19], v[242:245], v[206:209], v[0:3]
	v_mfma_f32_16x16x32_bf16 v[0:3], v[190:193], v[214:217], v[182:185]
	v_mfma_f32_16x16x32_bf16 v[8:11], v[222:225], v[230:233], v[0:3]
	v_mfma_f32_16x16x32_bf16 v[0:3], v[238:241], v[214:217], v[162:165]
	v_mfma_f32_16x16x32_bf16 v[0:3], v[242:245], v[230:233], v[0:3]
	s_setprio 0
	s_barrier
	s_nop 1
	s_andn2_b64 vcc, exec, s[8:9]
	s_cbranch_vccnz .LBB0_1014
	s_barrier

.LBB0_1239:
	s_add_i32 s2, s34, 2
	s_add_u32 s3, s74, s30
	s_addc_u32 s35, s75, s31
	s_add_u32 s3, s3, 0x100
	s_addc_u32 s35, s35, 0
	s_add_u32 s39, s9, s30
	s_addc_u32 s63, s17, s31
	s_cmp_eq_u32 s45, s34
	s_cselect_b32 s89, s11, s35
	s_cselect_b32 s88, s10, s3
	s_cselect_b32 s35, s13, s63
	s_cselect_b32 s34, s12, s39
	s_add_i32 s3, 0, 0x10000
	s_add_i32 s39, 0, 0x14000
	v_add_u32_e32 v136, s3, v220
	v_add_u32_e32 v160, s39, v220
	ds_read_b128 v[108:111], v136
	ds_read_b128 v[120:123], v136 offset:1024
	ds_read_b128 v[132:135], v136 offset:2048
	ds_read_b128 v[136:139], v136 offset:3072
	ds_read_b128 v[140:143], v160
	ds_read_b128 v[144:147], v160 offset:1024
	ds_read_b128 v[148:151], v160 offset:2048
	ds_read_b128 v[160:163], v160 offset:3072
	v_lshl_add_u64 v[196:197], v[96:97], 0, s[30:31]
	s_add_i32 m0, s15, 0xc000
	ds_read_b128 v[164:167], v223
	ds_read_b128 v[168:171], v223 offset:1024
	ds_read_b128 v[172:175], v223 offset:2048
	ds_read_b128 v[176:179], v223 offset:3072
	ds_read_b128 v[180:183], v223 offset:4096
	ds_read_b128 v[184:187], v223 offset:5120
	ds_read_b128 v[188:191], v223 offset:6144
	ds_read_b128 v[192:195], v223 offset:7168
	global_load_lds_dwordx4 v[196:197], off
	v_lshl_add_u64 v[196:197], v[98:99], 0, s[30:31]
	s_add_i32 m0, s15, 0xe000
	s_nop 0
	global_load_lds_dwordx4 v[196:197], off
	s_waitcnt vmcnt(8)
	s_waitcnt lgkmcnt(0)
	s_barrier
	s_setprio 1
	s_waitcnt lgkmcnt(0)
	v_mfma_f32_16x16x32_bf16 v[156:159], v[108:111], v[164:167], v[156:159]
	v_mfma_f32_16x16x32_bf16 v[156:159], v[120:123], v[168:171], v[156:159]
	v_mfma_f32_16x16x32_bf16 v[128:131], v[108:111], v[172:175], v[128:131]
	v_mfma_f32_16x16x32_bf16 v[128:131], v[120:123], v[176:179], v[128:131]
	v_mfma_f32_16x16x32_bf16 v[116:119], v[108:111], v[180:183], v[116:119]
	v_mfma_f32_16x16x32_bf16 v[116:119], v[120:123], v[184:187], v[116:119]
	v_mfma_f32_16x16x32_bf16 v[104:107], v[108:111], v[188:191], v[104:107]
	v_mfma_f32_16x16x32_bf16 v[104:107], v[120:123], v[192:195], v[104:107]
	v_mfma_f32_16x16x32_bf16 v[152:155], v[132:135], v[164:167], v[152:155]
	v_mfma_f32_16x16x32_bf16 v[152:155], v[136:139], v[168:171], v[152:155]
	v_mfma_f32_16x16x32_bf16 v[124:127], v[132:135], v[172:175], v[124:127]
	v_mfma_f32_16x16x32_bf16 v[124:127], v[136:139], v[176:179], v[124:127]
	v_mfma_f32_16x16x32_bf16 v[112:115], v[132:135], v[180:183], v[112:115]
	v_mfma_f32_16x16x32_bf16 v[112:115], v[136:139], v[184:187], v[112:115]
	v_mfma_f32_16x16x32_bf16 v[100:103], v[132:135], v[188:191], v[100:103]
	v_mfma_f32_16x16x32_bf16 v[100:103], v[136:139], v[192:195], v[100:103]
	v_mfma_f32_16x16x32_bf16 v[92:95], v[140:143], v[164:167], v[92:95]
	v_mfma_f32_16x16x32_bf16 v[92:95], v[144:147], v[168:171], v[92:95]
	v_mfma_f32_16x16x32_bf16 v[84:87], v[140:143], v[172:175], v[84:87]
	v_mfma_f32_16x16x32_bf16 v[84:87], v[144:147], v[176:179], v[84:87]
	v_mfma_f32_16x16x32_bf16 v[76:79], v[140:143], v[180:183], v[76:79]
	v_mfma_f32_16x16x32_bf16 v[76:79], v[144:147], v[184:187], v[76:79]
	v_mfma_f32_16x16x32_bf16 v[68:71], v[140:143], v[188:191], v[68:71]
	v_mfma_f32_16x16x32_bf16 v[68:71], v[144:147], v[192:195], v[68:71]
	v_mfma_f32_16x16x32_bf16 v[88:91], v[148:151], v[164:167], v[88:91]
	v_mfma_f32_16x16x32_bf16 v[88:91], v[160:163], v[168:171], v[88:91]
	v_mfma_f32_16x16x32_bf16 v[80:83], v[148:151], v[172:175], v[80:83]
	v_mfma_f32_16x16x32_bf16 v[80:83], v[160:163], v[176:179], v[80:83]
	v_mfma_f32_16x16x32_bf16 v[72:75], v[148:151], v[180:183], v[72:75]
	v_mfma_f32_16x16x32_bf16 v[72:75], v[160:163], v[184:187], v[72:75]
	v_mfma_f32_16x16x32_bf16 v[64:67], v[148:151], v[188:191], v[64:67]
	v_mfma_f32_16x16x32_bf16 v[64:67], v[160:163], v[192:195], v[64:67]
	s_setprio 0
	s_barrier
	s_nop 1
	s_add_i32 s3, s3, s64
	v_lshl_add_u64 v[196:197], s[34:35], 0, v[212:213]
	s_mov_b32 m0, s3
	ds_read_b128 v[164:167], v223 offset:16384
	ds_read_b128 v[168:171], v223 offset:17408
	ds_read_b128 v[172:175], v223 offset:18432
	ds_read_b128 v[176:179], v223 offset:19456
	ds_read_b128 v[180:183], v223 offset:20480
	ds_read_b128 v[184:187], v223 offset:21504
	ds_read_b128 v[188:191], v223 offset:22528
	ds_read_b128 v[192:195], v223 offset:23552
	global_load_lds_dwordx4 v[196:197], off
	s_add_i32 m0, s3, 0x2000
	s_add_u32 vcc_lo, s34, 0x80000
	v_lshl_add_u64 v[198:199], s[34:35], 0, v[208:209]
	s_addc_u32 vcc_hi, s35, 0
	s_add_i32 s3, s39, s64
	global_load_lds_dwordx4 v[198:199], off
	v_lshl_add_u64 v[200:201], vcc, 0, v[212:213]
	s_mov_b32 m0, s3
	v_lshl_add_u64 v[202:203], s[88:89], 0, v[206:207]
	global_load_lds_dwordx4 v[200:201], off
	v_lshl_add_u64 v[200:201], vcc, 0, v[208:209]
	s_add_i32 m0, s3, 0x2000
	s_nop 0
	global_load_lds_dwordx4 v[200:201], off
	v_lshl_add_u64 v[200:201], s[88:89], 0, v[204:205]
	s_mov_b32 m0, s15
	s_nop 0
	global_load_lds_dwordx4 v[200:201], off
	s_mov_b32 m0, s43
	s_nop 0
	global_load_lds_dwordx4 v[202:203], off
	s_waitcnt vmcnt(8)
	s_waitcnt lgkmcnt(0)
	s_barrier
	s_setprio 1
	s_waitcnt lgkmcnt(0)
	v_mfma_f32_16x16x32_bf16 v[60:63], v[108:111], v[164:167], v[60:63]
	v_mfma_f32_16x16x32_bf16 v[60:63], v[120:123], v[168:171], v[60:63]
	v_mfma_f32_16x16x32_bf16 v[52:55], v[108:111], v[172:175], v[52:55]
	v_mfma_f32_16x16x32_bf16 v[52:55], v[120:123], v[176:179], v[52:55]
	v_mfma_f32_16x16x32_bf16 v[44:47], v[108:111], v[180:183], v[44:47]
	v_mfma_f32_16x16x32_bf16 v[44:47], v[120:123], v[184:187], v[44:47]
	v_mfma_f32_16x16x32_bf16 v[36:39], v[108:111], v[188:191], v[36:39]
	v_mfma_f32_16x16x32_bf16 v[36:39], v[120:123], v[192:195], v[36:39]
	v_mfma_f32_16x16x32_bf16 v[56:59], v[132:135], v[164:167], v[56:59]
	v_mfma_f32_16x16x32_bf16 v[56:59], v[136:139], v[168:171], v[56:59]
	v_mfma_f32_16x16x32_bf16 v[48:51], v[132:135], v[172:175], v[48:51]
	v_mfma_f32_16x16x32_bf16 v[48:51], v[136:139], v[176:179], v[48:51]
	v_mfma_f32_16x16x32_bf16 v[40:43], v[132:135], v[180:183], v[40:43]
	v_mfma_f32_16x16x32_bf16 v[40:43], v[136:139], v[184:187], v[40:43]
	v_mfma_f32_16x16x32_bf16 v[32:35], v[132:135], v[188:191], v[32:35]
	v_mfma_f32_16x16x32_bf16 v[32:35], v[136:139], v[192:195], v[32:35]
	v_mfma_f32_16x16x32_bf16 v[28:31], v[140:143], v[164:167], v[28:31]
	v_mfma_f32_16x16x32_bf16 v[28:31], v[144:147], v[168:171], v[28:31]
	v_mfma_f32_16x16x32_bf16 v[20:23], v[140:143], v[172:175], v[20:23]
	v_mfma_f32_16x16x32_bf16 v[20:23], v[144:147], v[176:179], v[20:23]
	v_mfma_f32_16x16x32_bf16 v[12:15], v[140:143], v[180:183], v[12:15]
	v_mfma_f32_16x16x32_bf16 v[12:15], v[144:147], v[184:187], v[12:15]
	v_mfma_f32_16x16x32_bf16 v[4:7], v[140:143], v[188:191], v[4:7]
	v_mfma_f32_16x16x32_bf16 v[4:7], v[144:147], v[192:195], v[4:7]
	v_mfma_f32_16x16x32_bf16 v[24:27], v[148:151], v[164:167], v[24:27]
	v_mfma_f32_16x16x32_bf16 v[24:27], v[160:163], v[168:171], v[24:27]
	v_mfma_f32_16x16x32_bf16 v[16:19], v[148:151], v[172:175], v[16:19]
	v_mfma_f32_16x16x32_bf16 v[16:19], v[160:163], v[176:179], v[16:19]
	v_mfma_f32_16x16x32_bf16 v[8:11], v[148:151], v[180:183], v[8:11]
	v_mfma_f32_16x16x32_bf16 v[8:11], v[160:163], v[184:187], v[8:11]
	v_mfma_f32_16x16x32_bf16 v[0:3], v[148:151], v[188:191], v[0:3]
	v_mfma_f32_16x16x32_bf16 v[0:3], v[160:163], v[192:195], v[0:3]
	s_setprio 0
	s_barrier
	s_nop 1
	s_add_i32 s3, 0, 0x18000
	s_add_i32 s39, 0, 0x1c000
	v_add_u32_e32 v136, s3, v220
	v_add_u32_e32 v160, s39, v220
	ds_read_b128 v[108:111], v136
	ds_read_b128 v[120:123], v136 offset:1024
	ds_read_b128 v[132:135], v136 offset:2048
	ds_read_b128 v[136:139], v136 offset:3072
	ds_read_b128 v[140:143], v160
	ds_read_b128 v[144:147], v160 offset:1024
	ds_read_b128 v[148:151], v160 offset:2048
	ds_read_b128 v[160:163], v160 offset:3072
	s_add_u32 s88, s88, 0x80000
	s_addc_u32 s89, s89, 0
	s_mov_b32 m0, s69
	v_lshl_add_u64 v[214:215], s[88:89], 0, v[204:205]
	ds_read_b128 v[164:167], v223 offset:32768
	ds_read_b128 v[168:171], v223 offset:33792
	ds_read_b128 v[172:175], v223 offset:34816
	ds_read_b128 v[176:179], v223 offset:35840
	ds_read_b128 v[180:183], v223 offset:36864
	ds_read_b128 v[184:187], v223 offset:37888
	ds_read_b128 v[188:191], v223 offset:38912
	ds_read_b128 v[192:195], v223 offset:39936
	global_load_lds_dwordx4 v[214:215], off
	v_lshl_add_u64 v[214:215], s[88:89], 0, v[206:207]
	s_mov_b32 m0, s70
	s_nop 0
	global_load_lds_dwordx4 v[214:215], off
	s_waitcnt vmcnt(8)
	s_waitcnt lgkmcnt(0)
	s_barrier
	s_setprio 1
	s_waitcnt lgkmcnt(0)
	v_mfma_f32_16x16x32_bf16 v[156:159], v[108:111], v[164:167], v[156:159]
	v_mfma_f32_16x16x32_bf16 v[156:159], v[120:123], v[168:171], v[156:159]
	v_mfma_f32_16x16x32_bf16 v[128:131], v[108:111], v[172:175], v[128:131]
	v_mfma_f32_16x16x32_bf16 v[128:131], v[120:123], v[176:179], v[128:131]
	v_mfma_f32_16x16x32_bf16 v[116:119], v[108:111], v[180:183], v[116:119]
	v_mfma_f32_16x16x32_bf16 v[116:119], v[120:123], v[184:187], v[116:119]
	v_mfma_f32_16x16x32_bf16 v[104:107], v[108:111], v[188:191], v[104:107]
	v_mfma_f32_16x16x32_bf16 v[104:107], v[120:123], v[192:195], v[104:107]
	v_mfma_f32_16x16x32_bf16 v[152:155], v[132:135], v[164:167], v[152:155]
	v_mfma_f32_16x16x32_bf16 v[152:155], v[136:139], v[168:171], v[152:155]
	v_mfma_f32_16x16x32_bf16 v[124:127], v[132:135], v[172:175], v[124:127]
	v_mfma_f32_16x16x32_bf16 v[124:127], v[136:139], v[176:179], v[124:127]
	v_mfma_f32_16x16x32_bf16 v[112:115], v[132:135], v[180:183], v[112:115]
	v_mfma_f32_16x16x32_bf16 v[112:115], v[136:139], v[184:187], v[112:115]
	v_mfma_f32_16x16x32_bf16 v[100:103], v[132:135], v[188:191], v[100:103]
	v_mfma_f32_16x16x32_bf16 v[100:103], v[136:139], v[192:195], v[100:103]
	v_mfma_f32_16x16x32_bf16 v[92:95], v[140:143], v[164:167], v[92:95]
	v_mfma_f32_16x16x32_bf16 v[92:95], v[144:147], v[168:171], v[92:95]
	v_mfma_f32_16x16x32_bf16 v[84:87], v[140:143], v[172:175], v[84:87]
	v_mfma_f32_16x16x32_bf16 v[84:87], v[144:147], v[176:179], v[84:87]
	v_mfma_f32_16x16x32_bf16 v[76:79], v[140:143], v[180:183], v[76:79]
	v_mfma_f32_16x16x32_bf16 v[76:79], v[144:147], v[184:187], v[76:79]
	v_mfma_f32_16x16x32_bf16 v[68:71], v[140:143], v[188:191], v[68:71]
	v_mfma_f32_16x16x32_bf16 v[68:71], v[144:147], v[192:195], v[68:71]
	v_mfma_f32_16x16x32_bf16 v[88:91], v[148:151], v[164:167], v[88:91]
	v_mfma_f32_16x16x32_bf16 v[88:91], v[160:163], v[168:171], v[88:91]
	v_mfma_f32_16x16x32_bf16 v[80:83], v[148:151], v[172:175], v[80:83]
	v_mfma_f32_16x16x32_bf16 v[80:83], v[160:163], v[176:179], v[80:83]
	v_mfma_f32_16x16x32_bf16 v[72:75], v[148:151], v[180:183], v[72:75]
	v_mfma_f32_16x16x32_bf16 v[72:75], v[160:163], v[184:187], v[72:75]
	v_mfma_f32_16x16x32_bf16 v[64:67], v[148:151], v[188:191], v[64:67]
	v_mfma_f32_16x16x32_bf16 v[64:67], v[160:163], v[192:195], v[64:67]
	s_setprio 0
	s_barrier
	s_nop 1
	s_add_i32 s3, s3, s64
	v_lshl_add_u64 v[196:197], v[196:197], 0, s[72:73]
	s_mov_b32 m0, s3
	ds_read_b128 v[164:167], v223 offset:49152
	ds_read_b128 v[168:171], v223 offset:50176
	ds_read_b128 v[172:175], v223 offset:51200
	ds_read_b128 v[176:179], v223 offset:52224
	ds_read_b128 v[180:183], v223 offset:53248
	ds_read_b128 v[184:187], v223 offset:54272
	ds_read_b128 v[188:191], v223 offset:55296
	ds_read_b128 v[192:195], v223 offset:56320
	global_load_lds_dwordx4 v[196:197], off
	s_add_i32 m0, s3, 0x2000
	s_add_u32 s34, s34, 0x80080
	v_lshl_add_u64 v[196:197], v[198:199], 0, s[72:73]
	s_addc_u32 s35, s35, 0
	s_add_i32 s3, s39, s64
	global_load_lds_dwordx4 v[196:197], off
	v_lshl_add_u64 v[196:197], s[34:35], 0, v[212:213]
	s_mov_b32 m0, s3
	s_nop 0
	global_load_lds_dwordx4 v[196:197], off
	v_lshl_add_u64 v[196:197], s[34:35], 0, v[208:209]
	s_add_i32 m0, s3, 0x2000
	s_nop 0
	global_load_lds_dwordx4 v[196:197], off
	v_lshl_add_u64 v[196:197], v[200:201], 0, s[72:73]
	s_mov_b32 m0, s83
	s_nop 0
	global_load_lds_dwordx4 v[196:197], off
	v_lshl_add_u64 v[196:197], v[202:203], 0, s[72:73]
	s_mov_b32 m0, s84
	s_nop 0
	global_load_lds_dwordx4 v[196:197], off
	s_waitcnt vmcnt(8)
	s_waitcnt lgkmcnt(0)
	s_barrier
	s_setprio 1
	s_waitcnt lgkmcnt(0)
	v_mfma_f32_16x16x32_bf16 v[60:63], v[108:111], v[164:167], v[60:63]
	v_mfma_f32_16x16x32_bf16 v[60:63], v[120:123], v[168:171], v[60:63]
	v_mfma_f32_16x16x32_bf16 v[52:55], v[108:111], v[172:175], v[52:55]
	v_mfma_f32_16x16x32_bf16 v[52:55], v[120:123], v[176:179], v[52:55]
	v_mfma_f32_16x16x32_bf16 v[44:47], v[108:111], v[180:183], v[44:47]
	v_mfma_f32_16x16x32_bf16 v[44:47], v[120:123], v[184:187], v[44:47]
	v_mfma_f32_16x16x32_bf16 v[36:39], v[108:111], v[188:191], v[36:39]
	v_mfma_f32_16x16x32_bf16 v[36:39], v[120:123], v[192:195], v[36:39]
	v_mfma_f32_16x16x32_bf16 v[56:59], v[132:135], v[164:167], v[56:59]
	v_mfma_f32_16x16x32_bf16 v[56:59], v[136:139], v[168:171], v[56:59]
	v_mfma_f32_16x16x32_bf16 v[48:51], v[132:135], v[172:175], v[48:51]
	v_mfma_f32_16x16x32_bf16 v[48:51], v[136:139], v[176:179], v[48:51]
	v_mfma_f32_16x16x32_bf16 v[40:43], v[132:135], v[180:183], v[40:43]
	v_mfma_f32_16x16x32_bf16 v[40:43], v[136:139], v[184:187], v[40:43]
	v_mfma_f32_16x16x32_bf16 v[32:35], v[132:135], v[188:191], v[32:35]
	v_mfma_f32_16x16x32_bf16 v[32:35], v[136:139], v[192:195], v[32:35]
	v_mfma_f32_16x16x32_bf16 v[28:31], v[140:143], v[164:167], v[28:31]
	v_mfma_f32_16x16x32_bf16 v[28:31], v[144:147], v[168:171], v[28:31]
	v_mfma_f32_16x16x32_bf16 v[20:23], v[140:143], v[172:175], v[20:23]
	v_mfma_f32_16x16x32_bf16 v[20:23], v[144:147], v[176:179], v[20:23]
	v_mfma_f32_16x16x32_bf16 v[12:15], v[140:143], v[180:183], v[12:15]
	v_mfma_f32_16x16x32_bf16 v[12:15], v[144:147], v[184:187], v[12:15]
	v_mfma_f32_16x16x32_bf16 v[4:7], v[140:143], v[188:191], v[4:7]
	v_mfma_f32_16x16x32_bf16 v[4:7], v[144:147], v[192:195], v[4:7]
	v_mfma_f32_16x16x32_bf16 v[24:27], v[148:151], v[164:167], v[24:27]
	v_mfma_f32_16x16x32_bf16 v[24:27], v[160:163], v[168:171], v[24:27]
	v_mfma_f32_16x16x32_bf16 v[16:19], v[148:151], v[172:175], v[16:19]
	v_mfma_f32_16x16x32_bf16 v[16:19], v[160:163], v[176:179], v[16:19]
	v_mfma_f32_16x16x32_bf16 v[8:11], v[148:151], v[180:183], v[8:11]
	v_mfma_f32_16x16x32_bf16 v[8:11], v[160:163], v[184:187], v[8:11]
	v_mfma_f32_16x16x32_bf16 v[0:3], v[148:151], v[188:191], v[0:3]
	v_mfma_f32_16x16x32_bf16 v[0:3], v[160:163], v[192:195], v[0:3]
	s_setprio 0
	s_barrier
	s_nop 1
	s_add_u32 s30, s30, 0x100
	s_addc_u32 s31, s31, 0
	s_cmp_ge_i32 s2, s19
	s_mov_b32 s34, s2
	s_cbranch_scc1 .LBB0_1246

.LBB0_1413:
	s_lshl_b32 s2, s9, 7
	s_add_u32 s3, s74, s2
	s_addc_u32 s24, s75, 0
	s_add_u32 s20, s3, 0x100
	s_addc_u32 s21, s24, 0
	s_add_u32 s2, s14, s2
	s_addc_u32 s22, s15, 0
	s_add_u32 s2, s2, 0x100
	s_addc_u32 s25, s22, 0
	s_cmp_eq_u32 s9, 30
	s_cselect_b32 s23, s5, s21
	s_cselect_b32 s22, s59, s20
	s_cselect_b32 s21, s57, s25
	s_cselect_b32 s20, s30, s2
	s_add_i32 s25, 0, 0x10000
	s_add_i32 s26, 0, 0x14000
	v_add_u32_e32 v28, s25, v226
	v_add_u32_e32 v44, s26, v226
	ds_read_b128 v[16:19], v28
	ds_read_b128 v[20:23], v28 offset:1024
	ds_read_b128 v[24:27], v28 offset:2048
	ds_read_b128 v[28:31], v28 offset:3072
	ds_read_b128 v[32:35], v44
	ds_read_b128 v[36:39], v44 offset:1024
	ds_read_b128 v[40:43], v44 offset:2048
	ds_read_b128 v[44:47], v44 offset:3072
	s_add_u32 s2, s3, 0x80080
	s_addc_u32 s3, s24, 0
	v_lshl_add_u64 v[152:153], s[2:3], 0, v[218:219]
	s_add_i32 m0, s11, 0xc000
	ds_read_b128 v[48:51], v227
	ds_read_b128 v[52:55], v227 offset:1024
	ds_read_b128 v[56:59], v227 offset:2048
	ds_read_b128 v[60:63], v227 offset:3072
	ds_read_b128 v[136:139], v227 offset:4096
	ds_read_b128 v[140:143], v227 offset:5120
	ds_read_b128 v[144:147], v227 offset:6144
	ds_read_b128 v[148:151], v227 offset:7168
	global_load_lds_dwordx4 v[152:153], off
	v_lshl_add_u64 v[152:153], s[2:3], 0, v[222:223]
	s_add_i32 m0, s11, 0xe000
	s_nop 0
	global_load_lds_dwordx4 v[152:153], off
	s_waitcnt vmcnt(8)
	s_waitcnt lgkmcnt(0)
	s_barrier
	s_setprio 1
	s_waitcnt lgkmcnt(0)
	v_mfma_f32_16x16x32_bf16 v[152:155], v[16:19], v[48:51], v[164:167]
	v_mfma_f32_16x16x32_bf16 v[152:155], v[20:23], v[52:55], v[152:155]
	v_mfma_f32_16x16x32_bf16 v[160:163], v[16:19], v[56:59], v[160:163]
	v_mfma_f32_16x16x32_bf16 v[160:163], v[20:23], v[60:63], v[160:163]
	v_mfma_f32_16x16x32_bf16 v[108:111], v[16:19], v[136:139], v[108:111]
	v_mfma_f32_16x16x32_bf16 v[108:111], v[20:23], v[140:143], v[108:111]
	v_mfma_f32_16x16x32_bf16 v[164:167], v[16:19], v[144:147], v[168:171]
	v_mfma_f32_16x16x32_bf16 v[168:171], v[20:23], v[148:151], v[164:167]
	v_mfma_f32_16x16x32_bf16 v[64:67], v[24:27], v[48:51], v[64:67]
	v_mfma_f32_16x16x32_bf16 v[64:67], v[28:31], v[52:55], v[64:67]
	v_mfma_f32_16x16x32_bf16 v[156:159], v[24:27], v[56:59], v[156:159]
	v_mfma_f32_16x16x32_bf16 v[156:159], v[28:31], v[60:63], v[156:159]
	v_mfma_f32_16x16x32_bf16 v[104:107], v[24:27], v[136:139], v[104:107]
	v_mfma_f32_16x16x32_bf16 v[104:107], v[28:31], v[140:143], v[104:107]
	v_mfma_f32_16x16x32_bf16 v[68:71], v[24:27], v[144:147], v[68:71]
	v_mfma_f32_16x16x32_bf16 v[68:71], v[28:31], v[148:151], v[68:71]
	v_mfma_f32_16x16x32_bf16 v[88:91], v[32:35], v[48:51], v[88:91]
	v_mfma_f32_16x16x32_bf16 v[88:91], v[36:39], v[52:55], v[88:91]
	v_mfma_f32_16x16x32_bf16 v[48:51], v[40:43], v[48:51], v[72:75]
	v_mfma_f32_16x16x32_bf16 v[48:51], v[44:47], v[52:55], v[48:51]
	v_mfma_f32_16x16x32_bf16 v[72:75], v[40:43], v[136:139], v[96:99]
	v_mfma_f32_16x16x32_bf16 v[96:99], v[44:47], v[140:143], v[72:75]
	v_mfma_f32_16x16x32_bf16 v[72:75], v[32:35], v[144:147], v[92:95]
	v_mfma_f32_16x16x32_bf16 v[92:95], v[36:39], v[148:151], v[72:75]
	v_mfma_f32_16x16x32_bf16 v[52:55], v[32:35], v[56:59], v[132:135]
	v_mfma_f32_16x16x32_bf16 v[52:55], v[36:39], v[60:63], v[52:55]
	v_mfma_f32_16x16x32_bf16 v[56:59], v[40:43], v[56:59], v[128:131]
	v_mfma_f32_16x16x32_bf16 v[56:59], v[44:47], v[60:63], v[56:59]
	v_mfma_f32_16x16x32_bf16 v[72:75], v[40:43], v[144:147], v[76:79]
	v_mfma_f32_16x16x32_bf16 v[76:79], v[44:47], v[148:151], v[72:75]
	v_mfma_f32_16x16x32_bf16 v[60:63], v[32:35], v[136:139], v[100:103]
	v_mfma_f32_16x16x32_bf16 v[60:63], v[36:39], v[140:143], v[60:63]
	s_setprio 0
	s_barrier
	s_nop 1
	s_add_i32 s2, s25, s79
	v_lshl_add_u64 v[214:215], s[20:21], 0, v[220:221]
	s_mov_b32 m0, s2
	ds_read_b128 v[72:75], v227 offset:16384
	ds_read_b128 v[100:103], v227 offset:17408
	ds_read_b128 v[128:131], v227 offset:18432
	ds_read_b128 v[132:135], v227 offset:19456
	ds_read_b128 v[136:139], v227 offset:20480
	ds_read_b128 v[140:143], v227 offset:21504
	ds_read_b128 v[144:147], v227 offset:22528
	ds_read_b128 v[148:151], v227 offset:23552
	global_load_lds_dwordx4 v[214:215], off
	s_add_i32 m0, s2, 0x2000
	s_add_u32 s2, s20, 0x80000
	v_lshl_add_u64 v[216:217], s[20:21], 0, v[224:225]
	s_addc_u32 s3, s21, 0
	s_add_i32 s24, s26, s79
	global_load_lds_dwordx4 v[216:217], off
	v_lshl_add_u64 v[164:165], s[2:3], 0, v[220:221]
	s_mov_b32 m0, s24
	v_lshl_add_u64 v[230:231], s[22:23], 0, v[218:219]
	global_load_lds_dwordx4 v[164:165], off
	v_lshl_add_u64 v[164:165], s[2:3], 0, v[224:225]
	s_add_i32 m0, s24, 0x2000
	v_lshl_add_u64 v[232:233], s[22:23], 0, v[222:223]
	global_load_lds_dwordx4 v[164:165], off
	s_mov_b32 m0, s11
	s_nop 0
	global_load_lds_dwordx4 v[230:231], off
	s_mov_b32 m0, s88
	s_nop 0
	global_load_lds_dwordx4 v[232:233], off
	s_waitcnt vmcnt(8)
	s_waitcnt lgkmcnt(0)
	s_barrier
	s_setprio 1
	s_waitcnt lgkmcnt(0)
	v_mfma_f32_16x16x32_bf16 v[80:83], v[16:19], v[72:75], v[80:83]
	v_mfma_f32_16x16x32_bf16 v[80:83], v[20:23], v[100:103], v[80:83]
	v_mfma_f32_16x16x32_bf16 v[12:15], v[16:19], v[128:131], v[12:15]
	v_mfma_f32_16x16x32_bf16 v[12:15], v[20:23], v[132:135], v[12:15]
	v_mfma_f32_16x16x32_bf16 v[124:127], v[16:19], v[136:139], v[124:127]
	v_mfma_f32_16x16x32_bf16 v[124:127], v[20:23], v[140:143], v[124:127]
	v_mfma_f32_16x16x32_bf16 v[8:11], v[24:27], v[128:131], v[8:11]
	v_mfma_f32_16x16x32_bf16 v[8:11], v[28:31], v[132:135], v[8:11]
	v_mfma_f32_16x16x32_bf16 v[120:123], v[24:27], v[136:139], v[120:123]
	v_mfma_f32_16x16x32_bf16 v[120:123], v[28:31], v[140:143], v[120:123]
	v_mfma_f32_16x16x32_bf16 v[16:19], v[16:19], v[144:147], v[84:87]
	v_mfma_f32_16x16x32_bf16 v[16:19], v[20:23], v[148:151], v[16:19]
	v_mfma_f32_16x16x32_bf16 v[164:167], v[24:27], v[72:75], v[196:199]
	v_mfma_f32_16x16x32_bf16 v[176:179], v[28:31], v[100:103], v[164:167]
	v_mfma_f32_16x16x32_bf16 v[20:23], v[24:27], v[144:147], v[200:203]
	v_mfma_f32_16x16x32_bf16 v[20:23], v[28:31], v[148:151], v[20:23]
	v_mfma_f32_16x16x32_bf16 v[24:27], v[32:35], v[72:75], v[172:175]
	v_mfma_f32_16x16x32_bf16 v[24:27], v[36:39], v[100:103], v[24:27]
	v_mfma_f32_16x16x32_bf16 v[4:7], v[32:35], v[128:131], v[4:7]
	v_mfma_f32_16x16x32_bf16 v[4:7], v[36:39], v[132:135], v[4:7]
	v_mfma_f32_16x16x32_bf16 v[28:31], v[40:43], v[72:75], v[188:191]
	v_mfma_f32_16x16x32_bf16 v[28:31], v[44:47], v[100:103], v[28:31]
	v_mfma_f32_16x16x32_bf16 v[72:75], v[32:35], v[136:139], v[116:119]
	v_mfma_f32_16x16x32_bf16 v[116:119], v[36:39], v[140:143], v[72:75]
	v_mfma_f32_16x16x32_bf16 v[0:3], v[40:43], v[128:131], v[0:3]
	v_mfma_f32_16x16x32_bf16 v[0:3], v[44:47], v[132:135], v[0:3]
	v_mfma_f32_16x16x32_bf16 v[72:75], v[40:43], v[136:139], v[112:115]
	v_mfma_f32_16x16x32_bf16 v[112:115], v[44:47], v[140:143], v[72:75]
	v_mfma_f32_16x16x32_bf16 v[32:35], v[32:35], v[144:147], v[180:183]
	v_mfma_f32_16x16x32_bf16 v[32:35], v[36:39], v[148:151], v[32:35]
	v_mfma_f32_16x16x32_bf16 v[36:39], v[40:43], v[144:147], v[192:195]
	v_mfma_f32_16x16x32_bf16 v[36:39], v[44:47], v[148:151], v[36:39]
	s_setprio 0
	s_barrier
	s_nop 1
	s_add_i32 s24, 0, 0x18000
	v_add_u32_e32 v72, s24, v226
	s_add_i32 s25, 0, 0x1c000
	ds_read_b128 v[40:43], v72
	ds_read_b128 v[44:47], v72 offset:1024
	ds_read_b128 v[136:139], v72 offset:2048
	ds_read_b128 v[140:143], v72 offset:3072
	v_add_u32_e32 v72, s25, v226
	ds_read_b128 v[144:147], v72
	ds_read_b128 v[148:151], v72 offset:1024
	ds_read_b128 v[184:187], v72 offset:2048
	ds_read_b128 v[192:195], v72 offset:3072
	s_add_u32 s2, s22, 0x80000
	s_addc_u32 s3, s23, 0
	s_mov_b32 m0, s89
	v_lshl_add_u64 v[132:133], s[2:3], 0, v[218:219]
	ds_read_b128 v[72:75], v227 offset:32768
	ds_read_b128 v[84:87], v227 offset:33792
	ds_read_b128 v[100:103], v227 offset:34816
	ds_read_b128 v[128:131], v227 offset:35840
	ds_read_b128 v[172:175], v227 offset:36864
	ds_read_b128 v[180:183], v227 offset:37888
	ds_read_b128 v[188:191], v227 offset:38912
	ds_read_b128 v[196:199], v227 offset:39936
	global_load_lds_dwordx4 v[132:133], off
	v_lshl_add_u64 v[132:133], s[2:3], 0, v[222:223]
	s_mov_b32 m0, s76
	s_nop 0
	global_load_lds_dwordx4 v[132:133], off
	s_waitcnt vmcnt(8)
	s_waitcnt lgkmcnt(0)
	s_barrier
	s_setprio 1
	s_waitcnt lgkmcnt(0)
	v_mfma_f32_16x16x32_bf16 v[132:135], v[40:43], v[72:75], v[152:155]
	v_mfma_f32_16x16x32_bf16 v[164:167], v[44:47], v[84:87], v[132:135]
	v_mfma_f32_16x16x32_bf16 v[108:111], v[40:43], v[172:175], v[108:111]
	v_mfma_f32_16x16x32_bf16 v[108:111], v[44:47], v[180:183], v[108:111]
	v_mfma_f32_16x16x32_bf16 v[132:135], v[40:43], v[100:103], v[160:163]
	v_mfma_f32_16x16x32_bf16 v[160:163], v[44:47], v[128:131], v[132:135]
	v_mfma_f32_16x16x32_bf16 v[132:135], v[136:139], v[100:103], v[156:159]
	v_mfma_f32_16x16x32_bf16 v[156:159], v[140:143], v[128:131], v[132:135]
	v_mfma_f32_16x16x32_bf16 v[132:135], v[40:43], v[188:191], v[168:171]
	v_mfma_f32_16x16x32_bf16 v[168:171], v[44:47], v[196:199], v[132:135]
	v_mfma_f32_16x16x32_bf16 v[64:67], v[136:139], v[72:75], v[64:67]
	v_mfma_f32_16x16x32_bf16 v[64:67], v[140:143], v[84:87], v[64:67]
	v_mfma_f32_16x16x32_bf16 v[104:107], v[136:139], v[172:175], v[104:107]
	v_mfma_f32_16x16x32_bf16 v[104:107], v[140:143], v[180:183], v[104:107]
	v_mfma_f32_16x16x32_bf16 v[68:71], v[136:139], v[188:191], v[68:71]
	v_mfma_f32_16x16x32_bf16 v[68:71], v[140:143], v[196:199], v[68:71]
	v_mfma_f32_16x16x32_bf16 v[48:51], v[184:187], v[72:75], v[48:51]
	v_mfma_f32_16x16x32_bf16 v[88:91], v[144:147], v[72:75], v[88:91]
	v_mfma_f32_16x16x32_bf16 v[88:91], v[148:151], v[84:87], v[88:91]
	v_mfma_f32_16x16x32_bf16 v[72:75], v[192:195], v[84:87], v[48:51]
	v_mfma_f32_16x16x32_bf16 v[48:51], v[144:147], v[100:103], v[52:55]
	v_mfma_f32_16x16x32_bf16 v[132:135], v[148:151], v[128:131], v[48:51]
	v_mfma_f32_16x16x32_bf16 v[48:51], v[184:187], v[100:103], v[56:59]
	v_mfma_f32_16x16x32_bf16 v[128:131], v[192:195], v[128:131], v[48:51]
	v_mfma_f32_16x16x32_bf16 v[48:51], v[144:147], v[172:175], v[60:63]
	v_mfma_f32_16x16x32_bf16 v[100:103], v[148:151], v[180:183], v[48:51]
	v_mfma_f32_16x16x32_bf16 v[48:51], v[184:187], v[172:175], v[96:99]
	v_mfma_f32_16x16x32_bf16 v[96:99], v[192:195], v[180:183], v[48:51]
	v_mfma_f32_16x16x32_bf16 v[48:51], v[144:147], v[188:191], v[92:95]
	v_mfma_f32_16x16x32_bf16 v[92:95], v[148:151], v[196:199], v[48:51]
	v_mfma_f32_16x16x32_bf16 v[48:51], v[184:187], v[188:191], v[76:79]
	v_mfma_f32_16x16x32_bf16 v[76:79], v[192:195], v[196:199], v[48:51]
	s_setprio 0
	s_barrier
	s_nop 1
	s_add_i32 s2, s24, s79
	v_lshl_add_u64 v[84:85], v[214:215], 0, s[72:73]
	s_mov_b32 m0, s2
	s_nop 0
	ds_read_b128 v[48:51], v227 offset:49152
	ds_read_b128 v[52:55], v227 offset:50176
	ds_read_b128 v[56:59], v227 offset:51200
	ds_read_b128 v[60:63], v227 offset:52224
	ds_read_b128 v[152:155], v227 offset:53248
	ds_read_b128 v[180:183], v227 offset:54272
	ds_read_b128 v[204:207], v227 offset:55296
	ds_read_b128 v[208:211], v227 offset:56320
	global_load_lds_dwordx4 v[84:85], off
	s_add_i32 m0, s2, 0x2000
	s_add_u32 s2, s20, 0x80080
	v_lshl_add_u64 v[84:85], v[216:217], 0, s[72:73]
	s_addc_u32 s3, s21, 0
	s_add_i32 s20, s25, s79
	global_load_lds_dwordx4 v[84:85], off
	v_lshl_add_u64 v[84:85], s[2:3], 0, v[220:221]
	s_mov_b32 m0, s20
	s_nop 0
	global_load_lds_dwordx4 v[84:85], off
	v_lshl_add_u64 v[84:85], s[2:3], 0, v[224:225]
	s_add_i32 m0, s20, 0x2000
	s_nop 0
	global_load_lds_dwordx4 v[84:85], off
	v_lshl_add_u64 v[84:85], v[230:231], 0, s[72:73]
	s_mov_b32 m0, s67
	s_nop 0
	global_load_lds_dwordx4 v[84:85], off
	v_lshl_add_u64 v[84:85], v[232:233], 0, s[72:73]
	s_mov_b32 m0, s84
	s_nop 0
	global_load_lds_dwordx4 v[84:85], off
	s_waitcnt vmcnt(8)
	s_waitcnt lgkmcnt(0)
	s_barrier
	s_setprio 1
	s_waitcnt lgkmcnt(0)
	v_mfma_f32_16x16x32_bf16 v[84:87], v[136:139], v[48:51], v[176:179]
	v_mfma_f32_16x16x32_bf16 v[196:199], v[140:143], v[52:55], v[84:87]
	v_mfma_f32_16x16x32_bf16 v[12:15], v[40:43], v[56:59], v[12:15]
	v_mfma_f32_16x16x32_bf16 v[12:15], v[44:47], v[60:63], v[12:15]
	v_mfma_f32_16x16x32_bf16 v[84:87], v[40:43], v[152:155], v[124:127]
	v_mfma_f32_16x16x32_bf16 v[124:127], v[44:47], v[180:183], v[84:87]
	v_mfma_f32_16x16x32_bf16 v[84:87], v[136:139], v[152:155], v[120:123]
	v_mfma_f32_16x16x32_bf16 v[120:123], v[140:143], v[180:183], v[84:87]
	v_mfma_f32_16x16x32_bf16 v[16:19], v[40:43], v[204:207], v[16:19]
	v_mfma_f32_16x16x32_bf16 v[84:87], v[44:47], v[208:211], v[16:19]
	v_mfma_f32_16x16x32_bf16 v[80:83], v[40:43], v[48:51], v[80:83]
	v_mfma_f32_16x16x32_bf16 v[80:83], v[44:47], v[52:55], v[80:83]
	v_mfma_f32_16x16x32_bf16 v[8:11], v[136:139], v[56:59], v[8:11]
	v_mfma_f32_16x16x32_bf16 v[8:11], v[140:143], v[60:63], v[8:11]
	v_mfma_f32_16x16x32_bf16 v[16:19], v[136:139], v[204:207], v[20:23]
	v_mfma_f32_16x16x32_bf16 v[200:203], v[140:143], v[208:211], v[16:19]
	v_mfma_f32_16x16x32_bf16 v[4:7], v[144:147], v[56:59], v[4:7]
	v_mfma_f32_16x16x32_bf16 v[4:7], v[148:151], v[60:63], v[4:7]
	v_mfma_f32_16x16x32_bf16 v[16:19], v[144:147], v[48:51], v[24:27]
	v_mfma_f32_16x16x32_bf16 v[172:175], v[148:151], v[52:55], v[16:19]
	v_mfma_f32_16x16x32_bf16 v[16:19], v[184:187], v[48:51], v[28:31]
	v_mfma_f32_16x16x32_bf16 v[188:191], v[192:195], v[52:55], v[16:19]
	v_mfma_f32_16x16x32_bf16 v[16:19], v[144:147], v[152:155], v[116:119]
	v_mfma_f32_16x16x32_bf16 v[116:119], v[148:151], v[180:183], v[16:19]
	v_mfma_f32_16x16x32_bf16 v[16:19], v[184:187], v[152:155], v[112:115]
	v_mfma_f32_16x16x32_bf16 v[112:115], v[192:195], v[180:183], v[16:19]
	v_mfma_f32_16x16x32_bf16 v[16:19], v[144:147], v[204:207], v[32:35]
	v_mfma_f32_16x16x32_bf16 v[180:183], v[148:151], v[208:211], v[16:19]
	v_mfma_f32_16x16x32_bf16 v[0:3], v[184:187], v[56:59], v[0:3]
	v_mfma_f32_16x16x32_bf16 v[0:3], v[192:195], v[60:63], v[0:3]
	v_mfma_f32_16x16x32_bf16 v[16:19], v[184:187], v[204:207], v[36:39]
	v_mfma_f32_16x16x32_bf16 v[192:195], v[192:195], v[208:211], v[16:19]
	s_setprio 0
	s_barrier
	s_nop 1
	s_add_i32 s2, s9, 2
	s_cmp_gt_u32 s9, 29
	s_mov_b32 s9, s2
	s_cbranch_scc1 .LBB0_1436

.LBB0_1660:
	s_add_i32 s2, s28, 2
	s_add_u32 s3, s12, s26
	s_addc_u32 s29, s13, s27
	s_add_u32 s3, s3, 0x100
	s_addc_u32 s29, s29, 0
	s_add_u32 s55, s15, s26
	s_addc_u32 s63, s41, s27
	s_cmp_eq_u32 s40, s28
	s_cselect_b32 s31, s75, s29
	s_cselect_b32 s30, s74, s3
	s_cselect_b32 s29, s9, s63
	s_cselect_b32 s28, s8, s55
	s_add_i32 s3, 0, 0x10000
	s_add_i32 s55, 0, 0x14000
	v_add_u32_e32 v112, s3, v238
	v_add_u32_e32 v160, s55, v238
	ds_read_b128 v[76:79], v112
	ds_read_b128 v[88:91], v112 offset:1024
	ds_read_b128 v[100:103], v112 offset:2048
	ds_read_b128 v[112:115], v112 offset:3072
	ds_read_b128 v[124:127], v160
	ds_read_b128 v[136:139], v160 offset:1024
	ds_read_b128 v[148:151], v160 offset:2048
	ds_read_b128 v[160:163], v160 offset:3072
	v_lshl_add_u64 v[196:197], v[68:69], 0, s[26:27]
	s_add_i32 m0, s11, 0xc000
	ds_read_b128 v[164:167], v241
	ds_read_b128 v[168:171], v241 offset:1024
	ds_read_b128 v[172:175], v241 offset:2048
	ds_read_b128 v[176:179], v241 offset:3072
	ds_read_b128 v[180:183], v241 offset:4096
	ds_read_b128 v[184:187], v241 offset:5120
	ds_read_b128 v[188:191], v241 offset:6144
	ds_read_b128 v[192:195], v241 offset:7168
	global_load_lds_dwordx4 v[196:197], off
	v_lshl_add_u64 v[196:197], v[70:71], 0, s[26:27]
	s_add_i32 m0, s11, 0xe000
	s_nop 0
	global_load_lds_dwordx4 v[196:197], off
	s_waitcnt vmcnt(8)
	s_waitcnt lgkmcnt(0)
	s_barrier
	s_setprio 1
	s_waitcnt lgkmcnt(0)
	v_mfma_f32_16x16x32_bf16 v[156:159], v[76:79], v[164:167], v[156:159]
	v_mfma_f32_16x16x32_bf16 v[156:159], v[88:91], v[168:171], v[156:159]
	v_mfma_f32_16x16x32_bf16 v[144:147], v[76:79], v[172:175], v[144:147]
	v_mfma_f32_16x16x32_bf16 v[144:147], v[88:91], v[176:179], v[144:147]
	v_mfma_f32_16x16x32_bf16 v[132:135], v[76:79], v[180:183], v[132:135]
	v_mfma_f32_16x16x32_bf16 v[132:135], v[88:91], v[184:187], v[132:135]
	v_mfma_f32_16x16x32_bf16 v[120:123], v[76:79], v[188:191], v[120:123]
	v_mfma_f32_16x16x32_bf16 v[120:123], v[88:91], v[192:195], v[120:123]
	v_mfma_f32_16x16x32_bf16 v[152:155], v[100:103], v[164:167], v[152:155]
	v_mfma_f32_16x16x32_bf16 v[152:155], v[112:115], v[168:171], v[152:155]
	v_mfma_f32_16x16x32_bf16 v[140:143], v[100:103], v[172:175], v[140:143]
	v_mfma_f32_16x16x32_bf16 v[140:143], v[112:115], v[176:179], v[140:143]
	v_mfma_f32_16x16x32_bf16 v[128:131], v[100:103], v[180:183], v[128:131]
	v_mfma_f32_16x16x32_bf16 v[128:131], v[112:115], v[184:187], v[128:131]
	v_mfma_f32_16x16x32_bf16 v[116:119], v[100:103], v[188:191], v[116:119]
	v_mfma_f32_16x16x32_bf16 v[116:119], v[112:115], v[192:195], v[116:119]
	v_mfma_f32_16x16x32_bf16 v[108:111], v[124:127], v[164:167], v[108:111]
	v_mfma_f32_16x16x32_bf16 v[108:111], v[136:139], v[168:171], v[108:111]
	v_mfma_f32_16x16x32_bf16 v[96:99], v[124:127], v[172:175], v[96:99]
	v_mfma_f32_16x16x32_bf16 v[96:99], v[136:139], v[176:179], v[96:99]
	v_mfma_f32_16x16x32_bf16 v[84:87], v[124:127], v[180:183], v[84:87]
	v_mfma_f32_16x16x32_bf16 v[84:87], v[136:139], v[184:187], v[84:87]
	v_mfma_f32_16x16x32_bf16 v[72:75], v[124:127], v[188:191], v[72:75]
	v_mfma_f32_16x16x32_bf16 v[72:75], v[136:139], v[192:195], v[72:75]
	v_mfma_f32_16x16x32_bf16 v[104:107], v[148:151], v[164:167], v[104:107]
	v_mfma_f32_16x16x32_bf16 v[104:107], v[160:163], v[168:171], v[104:107]
	v_mfma_f32_16x16x32_bf16 v[92:95], v[148:151], v[172:175], v[92:95]
	v_mfma_f32_16x16x32_bf16 v[92:95], v[160:163], v[176:179], v[92:95]
	v_mfma_f32_16x16x32_bf16 v[80:83], v[148:151], v[180:183], v[80:83]
	v_mfma_f32_16x16x32_bf16 v[80:83], v[160:163], v[184:187], v[80:83]
	v_mfma_f32_16x16x32_bf16 v[64:67], v[148:151], v[188:191], v[64:67]
	v_mfma_f32_16x16x32_bf16 v[64:67], v[160:163], v[192:195], v[64:67]
	s_setprio 0
	s_barrier
	s_nop 1
	s_add_i32 s3, s3, s33
	v_lshl_add_u64 v[196:197], s[28:29], 0, v[210:211]
	s_mov_b32 m0, s3
	ds_read_b128 v[164:167], v241 offset:16384
	ds_read_b128 v[168:171], v241 offset:17408
	ds_read_b128 v[172:175], v241 offset:18432
	ds_read_b128 v[176:179], v241 offset:19456
	ds_read_b128 v[180:183], v241 offset:20480
	ds_read_b128 v[184:187], v241 offset:21504
	ds_read_b128 v[188:191], v241 offset:22528
	ds_read_b128 v[192:195], v241 offset:23552
	global_load_lds_dwordx4 v[196:197], off
	s_add_i32 m0, s3, 0x2000
	s_add_u32 vcc_lo, s28, 0x160000
	v_lshl_add_u64 v[198:199], s[28:29], 0, v[220:221]
	s_addc_u32 vcc_hi, s29, 0
	s_add_i32 s3, s55, s33
	global_load_lds_dwordx4 v[198:199], off
	v_lshl_add_u64 v[200:201], vcc, 0, v[210:211]
	s_mov_b32 m0, s3
	v_lshl_add_u64 v[202:203], s[30:31], 0, v[218:219]
	global_load_lds_dwordx4 v[200:201], off
	v_lshl_add_u64 v[200:201], vcc, 0, v[220:221]
	s_add_i32 m0, s3, 0x2000
	s_nop 0
	global_load_lds_dwordx4 v[200:201], off
	v_lshl_add_u64 v[200:201], s[30:31], 0, v[208:209]
	s_mov_b32 m0, s11
	s_nop 0
	global_load_lds_dwordx4 v[200:201], off
	s_mov_b32 m0, s65
	s_nop 0
	global_load_lds_dwordx4 v[202:203], off
	s_waitcnt vmcnt(8)
	s_waitcnt lgkmcnt(0)
	s_barrier
	s_setprio 1
	s_waitcnt lgkmcnt(0)
	v_mfma_f32_16x16x32_bf16 v[60:63], v[76:79], v[164:167], v[60:63]
	v_mfma_f32_16x16x32_bf16 v[60:63], v[88:91], v[168:171], v[60:63]
	v_mfma_f32_16x16x32_bf16 v[52:55], v[76:79], v[172:175], v[52:55]
	v_mfma_f32_16x16x32_bf16 v[52:55], v[88:91], v[176:179], v[52:55]
	v_mfma_f32_16x16x32_bf16 v[44:47], v[76:79], v[180:183], v[44:47]
	v_mfma_f32_16x16x32_bf16 v[44:47], v[88:91], v[184:187], v[44:47]
	v_mfma_f32_16x16x32_bf16 v[36:39], v[76:79], v[188:191], v[36:39]
	v_mfma_f32_16x16x32_bf16 v[36:39], v[88:91], v[192:195], v[36:39]
	v_mfma_f32_16x16x32_bf16 v[56:59], v[100:103], v[164:167], v[56:59]
	v_mfma_f32_16x16x32_bf16 v[56:59], v[112:115], v[168:171], v[56:59]
	v_mfma_f32_16x16x32_bf16 v[48:51], v[100:103], v[172:175], v[48:51]
	v_mfma_f32_16x16x32_bf16 v[48:51], v[112:115], v[176:179], v[48:51]
	v_mfma_f32_16x16x32_bf16 v[40:43], v[100:103], v[180:183], v[40:43]
	v_mfma_f32_16x16x32_bf16 v[40:43], v[112:115], v[184:187], v[40:43]
	v_mfma_f32_16x16x32_bf16 v[32:35], v[100:103], v[188:191], v[32:35]
	v_mfma_f32_16x16x32_bf16 v[32:35], v[112:115], v[192:195], v[32:35]
	v_mfma_f32_16x16x32_bf16 v[28:31], v[124:127], v[164:167], v[28:31]
	v_mfma_f32_16x16x32_bf16 v[28:31], v[136:139], v[168:171], v[28:31]
	v_mfma_f32_16x16x32_bf16 v[20:23], v[124:127], v[172:175], v[20:23]
	v_mfma_f32_16x16x32_bf16 v[20:23], v[136:139], v[176:179], v[20:23]
	v_mfma_f32_16x16x32_bf16 v[12:15], v[124:127], v[180:183], v[12:15]
	v_mfma_f32_16x16x32_bf16 v[12:15], v[136:139], v[184:187], v[12:15]
	v_mfma_f32_16x16x32_bf16 v[4:7], v[124:127], v[188:191], v[4:7]
	v_mfma_f32_16x16x32_bf16 v[4:7], v[136:139], v[192:195], v[4:7]
	v_mfma_f32_16x16x32_bf16 v[24:27], v[148:151], v[164:167], v[24:27]
	v_mfma_f32_16x16x32_bf16 v[24:27], v[160:163], v[168:171], v[24:27]
	v_mfma_f32_16x16x32_bf16 v[16:19], v[148:151], v[172:175], v[16:19]
	v_mfma_f32_16x16x32_bf16 v[16:19], v[160:163], v[176:179], v[16:19]
	v_mfma_f32_16x16x32_bf16 v[8:11], v[148:151], v[180:183], v[8:11]
	v_mfma_f32_16x16x32_bf16 v[8:11], v[160:163], v[184:187], v[8:11]
	v_mfma_f32_16x16x32_bf16 v[0:3], v[148:151], v[188:191], v[0:3]
	v_mfma_f32_16x16x32_bf16 v[0:3], v[160:163], v[192:195], v[0:3]
	s_setprio 0
	s_barrier
	s_nop 1
	s_add_i32 s3, 0, 0x18000
	s_add_i32 s55, 0, 0x1c000
	v_add_u32_e32 v112, s3, v238
	v_add_u32_e32 v160, s55, v238
	ds_read_b128 v[76:79], v112
	ds_read_b128 v[88:91], v112 offset:1024
	ds_read_b128 v[100:103], v112 offset:2048
	ds_read_b128 v[112:115], v112 offset:3072
	ds_read_b128 v[124:127], v160
	ds_read_b128 v[136:139], v160 offset:1024
	ds_read_b128 v[148:151], v160 offset:2048
	ds_read_b128 v[160:163], v160 offset:3072
	s_add_u32 s30, s30, 0x160000
	s_addc_u32 s31, s31, 0
	s_mov_b32 m0, s34
	v_lshl_add_u64 v[204:205], s[30:31], 0, v[208:209]
	ds_read_b128 v[164:167], v241 offset:32768
	ds_read_b128 v[168:171], v241 offset:33792
	ds_read_b128 v[172:175], v241 offset:34816
	ds_read_b128 v[176:179], v241 offset:35840
	ds_read_b128 v[180:183], v241 offset:36864
	ds_read_b128 v[184:187], v241 offset:37888
	ds_read_b128 v[188:191], v241 offset:38912
	ds_read_b128 v[192:195], v241 offset:39936
	global_load_lds_dwordx4 v[204:205], off
	v_lshl_add_u64 v[204:205], s[30:31], 0, v[218:219]
	s_mov_b32 m0, s67
	s_nop 0
	global_load_lds_dwordx4 v[204:205], off
	s_waitcnt vmcnt(8)
	s_waitcnt lgkmcnt(0)
	s_barrier
	s_setprio 1
	s_waitcnt lgkmcnt(0)
	v_mfma_f32_16x16x32_bf16 v[156:159], v[76:79], v[164:167], v[156:159]
	v_mfma_f32_16x16x32_bf16 v[156:159], v[88:91], v[168:171], v[156:159]
	v_mfma_f32_16x16x32_bf16 v[144:147], v[76:79], v[172:175], v[144:147]
	v_mfma_f32_16x16x32_bf16 v[144:147], v[88:91], v[176:179], v[144:147]
	v_mfma_f32_16x16x32_bf16 v[132:135], v[76:79], v[180:183], v[132:135]
	v_mfma_f32_16x16x32_bf16 v[132:135], v[88:91], v[184:187], v[132:135]
	v_mfma_f32_16x16x32_bf16 v[120:123], v[76:79], v[188:191], v[120:123]
	v_mfma_f32_16x16x32_bf16 v[120:123], v[88:91], v[192:195], v[120:123]
	v_mfma_f32_16x16x32_bf16 v[152:155], v[100:103], v[164:167], v[152:155]
	v_mfma_f32_16x16x32_bf16 v[152:155], v[112:115], v[168:171], v[152:155]
	v_mfma_f32_16x16x32_bf16 v[140:143], v[100:103], v[172:175], v[140:143]
	v_mfma_f32_16x16x32_bf16 v[140:143], v[112:115], v[176:179], v[140:143]
	v_mfma_f32_16x16x32_bf16 v[128:131], v[100:103], v[180:183], v[128:131]
	v_mfma_f32_16x16x32_bf16 v[128:131], v[112:115], v[184:187], v[128:131]
	v_mfma_f32_16x16x32_bf16 v[116:119], v[100:103], v[188:191], v[116:119]
	v_mfma_f32_16x16x32_bf16 v[116:119], v[112:115], v[192:195], v[116:119]
	v_mfma_f32_16x16x32_bf16 v[108:111], v[124:127], v[164:167], v[108:111]
	v_mfma_f32_16x16x32_bf16 v[108:111], v[136:139], v[168:171], v[108:111]
	v_mfma_f32_16x16x32_bf16 v[96:99], v[124:127], v[172:175], v[96:99]
	v_mfma_f32_16x16x32_bf16 v[96:99], v[136:139], v[176:179], v[96:99]
	v_mfma_f32_16x16x32_bf16 v[84:87], v[124:127], v[180:183], v[84:87]
	v_mfma_f32_16x16x32_bf16 v[84:87], v[136:139], v[184:187], v[84:87]
	v_mfma_f32_16x16x32_bf16 v[72:75], v[124:127], v[188:191], v[72:75]
	v_mfma_f32_16x16x32_bf16 v[72:75], v[136:139], v[192:195], v[72:75]
	v_mfma_f32_16x16x32_bf16 v[104:107], v[148:151], v[164:167], v[104:107]
	v_mfma_f32_16x16x32_bf16 v[104:107], v[160:163], v[168:171], v[104:107]
	v_mfma_f32_16x16x32_bf16 v[92:95], v[148:151], v[172:175], v[92:95]
	v_mfma_f32_16x16x32_bf16 v[92:95], v[160:163], v[176:179], v[92:95]
	v_mfma_f32_16x16x32_bf16 v[80:83], v[148:151], v[180:183], v[80:83]
	v_mfma_f32_16x16x32_bf16 v[80:83], v[160:163], v[184:187], v[80:83]
	v_mfma_f32_16x16x32_bf16 v[64:67], v[148:151], v[188:191], v[64:67]
	v_mfma_f32_16x16x32_bf16 v[64:67], v[160:163], v[192:195], v[64:67]
	s_setprio 0
	s_barrier
	s_nop 1
	s_add_i32 s3, s3, s33
	v_lshl_add_u64 v[196:197], v[196:197], 0, s[72:73]
	s_mov_b32 m0, s3
	ds_read_b128 v[164:167], v241 offset:49152
	ds_read_b128 v[168:171], v241 offset:50176
	ds_read_b128 v[172:175], v241 offset:51200
	ds_read_b128 v[176:179], v241 offset:52224
	ds_read_b128 v[180:183], v241 offset:53248
	ds_read_b128 v[184:187], v241 offset:54272
	ds_read_b128 v[188:191], v241 offset:55296
	ds_read_b128 v[192:195], v241 offset:56320
	global_load_lds_dwordx4 v[196:197], off
	s_add_i32 m0, s3, 0x2000
	s_add_u32 s28, s28, 0x160080
	v_lshl_add_u64 v[196:197], v[198:199], 0, s[72:73]
	s_addc_u32 s29, s29, 0
	s_add_i32 s3, s55, s33
	global_load_lds_dwordx4 v[196:197], off
	v_lshl_add_u64 v[196:197], s[28:29], 0, v[210:211]
	s_mov_b32 m0, s3
	s_nop 0
	global_load_lds_dwordx4 v[196:197], off
	v_lshl_add_u64 v[196:197], s[28:29], 0, v[220:221]
	s_add_i32 m0, s3, 0x2000
	s_nop 0
	global_load_lds_dwordx4 v[196:197], off
	v_lshl_add_u64 v[196:197], v[200:201], 0, s[72:73]
	s_mov_b32 m0, s81
	s_nop 0
	global_load_lds_dwordx4 v[196:197], off
	v_lshl_add_u64 v[196:197], v[202:203], 0, s[72:73]
	s_mov_b32 m0, s82
	s_nop 0
	global_load_lds_dwordx4 v[196:197], off
	s_waitcnt vmcnt(8)
	s_waitcnt lgkmcnt(0)
	s_barrier
	s_setprio 1
	s_waitcnt lgkmcnt(0)
	v_mfma_f32_16x16x32_bf16 v[60:63], v[76:79], v[164:167], v[60:63]
	v_mfma_f32_16x16x32_bf16 v[60:63], v[88:91], v[168:171], v[60:63]
	v_mfma_f32_16x16x32_bf16 v[52:55], v[76:79], v[172:175], v[52:55]
	v_mfma_f32_16x16x32_bf16 v[52:55], v[88:91], v[176:179], v[52:55]
	v_mfma_f32_16x16x32_bf16 v[44:47], v[76:79], v[180:183], v[44:47]
	v_mfma_f32_16x16x32_bf16 v[44:47], v[88:91], v[184:187], v[44:47]
	v_mfma_f32_16x16x32_bf16 v[36:39], v[76:79], v[188:191], v[36:39]
	v_mfma_f32_16x16x32_bf16 v[36:39], v[88:91], v[192:195], v[36:39]
	v_mfma_f32_16x16x32_bf16 v[56:59], v[100:103], v[164:167], v[56:59]
	v_mfma_f32_16x16x32_bf16 v[56:59], v[112:115], v[168:171], v[56:59]
	v_mfma_f32_16x16x32_bf16 v[48:51], v[100:103], v[172:175], v[48:51]
	v_mfma_f32_16x16x32_bf16 v[48:51], v[112:115], v[176:179], v[48:51]
	v_mfma_f32_16x16x32_bf16 v[40:43], v[100:103], v[180:183], v[40:43]
	v_mfma_f32_16x16x32_bf16 v[40:43], v[112:115], v[184:187], v[40:43]
	v_mfma_f32_16x16x32_bf16 v[32:35], v[100:103], v[188:191], v[32:35]
	v_mfma_f32_16x16x32_bf16 v[32:35], v[112:115], v[192:195], v[32:35]
	v_mfma_f32_16x16x32_bf16 v[28:31], v[124:127], v[164:167], v[28:31]
	v_mfma_f32_16x16x32_bf16 v[28:31], v[136:139], v[168:171], v[28:31]
	v_mfma_f32_16x16x32_bf16 v[20:23], v[124:127], v[172:175], v[20:23]
	v_mfma_f32_16x16x32_bf16 v[20:23], v[136:139], v[176:179], v[20:23]
	v_mfma_f32_16x16x32_bf16 v[12:15], v[124:127], v[180:183], v[12:15]
	v_mfma_f32_16x16x32_bf16 v[12:15], v[136:139], v[184:187], v[12:15]
	v_mfma_f32_16x16x32_bf16 v[4:7], v[124:127], v[188:191], v[4:7]
	v_mfma_f32_16x16x32_bf16 v[4:7], v[136:139], v[192:195], v[4:7]
	v_mfma_f32_16x16x32_bf16 v[24:27], v[148:151], v[164:167], v[24:27]
	v_mfma_f32_16x16x32_bf16 v[24:27], v[160:163], v[168:171], v[24:27]
	v_mfma_f32_16x16x32_bf16 v[16:19], v[148:151], v[172:175], v[16:19]
	v_mfma_f32_16x16x32_bf16 v[16:19], v[160:163], v[176:179], v[16:19]
	v_mfma_f32_16x16x32_bf16 v[8:11], v[148:151], v[180:183], v[8:11]
	v_mfma_f32_16x16x32_bf16 v[8:11], v[160:163], v[184:187], v[8:11]
	v_mfma_f32_16x16x32_bf16 v[0:3], v[148:151], v[188:191], v[0:3]
	v_mfma_f32_16x16x32_bf16 v[0:3], v[160:163], v[192:195], v[0:3]
	s_setprio 0
	s_barrier
	s_nop 1
	s_add_u32 s26, s26, 0x100
	s_addc_u32 s27, s27, 0
	s_cmp_ge_i32 s2, s17
	s_mov_b32 s28, s2
	s_cbranch_scc1 .LBB0_1669
